# v17 + first K-loop iteration of every GEMM unit peeled with SrcC=0 (128-register accumulator zeroing per tile removed)
# speedup vs baseline: 1.0025x; 1.0025x over previous
.LBB0_175:
	s_ashr_i32 s43, s42, 31
	s_lshl_b64 s[10:11], s[42:43], 20
	s_add_u32 s44, s51, s10
	s_addc_u32 s45, s52, s11
	s_and_b64 s[10:11], s[38:39], exec
	s_cselect_b32 s3, s45, s27
	s_cselect_b32 s10, s44, s26
	s_ashr_i32 s29, s28, 31
	s_lshl_b64 s[36:37], s[28:29], 20
	s_add_u32 s46, s7, s36
	s_addc_u32 s47, s53, s37
	s_and_b64 s[36:37], s[38:39], exec
	s_cselect_b32 s11, s47, s35
	s_cselect_b32 s21, s46, s34
	s_add_u32 s26, s26, 0x80080
	s_addc_u32 s27, s27, 0
	s_add_u32 s22, s34, 0x100
	s_addc_u32 s29, s35, 0
	s_mov_b32 s33, -2
	v_lshl_add_u32 v148, s2, 8, v150
	v_ashrrev_i32_e32 v149, 31, v148
	v_lshl_add_u64 v[144:145], v[148:149], 2, s[40:41]
	global_load_dword v244, v[144:145], off
	global_load_dword v245, v[144:145], off offset:64
	global_load_dword v246, v[144:145], off offset:128
	global_load_dword v247, v[144:145], off offset:192
	global_load_dword v248, v[144:145], off offset:512
	global_load_dword v249, v[144:145], off offset:576
	global_load_dword v250, v[144:145], off offset:640
	global_load_dword v251, v[144:145], off offset:704
	s_add_u32 s34, s26, 0xfff80080
	s_addc_u32 s35, s27, -1
	s_add_i32 s43, 0, 0x10000
	s_cmp_eq_u32 s33, 28
	s_cselect_b32 s37, s3, s35
	s_cselect_b32 s36, s10, s34
	s_cselect_b32 s35, s11, s29
	s_cselect_b32 s34, s21, s22
	s_add_i32 s66, 0, 0x14000
	v_add_u32_e32 v158, s43, v151
	v_add_u32_e32 v182, s66, v151
	ds_read_b128 v[142:145], v158
	ds_read_b128 v[146:149], v158 offset:1024
	ds_read_b128 v[154:157], v158 offset:2048
	ds_read_b128 v[158:161], v158 offset:3072
	ds_read_b128 v[162:165], v182
	ds_read_b128 v[166:169], v182 offset:1024
	ds_read_b128 v[178:181], v182 offset:2048
	ds_read_b128 v[182:185], v182 offset:3072
	v_lshl_add_u64 v[228:229], s[26:27], 0, v[138:139]
	s_add_i32 m0, s56, 0xc000
	ds_read_b128 v[186:189], v153
	ds_read_b128 v[190:193], v153 offset:1024
	ds_read_b128 v[194:197], v153 offset:2048
	ds_read_b128 v[208:211], v153 offset:3072
	ds_read_b128 v[212:215], v153 offset:4096
	ds_read_b128 v[216:219], v153 offset:5120
	ds_read_b128 v[220:223], v153 offset:6144
	ds_read_b128 v[224:227], v153 offset:7168
	global_load_lds_dwordx4 v[228:229], off
	v_lshl_add_u64 v[228:229], s[26:27], 0, v[140:141]
	s_add_i32 m0, s56, 0xe000
	s_nop 0
	global_load_lds_dwordx4 v[228:229], off
	s_waitcnt vmcnt(8)
	s_waitcnt lgkmcnt(0)
	s_barrier
	s_setprio 1
	s_waitcnt lgkmcnt(0)
	v_mfma_f32_16x16x32_bf16 v[128:131], v[142:145], v[186:189], 0
	v_mfma_f32_16x16x32_bf16 v[128:131], v[146:149], v[190:193], v[128:131]
	v_mfma_f32_16x16x32_bf16 v[124:127], v[158:161], v[190:193], 0
	v_mfma_f32_16x16x32_bf16 v[124:127], v[154:157], v[186:189], v[124:127]
	v_mfma_f32_16x16x32_bf16 v[108:111], v[154:157], v[194:197], 0
	v_mfma_f32_16x16x32_bf16 v[108:111], v[158:161], v[208:211], v[108:111]
	v_mfma_f32_16x16x32_bf16 v[112:115], v[146:149], v[208:211], 0
	v_mfma_f32_16x16x32_bf16 v[112:115], v[142:145], v[194:197], v[112:115]
	v_mfma_f32_16x16x32_bf16 v[96:99], v[142:145], v[212:215], 0
	v_mfma_f32_16x16x32_bf16 v[96:99], v[146:149], v[216:219], v[96:99]
	v_mfma_f32_16x16x32_bf16 v[92:95], v[158:161], v[216:219], 0
	v_mfma_f32_16x16x32_bf16 v[92:95], v[154:157], v[212:215], v[92:95]
	v_mfma_f32_16x16x32_bf16 v[76:79], v[154:157], v[220:223], 0
	v_mfma_f32_16x16x32_bf16 v[76:79], v[158:161], v[224:227], v[76:79]
	v_mfma_f32_16x16x32_bf16 v[80:83], v[146:149], v[224:227], 0
	v_mfma_f32_16x16x32_bf16 v[80:83], v[142:145], v[220:223], v[80:83]
	s_setprio 0
	s_setprio 1
	v_mfma_f32_16x16x32_bf16 v[120:123], v[162:165], v[186:189], 0
	v_mfma_f32_16x16x32_bf16 v[120:123], v[166:169], v[190:193], v[120:123]
	v_mfma_f32_16x16x32_bf16 v[116:119], v[182:185], v[190:193], 0
	v_mfma_f32_16x16x32_bf16 v[116:119], v[178:181], v[186:189], v[116:119]
	v_mfma_f32_16x16x32_bf16 v[100:103], v[178:181], v[194:197], 0
	v_mfma_f32_16x16x32_bf16 v[100:103], v[182:185], v[208:211], v[100:103]
	v_mfma_f32_16x16x32_bf16 v[104:107], v[166:169], v[208:211], 0
	v_mfma_f32_16x16x32_bf16 v[104:107], v[162:165], v[194:197], v[104:107]
	v_mfma_f32_16x16x32_bf16 v[88:91], v[162:165], v[212:215], 0
	v_mfma_f32_16x16x32_bf16 v[88:91], v[166:169], v[216:219], v[88:91]
	v_mfma_f32_16x16x32_bf16 v[84:87], v[182:185], v[216:219], 0
	v_mfma_f32_16x16x32_bf16 v[84:87], v[178:181], v[212:215], v[84:87]
	v_mfma_f32_16x16x32_bf16 v[68:71], v[178:181], v[220:223], 0
	v_mfma_f32_16x16x32_bf16 v[68:71], v[182:185], v[224:227], v[68:71]
	v_mfma_f32_16x16x32_bf16 v[72:75], v[166:169], v[224:227], 0
	v_mfma_f32_16x16x32_bf16 v[72:75], v[162:165], v[220:223], v[72:75]
	s_setprio 0
	s_barrier
	s_add_i32 s43, s43, s54
	v_lshl_add_u64 v[228:229], s[34:35], 0, v[2:3]
	s_mov_b32 m0, s43
	ds_read_b128 v[186:189], v153 offset:16384
	ds_read_b128 v[190:193], v153 offset:17408
	ds_read_b128 v[194:197], v153 offset:18432
	ds_read_b128 v[208:211], v153 offset:19456
	ds_read_b128 v[212:215], v153 offset:20480
	ds_read_b128 v[216:219], v153 offset:21504
	ds_read_b128 v[220:223], v153 offset:22528
	ds_read_b128 v[224:227], v153 offset:23552
	global_load_lds_dwordx4 v[228:229], off
	s_add_i32 m0, s43, 0x2000
	s_add_u32 s64, s34, 0x80000
	v_lshl_add_u64 v[230:231], s[34:35], 0, v[132:133]
	s_addc_u32 s65, s35, 0
	s_add_i32 s43, s66, s54
	global_load_lds_dwordx4 v[230:231], off
	v_lshl_add_u64 v[232:233], s[64:65], 0, v[2:3]
	s_mov_b32 m0, s43
	v_lshl_add_u64 v[234:235], s[36:37], 0, v[134:135]
	global_load_lds_dwordx4 v[232:233], off
	v_lshl_add_u64 v[232:233], s[64:65], 0, v[132:133]
	s_add_i32 m0, s43, 0x2000
	s_nop 0
	global_load_lds_dwordx4 v[232:233], off
	v_lshl_add_u64 v[232:233], s[36:37], 0, v[136:137]
	s_mov_b32 m0, s56
	s_nop 0
	global_load_lds_dwordx4 v[232:233], off
	s_mov_b32 m0, s57
	s_nop 0
	global_load_lds_dwordx4 v[234:235], off
	s_waitcnt vmcnt(8)
	s_waitcnt lgkmcnt(0)
	s_barrier
	s_setprio 1
	s_waitcnt lgkmcnt(0)
	v_mfma_f32_16x16x32_bf16 v[64:67], v[142:145], v[186:189], 0
	v_mfma_f32_16x16x32_bf16 v[64:67], v[146:149], v[190:193], v[64:67]
	v_mfma_f32_16x16x32_bf16 v[60:63], v[158:161], v[190:193], 0
	v_mfma_f32_16x16x32_bf16 v[60:63], v[154:157], v[186:189], v[60:63]
	v_mfma_f32_16x16x32_bf16 v[44:47], v[154:157], v[194:197], 0
	v_mfma_f32_16x16x32_bf16 v[44:47], v[158:161], v[208:211], v[44:47]
	v_mfma_f32_16x16x32_bf16 v[48:51], v[146:149], v[208:211], 0
	v_mfma_f32_16x16x32_bf16 v[48:51], v[142:145], v[194:197], v[48:51]
	v_mfma_f32_16x16x32_bf16 v[32:35], v[142:145], v[212:215], 0
	v_mfma_f32_16x16x32_bf16 v[32:35], v[146:149], v[216:219], v[32:35]
	v_mfma_f32_16x16x32_bf16 v[28:31], v[158:161], v[216:219], 0
	v_mfma_f32_16x16x32_bf16 v[28:31], v[154:157], v[212:215], v[28:31]
	v_mfma_f32_16x16x32_bf16 v[12:15], v[154:157], v[220:223], 0
	v_mfma_f32_16x16x32_bf16 v[12:15], v[158:161], v[224:227], v[12:15]
	v_mfma_f32_16x16x32_bf16 v[16:19], v[146:149], v[224:227], 0
	v_mfma_f32_16x16x32_bf16 v[16:19], v[142:145], v[220:223], v[16:19]
	s_setprio 0
	s_setprio 1
	v_mfma_f32_16x16x32_bf16 v[56:59], v[162:165], v[186:189], 0
	v_mfma_f32_16x16x32_bf16 v[56:59], v[166:169], v[190:193], v[56:59]
	v_mfma_f32_16x16x32_bf16 v[52:55], v[182:185], v[190:193], 0
	v_mfma_f32_16x16x32_bf16 v[52:55], v[178:181], v[186:189], v[52:55]
	v_mfma_f32_16x16x32_bf16 v[36:39], v[178:181], v[194:197], 0
	v_mfma_f32_16x16x32_bf16 v[36:39], v[182:185], v[208:211], v[36:39]
	v_mfma_f32_16x16x32_bf16 v[40:43], v[166:169], v[208:211], 0
	v_mfma_f32_16x16x32_bf16 v[40:43], v[162:165], v[194:197], v[40:43]
	v_mfma_f32_16x16x32_bf16 v[24:27], v[162:165], v[212:215], 0
	v_mfma_f32_16x16x32_bf16 v[24:27], v[166:169], v[216:219], v[24:27]
	v_mfma_f32_16x16x32_bf16 v[20:23], v[182:185], v[216:219], 0
	v_mfma_f32_16x16x32_bf16 v[20:23], v[178:181], v[212:215], v[20:23]
	v_mfma_f32_16x16x32_bf16 v[4:7], v[178:181], v[220:223], 0
	v_mfma_f32_16x16x32_bf16 v[4:7], v[182:185], v[224:227], v[4:7]
	v_mfma_f32_16x16x32_bf16 v[8:11], v[166:169], v[224:227], 0
	v_mfma_f32_16x16x32_bf16 v[8:11], v[162:165], v[220:223], v[8:11]
	s_setprio 0
	s_barrier
	s_add_i32 s43, 0, 0x18000
	s_add_i32 s64, 0, 0x1c000
	v_add_u32_e32 v158, s43, v151
	v_add_u32_e32 v182, s64, v151
	ds_read_b128 v[142:145], v158
	ds_read_b128 v[146:149], v158 offset:1024
	ds_read_b128 v[154:157], v158 offset:2048
	ds_read_b128 v[158:161], v158 offset:3072
	ds_read_b128 v[162:165], v182
	ds_read_b128 v[166:169], v182 offset:1024
	ds_read_b128 v[178:181], v182 offset:2048
	ds_read_b128 v[182:185], v182 offset:3072
	s_add_u32 s36, s36, 0x80000
	s_addc_u32 s37, s37, 0
	s_mov_b32 m0, s58
	v_lshl_add_u64 v[236:237], s[36:37], 0, v[136:137]
	ds_read_b128 v[186:189], v153 offset:32768
	ds_read_b128 v[190:193], v153 offset:33792
	ds_read_b128 v[194:197], v153 offset:34816
	ds_read_b128 v[208:211], v153 offset:35840
	ds_read_b128 v[212:215], v153 offset:36864
	ds_read_b128 v[216:219], v153 offset:37888
	ds_read_b128 v[220:223], v153 offset:38912
	ds_read_b128 v[224:227], v153 offset:39936
	global_load_lds_dwordx4 v[236:237], off
	v_lshl_add_u64 v[236:237], s[36:37], 0, v[134:135]
	s_mov_b32 m0, s59
	s_nop 0
	global_load_lds_dwordx4 v[236:237], off
	s_waitcnt vmcnt(8)
	s_waitcnt lgkmcnt(0)
	s_barrier
	s_setprio 1
	s_waitcnt lgkmcnt(0)
	v_mfma_f32_16x16x32_bf16 v[128:131], v[142:145], v[186:189], v[128:131]
	v_mfma_f32_16x16x32_bf16 v[128:131], v[146:149], v[190:193], v[128:131]
	v_mfma_f32_16x16x32_bf16 v[124:127], v[158:161], v[190:193], v[124:127]
	v_mfma_f32_16x16x32_bf16 v[124:127], v[154:157], v[186:189], v[124:127]
	v_mfma_f32_16x16x32_bf16 v[108:111], v[154:157], v[194:197], v[108:111]
	v_mfma_f32_16x16x32_bf16 v[108:111], v[158:161], v[208:211], v[108:111]
	v_mfma_f32_16x16x32_bf16 v[112:115], v[146:149], v[208:211], v[112:115]
	v_mfma_f32_16x16x32_bf16 v[112:115], v[142:145], v[194:197], v[112:115]
	v_mfma_f32_16x16x32_bf16 v[96:99], v[142:145], v[212:215], v[96:99]
	v_mfma_f32_16x16x32_bf16 v[96:99], v[146:149], v[216:219], v[96:99]
	v_mfma_f32_16x16x32_bf16 v[92:95], v[158:161], v[216:219], v[92:95]
	v_mfma_f32_16x16x32_bf16 v[92:95], v[154:157], v[212:215], v[92:95]
	v_mfma_f32_16x16x32_bf16 v[76:79], v[154:157], v[220:223], v[76:79]
	v_mfma_f32_16x16x32_bf16 v[76:79], v[158:161], v[224:227], v[76:79]
	v_mfma_f32_16x16x32_bf16 v[80:83], v[146:149], v[224:227], v[80:83]
	v_mfma_f32_16x16x32_bf16 v[80:83], v[142:145], v[220:223], v[80:83]
	s_setprio 0
	s_setprio 1
	v_mfma_f32_16x16x32_bf16 v[120:123], v[162:165], v[186:189], v[120:123]
	v_mfma_f32_16x16x32_bf16 v[120:123], v[166:169], v[190:193], v[120:123]
	v_mfma_f32_16x16x32_bf16 v[116:119], v[182:185], v[190:193], v[116:119]
	v_mfma_f32_16x16x32_bf16 v[116:119], v[178:181], v[186:189], v[116:119]
	v_mfma_f32_16x16x32_bf16 v[100:103], v[178:181], v[194:197], v[100:103]
	v_mfma_f32_16x16x32_bf16 v[100:103], v[182:185], v[208:211], v[100:103]
	v_mfma_f32_16x16x32_bf16 v[104:107], v[166:169], v[208:211], v[104:107]
	v_mfma_f32_16x16x32_bf16 v[104:107], v[162:165], v[194:197], v[104:107]
	v_mfma_f32_16x16x32_bf16 v[88:91], v[162:165], v[212:215], v[88:91]
	v_mfma_f32_16x16x32_bf16 v[88:91], v[166:169], v[216:219], v[88:91]
	v_mfma_f32_16x16x32_bf16 v[84:87], v[182:185], v[216:219], v[84:87]
	v_mfma_f32_16x16x32_bf16 v[84:87], v[178:181], v[212:215], v[84:87]
	v_mfma_f32_16x16x32_bf16 v[68:71], v[178:181], v[220:223], v[68:71]
	v_mfma_f32_16x16x32_bf16 v[68:71], v[182:185], v[224:227], v[68:71]
	v_mfma_f32_16x16x32_bf16 v[72:75], v[166:169], v[224:227], v[72:75]
	v_mfma_f32_16x16x32_bf16 v[72:75], v[162:165], v[220:223], v[72:75]
	s_setprio 0
	s_barrier
	s_add_i32 s36, s43, s54
	v_lshl_add_u64 v[228:229], v[228:229], 0, s[18:19]
	s_mov_b32 m0, s36
	ds_read_b128 v[186:189], v153 offset:49152
	ds_read_b128 v[190:193], v153 offset:50176
	ds_read_b128 v[194:197], v153 offset:51200
	ds_read_b128 v[208:211], v153 offset:52224
	ds_read_b128 v[212:215], v153 offset:53248
	ds_read_b128 v[216:219], v153 offset:54272
	ds_read_b128 v[220:223], v153 offset:55296
	ds_read_b128 v[224:227], v153 offset:56320
	global_load_lds_dwordx4 v[228:229], off
	s_add_i32 m0, s36, 0x2000
	s_add_u32 s34, s34, 0x80080
	v_lshl_add_u64 v[228:229], v[230:231], 0, s[18:19]
	s_addc_u32 s35, s35, 0
	s_add_i32 s36, s64, s54
	global_load_lds_dwordx4 v[228:229], off
	v_lshl_add_u64 v[228:229], s[34:35], 0, v[2:3]
	s_mov_b32 m0, s36
	s_nop 0
	global_load_lds_dwordx4 v[228:229], off
	v_lshl_add_u64 v[228:229], s[34:35], 0, v[132:133]
	s_add_i32 m0, s36, 0x2000
	s_nop 0
	global_load_lds_dwordx4 v[228:229], off
	v_lshl_add_u64 v[228:229], v[232:233], 0, s[18:19]
	s_mov_b32 m0, s60
	s_nop 0
	global_load_lds_dwordx4 v[228:229], off
	v_lshl_add_u64 v[228:229], v[234:235], 0, s[18:19]
	s_mov_b32 m0, s61
	s_nop 0
	global_load_lds_dwordx4 v[228:229], off
	s_waitcnt vmcnt(8)
	s_waitcnt lgkmcnt(0)
	s_barrier
	s_setprio 1
	s_waitcnt lgkmcnt(0)
	v_mfma_f32_16x16x32_bf16 v[64:67], v[142:145], v[186:189], v[64:67]
	v_mfma_f32_16x16x32_bf16 v[64:67], v[146:149], v[190:193], v[64:67]
	v_mfma_f32_16x16x32_bf16 v[60:63], v[158:161], v[190:193], v[60:63]
	v_mfma_f32_16x16x32_bf16 v[60:63], v[154:157], v[186:189], v[60:63]
	v_mfma_f32_16x16x32_bf16 v[44:47], v[154:157], v[194:197], v[44:47]
	v_mfma_f32_16x16x32_bf16 v[44:47], v[158:161], v[208:211], v[44:47]
	v_mfma_f32_16x16x32_bf16 v[48:51], v[146:149], v[208:211], v[48:51]
	v_mfma_f32_16x16x32_bf16 v[48:51], v[142:145], v[194:197], v[48:51]
	v_mfma_f32_16x16x32_bf16 v[32:35], v[142:145], v[212:215], v[32:35]
	v_mfma_f32_16x16x32_bf16 v[32:35], v[146:149], v[216:219], v[32:35]
	v_mfma_f32_16x16x32_bf16 v[28:31], v[158:161], v[216:219], v[28:31]
	v_mfma_f32_16x16x32_bf16 v[28:31], v[154:157], v[212:215], v[28:31]
	v_mfma_f32_16x16x32_bf16 v[12:15], v[154:157], v[220:223], v[12:15]
	v_mfma_f32_16x16x32_bf16 v[12:15], v[158:161], v[224:227], v[12:15]
	v_mfma_f32_16x16x32_bf16 v[16:19], v[146:149], v[224:227], v[16:19]
	v_mfma_f32_16x16x32_bf16 v[16:19], v[142:145], v[220:223], v[16:19]
	s_setprio 0
	s_setprio 1
	v_mfma_f32_16x16x32_bf16 v[56:59], v[162:165], v[186:189], v[56:59]
	v_mfma_f32_16x16x32_bf16 v[56:59], v[166:169], v[190:193], v[56:59]
	v_mfma_f32_16x16x32_bf16 v[52:55], v[182:185], v[190:193], v[52:55]
	v_mfma_f32_16x16x32_bf16 v[52:55], v[178:181], v[186:189], v[52:55]
	v_mfma_f32_16x16x32_bf16 v[36:39], v[178:181], v[194:197], v[36:39]
	v_mfma_f32_16x16x32_bf16 v[36:39], v[182:185], v[208:211], v[36:39]
	v_mfma_f32_16x16x32_bf16 v[40:43], v[166:169], v[208:211], v[40:43]
	v_mfma_f32_16x16x32_bf16 v[40:43], v[162:165], v[194:197], v[40:43]
	v_mfma_f32_16x16x32_bf16 v[24:27], v[162:165], v[212:215], v[24:27]
	v_mfma_f32_16x16x32_bf16 v[24:27], v[166:169], v[216:219], v[24:27]
	v_mfma_f32_16x16x32_bf16 v[20:23], v[182:185], v[216:219], v[20:23]
	v_mfma_f32_16x16x32_bf16 v[20:23], v[178:181], v[212:215], v[20:23]
	v_mfma_f32_16x16x32_bf16 v[4:7], v[178:181], v[220:223], v[4:7]
	v_mfma_f32_16x16x32_bf16 v[4:7], v[182:185], v[224:227], v[4:7]
	v_mfma_f32_16x16x32_bf16 v[8:11], v[166:169], v[224:227], v[8:11]
	v_mfma_f32_16x16x32_bf16 v[8:11], v[162:165], v[220:223], v[8:11]
	s_setprio 0
	s_barrier
	s_add_i32 s33, s33, 2
	s_add_u32 s26, s26, 0x100
	s_addc_u32 s27, s27, 0
	s_add_u32 s22, s22, 0x100
	s_addc_u32 s29, s29, 0
	s_cmp_gt_u32 s33, 29

.LBB0_197:
	s_ashr_i32 s43, s42, 31
	s_lshl_b64 s[10:11], s[42:43], 20
	s_add_u32 s44, s51, s10
	s_addc_u32 s45, s52, s11
	s_and_b64 s[10:11], s[38:39], exec
	s_cselect_b32 s3, s45, s27
	s_cselect_b32 s10, s44, s26
	s_ashr_i32 s29, s28, 31
	s_lshl_b64 s[36:37], s[28:29], 20
	s_add_u32 s46, s7, s36
	s_addc_u32 s47, s53, s37
	s_and_b64 s[36:37], s[38:39], exec
	s_cselect_b32 s11, s47, s35
	s_cselect_b32 s21, s46, s34
	s_add_u32 s26, s26, 0x80080
	s_addc_u32 s27, s27, 0
	s_add_u32 s22, s34, 0x100
	s_addc_u32 s29, s35, 0
	s_mov_b32 s33, -2
	v_lshl_add_u32 v142, s2, 8, v151
	v_ashrrev_i32_e32 v143, 31, v142
	v_lshl_add_u64 v[144:145], v[142:143], 2, s[40:41]
	global_load_dword v244, v[144:145], off
	global_load_dword v245, v[144:145], off offset:64
	global_load_dword v246, v[144:145], off offset:128
	global_load_dword v247, v[144:145], off offset:192
	global_load_dword v248, v[144:145], off offset:512
	global_load_dword v249, v[144:145], off offset:576
	global_load_dword v250, v[144:145], off offset:640
	global_load_dword v251, v[144:145], off offset:704
	s_add_u32 s34, s26, 0xfff80080
	s_addc_u32 s35, s27, -1
	s_add_i32 s43, 0, 0x10000
	s_cmp_eq_u32 s33, 28
	s_cselect_b32 s37, s3, s35
	s_cselect_b32 s36, s10, s34
	s_cselect_b32 s35, s11, s29
	s_cselect_b32 s34, s21, s22
	s_add_i32 s66, 0, 0x14000
	v_add_u32_e32 v164, s43, v152
	v_add_u32_e32 v168, s66, v152
	ds_read_b128 v[142:145], v164
	ds_read_b128 v[146:149], v164 offset:1024
	ds_read_b128 v[160:163], v164 offset:2048
	ds_read_b128 v[164:167], v164 offset:3072
	ds_read_b128 v[178:181], v168
	ds_read_b128 v[182:185], v168 offset:1024
	ds_read_b128 v[186:189], v168 offset:2048
	ds_read_b128 v[190:193], v168 offset:3072
	v_lshl_add_u64 v[168:169], s[26:27], 0, v[138:139]
	s_add_i32 m0, s56, 0xc000
	ds_read_b128 v[194:197], v159
	ds_read_b128 v[208:211], v159 offset:1024
	ds_read_b128 v[212:215], v159 offset:2048
	ds_read_b128 v[216:219], v159 offset:3072
	ds_read_b128 v[220:223], v159 offset:4096
	ds_read_b128 v[224:227], v159 offset:5120
	ds_read_b128 v[228:231], v159 offset:6144
	ds_read_b128 v[232:235], v159 offset:7168
	global_load_lds_dwordx4 v[168:169], off
	v_lshl_add_u64 v[168:169], s[26:27], 0, v[140:141]
	s_add_i32 m0, s56, 0xe000
	s_nop 0
	global_load_lds_dwordx4 v[168:169], off
	s_waitcnt vmcnt(8)
	s_waitcnt lgkmcnt(0)
	s_barrier
	s_setprio 1
	s_waitcnt lgkmcnt(0)
	v_mfma_f32_16x16x32_bf16 v[128:131], v[142:145], v[194:197], 0
	v_mfma_f32_16x16x32_bf16 v[128:131], v[146:149], v[208:211], v[128:131]
	v_mfma_f32_16x16x32_bf16 v[124:127], v[164:167], v[208:211], 0
	v_mfma_f32_16x16x32_bf16 v[124:127], v[160:163], v[194:197], v[124:127]
	v_mfma_f32_16x16x32_bf16 v[108:111], v[160:163], v[212:215], 0
	v_mfma_f32_16x16x32_bf16 v[108:111], v[164:167], v[216:219], v[108:111]
	v_mfma_f32_16x16x32_bf16 v[112:115], v[146:149], v[216:219], 0
	v_mfma_f32_16x16x32_bf16 v[112:115], v[142:145], v[212:215], v[112:115]
	v_mfma_f32_16x16x32_bf16 v[96:99], v[142:145], v[220:223], 0
	v_mfma_f32_16x16x32_bf16 v[96:99], v[146:149], v[224:227], v[96:99]
	v_mfma_f32_16x16x32_bf16 v[92:95], v[164:167], v[224:227], 0
	v_mfma_f32_16x16x32_bf16 v[92:95], v[160:163], v[220:223], v[92:95]
	v_mfma_f32_16x16x32_bf16 v[76:79], v[160:163], v[228:231], 0
	v_mfma_f32_16x16x32_bf16 v[76:79], v[164:167], v[232:235], v[76:79]
	v_mfma_f32_16x16x32_bf16 v[80:83], v[146:149], v[232:235], 0
	v_mfma_f32_16x16x32_bf16 v[80:83], v[142:145], v[228:231], v[80:83]
	s_setprio 0
	s_setprio 1
	v_mfma_f32_16x16x32_bf16 v[120:123], v[178:181], v[194:197], 0
	v_mfma_f32_16x16x32_bf16 v[120:123], v[182:185], v[208:211], v[120:123]
	v_mfma_f32_16x16x32_bf16 v[116:119], v[190:193], v[208:211], 0
	v_mfma_f32_16x16x32_bf16 v[116:119], v[186:189], v[194:197], v[116:119]
	v_mfma_f32_16x16x32_bf16 v[100:103], v[186:189], v[212:215], 0
	v_mfma_f32_16x16x32_bf16 v[100:103], v[190:193], v[216:219], v[100:103]
	v_mfma_f32_16x16x32_bf16 v[104:107], v[182:185], v[216:219], 0
	v_mfma_f32_16x16x32_bf16 v[104:107], v[178:181], v[212:215], v[104:107]
	v_mfma_f32_16x16x32_bf16 v[88:91], v[178:181], v[220:223], 0
	v_mfma_f32_16x16x32_bf16 v[88:91], v[182:185], v[224:227], v[88:91]
	v_mfma_f32_16x16x32_bf16 v[84:87], v[190:193], v[224:227], 0
	v_mfma_f32_16x16x32_bf16 v[84:87], v[186:189], v[220:223], v[84:87]
	v_mfma_f32_16x16x32_bf16 v[68:71], v[186:189], v[228:231], 0
	v_mfma_f32_16x16x32_bf16 v[68:71], v[190:193], v[232:235], v[68:71]
	v_mfma_f32_16x16x32_bf16 v[72:75], v[182:185], v[232:235], 0
	v_mfma_f32_16x16x32_bf16 v[72:75], v[178:181], v[228:231], v[72:75]
	s_setprio 0
	s_barrier
	s_add_i32 s43, s43, s54
	v_lshl_add_u64 v[168:169], s[34:35], 0, v[2:3]
	s_mov_b32 m0, s43
	ds_read_b128 v[194:197], v159 offset:16384
	ds_read_b128 v[208:211], v159 offset:17408
	ds_read_b128 v[212:215], v159 offset:18432
	ds_read_b128 v[216:219], v159 offset:19456
	ds_read_b128 v[220:223], v159 offset:20480
	ds_read_b128 v[224:227], v159 offset:21504
	ds_read_b128 v[228:231], v159 offset:22528
	ds_read_b128 v[232:235], v159 offset:23552
	global_load_lds_dwordx4 v[168:169], off
	s_add_i32 m0, s43, 0x2000
	s_add_u32 s64, s34, 0x80000
	v_lshl_add_u64 v[236:237], s[34:35], 0, v[132:133]
	s_addc_u32 s65, s35, 0
	s_add_i32 s43, s66, s54
	global_load_lds_dwordx4 v[236:237], off
	v_lshl_add_u64 v[238:239], s[64:65], 0, v[2:3]
	s_mov_b32 m0, s43
	v_lshl_add_u64 v[240:241], s[36:37], 0, v[134:135]
	global_load_lds_dwordx4 v[238:239], off
	v_lshl_add_u64 v[238:239], s[64:65], 0, v[132:133]
	s_add_i32 m0, s43, 0x2000
	s_nop 0
	global_load_lds_dwordx4 v[238:239], off
	v_lshl_add_u64 v[238:239], s[36:37], 0, v[136:137]
	s_mov_b32 m0, s56
	s_nop 0
	global_load_lds_dwordx4 v[238:239], off
	s_mov_b32 m0, s57
	s_nop 0
	global_load_lds_dwordx4 v[240:241], off
	s_waitcnt vmcnt(8)
	s_waitcnt lgkmcnt(0)
	s_barrier
	s_setprio 1
	s_waitcnt lgkmcnt(0)
	v_mfma_f32_16x16x32_bf16 v[64:67], v[142:145], v[194:197], 0
	v_mfma_f32_16x16x32_bf16 v[64:67], v[146:149], v[208:211], v[64:67]
	v_mfma_f32_16x16x32_bf16 v[60:63], v[164:167], v[208:211], 0
	v_mfma_f32_16x16x32_bf16 v[60:63], v[160:163], v[194:197], v[60:63]
	v_mfma_f32_16x16x32_bf16 v[44:47], v[160:163], v[212:215], 0
	v_mfma_f32_16x16x32_bf16 v[44:47], v[164:167], v[216:219], v[44:47]
	v_mfma_f32_16x16x32_bf16 v[48:51], v[146:149], v[216:219], 0
	v_mfma_f32_16x16x32_bf16 v[48:51], v[142:145], v[212:215], v[48:51]
	v_mfma_f32_16x16x32_bf16 v[32:35], v[142:145], v[220:223], 0
	v_mfma_f32_16x16x32_bf16 v[32:35], v[146:149], v[224:227], v[32:35]
	v_mfma_f32_16x16x32_bf16 v[28:31], v[164:167], v[224:227], 0
	v_mfma_f32_16x16x32_bf16 v[28:31], v[160:163], v[220:223], v[28:31]
	v_mfma_f32_16x16x32_bf16 v[12:15], v[160:163], v[228:231], 0
	v_mfma_f32_16x16x32_bf16 v[12:15], v[164:167], v[232:235], v[12:15]
	v_mfma_f32_16x16x32_bf16 v[16:19], v[146:149], v[232:235], 0
	v_mfma_f32_16x16x32_bf16 v[16:19], v[142:145], v[228:231], v[16:19]
	s_setprio 0
	s_setprio 1
	v_mfma_f32_16x16x32_bf16 v[56:59], v[178:181], v[194:197], 0
	v_mfma_f32_16x16x32_bf16 v[56:59], v[182:185], v[208:211], v[56:59]
	v_mfma_f32_16x16x32_bf16 v[52:55], v[190:193], v[208:211], 0
	v_mfma_f32_16x16x32_bf16 v[52:55], v[186:189], v[194:197], v[52:55]
	v_mfma_f32_16x16x32_bf16 v[36:39], v[186:189], v[212:215], 0
	v_mfma_f32_16x16x32_bf16 v[36:39], v[190:193], v[216:219], v[36:39]
	v_mfma_f32_16x16x32_bf16 v[40:43], v[182:185], v[216:219], 0
	v_mfma_f32_16x16x32_bf16 v[40:43], v[178:181], v[212:215], v[40:43]
	v_mfma_f32_16x16x32_bf16 v[24:27], v[178:181], v[220:223], 0
	v_mfma_f32_16x16x32_bf16 v[24:27], v[182:185], v[224:227], v[24:27]
	v_mfma_f32_16x16x32_bf16 v[20:23], v[190:193], v[224:227], 0
	v_mfma_f32_16x16x32_bf16 v[20:23], v[186:189], v[220:223], v[20:23]
	v_mfma_f32_16x16x32_bf16 v[4:7], v[186:189], v[228:231], 0
	v_mfma_f32_16x16x32_bf16 v[4:7], v[190:193], v[232:235], v[4:7]
	v_mfma_f32_16x16x32_bf16 v[8:11], v[182:185], v[232:235], 0
	v_mfma_f32_16x16x32_bf16 v[8:11], v[178:181], v[228:231], v[8:11]
	s_setprio 0
	s_barrier
	s_add_i32 s43, 0, 0x18000
	s_add_i32 s64, 0, 0x1c000
	v_add_u32_e32 v164, s43, v152
	v_add_u32_e32 v190, s64, v152
	ds_read_b128 v[142:145], v164
	ds_read_b128 v[146:149], v164 offset:1024
	ds_read_b128 v[160:163], v164 offset:2048
	ds_read_b128 v[164:167], v164 offset:3072
	ds_read_b128 v[178:181], v190
	ds_read_b128 v[182:185], v190 offset:1024
	ds_read_b128 v[186:189], v190 offset:2048
	ds_read_b128 v[190:193], v190 offset:3072
	s_add_u32 s36, s36, 0x80000
	s_addc_u32 s37, s37, 0
	s_mov_b32 m0, s58
	v_lshl_add_u64 v[242:243], s[36:37], 0, v[136:137]
	ds_read_b128 v[194:197], v159 offset:32768
	ds_read_b128 v[208:211], v159 offset:33792
	ds_read_b128 v[212:215], v159 offset:34816
	ds_read_b128 v[216:219], v159 offset:35840
	ds_read_b128 v[220:223], v159 offset:36864
	ds_read_b128 v[224:227], v159 offset:37888
	ds_read_b128 v[228:231], v159 offset:38912
	ds_read_b128 v[232:235], v159 offset:39936
	global_load_lds_dwordx4 v[242:243], off
	v_lshl_add_u64 v[242:243], s[36:37], 0, v[134:135]
	s_mov_b32 m0, s59
	s_nop 0
	global_load_lds_dwordx4 v[242:243], off
	s_waitcnt vmcnt(8)
	s_waitcnt lgkmcnt(0)
	s_barrier
	s_setprio 1
	s_waitcnt lgkmcnt(0)
	v_mfma_f32_16x16x32_bf16 v[128:131], v[142:145], v[194:197], v[128:131]
	v_mfma_f32_16x16x32_bf16 v[128:131], v[146:149], v[208:211], v[128:131]
	v_mfma_f32_16x16x32_bf16 v[124:127], v[164:167], v[208:211], v[124:127]
	v_mfma_f32_16x16x32_bf16 v[124:127], v[160:163], v[194:197], v[124:127]
	v_mfma_f32_16x16x32_bf16 v[108:111], v[160:163], v[212:215], v[108:111]
	v_mfma_f32_16x16x32_bf16 v[108:111], v[164:167], v[216:219], v[108:111]
	v_mfma_f32_16x16x32_bf16 v[112:115], v[146:149], v[216:219], v[112:115]
	v_mfma_f32_16x16x32_bf16 v[112:115], v[142:145], v[212:215], v[112:115]
	v_mfma_f32_16x16x32_bf16 v[96:99], v[142:145], v[220:223], v[96:99]
	v_mfma_f32_16x16x32_bf16 v[96:99], v[146:149], v[224:227], v[96:99]
	v_mfma_f32_16x16x32_bf16 v[92:95], v[164:167], v[224:227], v[92:95]
	v_mfma_f32_16x16x32_bf16 v[92:95], v[160:163], v[220:223], v[92:95]
	v_mfma_f32_16x16x32_bf16 v[76:79], v[160:163], v[228:231], v[76:79]
	v_mfma_f32_16x16x32_bf16 v[76:79], v[164:167], v[232:235], v[76:79]
	v_mfma_f32_16x16x32_bf16 v[80:83], v[146:149], v[232:235], v[80:83]
	v_mfma_f32_16x16x32_bf16 v[80:83], v[142:145], v[228:231], v[80:83]
	s_setprio 0
	s_setprio 1
	v_mfma_f32_16x16x32_bf16 v[120:123], v[178:181], v[194:197], v[120:123]
	v_mfma_f32_16x16x32_bf16 v[120:123], v[182:185], v[208:211], v[120:123]
	v_mfma_f32_16x16x32_bf16 v[116:119], v[190:193], v[208:211], v[116:119]
	v_mfma_f32_16x16x32_bf16 v[116:119], v[186:189], v[194:197], v[116:119]
	v_mfma_f32_16x16x32_bf16 v[100:103], v[186:189], v[212:215], v[100:103]
	v_mfma_f32_16x16x32_bf16 v[100:103], v[190:193], v[216:219], v[100:103]
	v_mfma_f32_16x16x32_bf16 v[104:107], v[182:185], v[216:219], v[104:107]
	v_mfma_f32_16x16x32_bf16 v[104:107], v[178:181], v[212:215], v[104:107]
	v_mfma_f32_16x16x32_bf16 v[88:91], v[178:181], v[220:223], v[88:91]
	v_mfma_f32_16x16x32_bf16 v[88:91], v[182:185], v[224:227], v[88:91]
	v_mfma_f32_16x16x32_bf16 v[84:87], v[190:193], v[224:227], v[84:87]
	v_mfma_f32_16x16x32_bf16 v[84:87], v[186:189], v[220:223], v[84:87]
	v_mfma_f32_16x16x32_bf16 v[68:71], v[186:189], v[228:231], v[68:71]
	v_mfma_f32_16x16x32_bf16 v[68:71], v[190:193], v[232:235], v[68:71]
	v_mfma_f32_16x16x32_bf16 v[72:75], v[182:185], v[232:235], v[72:75]
	v_mfma_f32_16x16x32_bf16 v[72:75], v[178:181], v[228:231], v[72:75]
	s_setprio 0
	s_barrier
	s_add_i32 s36, s43, s54
	v_lshl_add_u64 v[168:169], v[168:169], 0, s[18:19]
	s_mov_b32 m0, s36
	ds_read_b128 v[194:197], v159 offset:49152
	ds_read_b128 v[208:211], v159 offset:50176
	ds_read_b128 v[212:215], v159 offset:51200
	ds_read_b128 v[216:219], v159 offset:52224
	ds_read_b128 v[220:223], v159 offset:53248
	ds_read_b128 v[224:227], v159 offset:54272
	ds_read_b128 v[228:231], v159 offset:55296
	ds_read_b128 v[232:235], v159 offset:56320
	global_load_lds_dwordx4 v[168:169], off
	s_add_i32 m0, s36, 0x2000
	s_add_u32 s34, s34, 0x80080
	v_lshl_add_u64 v[168:169], v[236:237], 0, s[18:19]
	s_addc_u32 s35, s35, 0
	s_add_i32 s36, s64, s54
	global_load_lds_dwordx4 v[168:169], off
	v_lshl_add_u64 v[168:169], s[34:35], 0, v[2:3]
	s_mov_b32 m0, s36
	s_nop 0
	global_load_lds_dwordx4 v[168:169], off
	v_lshl_add_u64 v[168:169], s[34:35], 0, v[132:133]
	s_add_i32 m0, s36, 0x2000
	s_nop 0
	global_load_lds_dwordx4 v[168:169], off
	v_lshl_add_u64 v[168:169], v[238:239], 0, s[18:19]
	s_mov_b32 m0, s60
	s_nop 0
	global_load_lds_dwordx4 v[168:169], off
	v_lshl_add_u64 v[168:169], v[240:241], 0, s[18:19]
	s_mov_b32 m0, s61
	s_nop 0
	global_load_lds_dwordx4 v[168:169], off
	s_waitcnt vmcnt(8)
	s_waitcnt lgkmcnt(0)
	s_barrier
	s_setprio 1
	s_waitcnt lgkmcnt(0)
	v_mfma_f32_16x16x32_bf16 v[64:67], v[142:145], v[194:197], v[64:67]
	v_mfma_f32_16x16x32_bf16 v[64:67], v[146:149], v[208:211], v[64:67]
	v_mfma_f32_16x16x32_bf16 v[60:63], v[164:167], v[208:211], v[60:63]
	v_mfma_f32_16x16x32_bf16 v[60:63], v[160:163], v[194:197], v[60:63]
	v_mfma_f32_16x16x32_bf16 v[44:47], v[160:163], v[212:215], v[44:47]
	v_mfma_f32_16x16x32_bf16 v[44:47], v[164:167], v[216:219], v[44:47]
	v_mfma_f32_16x16x32_bf16 v[48:51], v[146:149], v[216:219], v[48:51]
	v_mfma_f32_16x16x32_bf16 v[48:51], v[142:145], v[212:215], v[48:51]
	v_mfma_f32_16x16x32_bf16 v[32:35], v[142:145], v[220:223], v[32:35]
	v_mfma_f32_16x16x32_bf16 v[32:35], v[146:149], v[224:227], v[32:35]
	v_mfma_f32_16x16x32_bf16 v[28:31], v[164:167], v[224:227], v[28:31]
	v_mfma_f32_16x16x32_bf16 v[28:31], v[160:163], v[220:223], v[28:31]
	v_mfma_f32_16x16x32_bf16 v[12:15], v[160:163], v[228:231], v[12:15]
	v_mfma_f32_16x16x32_bf16 v[12:15], v[164:167], v[232:235], v[12:15]
	v_mfma_f32_16x16x32_bf16 v[16:19], v[146:149], v[232:235], v[16:19]
	v_mfma_f32_16x16x32_bf16 v[16:19], v[142:145], v[228:231], v[16:19]
	s_setprio 0
	s_setprio 1
	v_mfma_f32_16x16x32_bf16 v[56:59], v[178:181], v[194:197], v[56:59]
	v_mfma_f32_16x16x32_bf16 v[56:59], v[182:185], v[208:211], v[56:59]
	v_mfma_f32_16x16x32_bf16 v[52:55], v[190:193], v[208:211], v[52:55]
	v_mfma_f32_16x16x32_bf16 v[52:55], v[186:189], v[194:197], v[52:55]
	v_mfma_f32_16x16x32_bf16 v[36:39], v[186:189], v[212:215], v[36:39]
	v_mfma_f32_16x16x32_bf16 v[36:39], v[190:193], v[216:219], v[36:39]
	v_mfma_f32_16x16x32_bf16 v[40:43], v[182:185], v[216:219], v[40:43]
	v_mfma_f32_16x16x32_bf16 v[40:43], v[178:181], v[212:215], v[40:43]
	v_mfma_f32_16x16x32_bf16 v[24:27], v[178:181], v[220:223], v[24:27]
	v_mfma_f32_16x16x32_bf16 v[24:27], v[182:185], v[224:227], v[24:27]
	v_mfma_f32_16x16x32_bf16 v[20:23], v[190:193], v[224:227], v[20:23]
	v_mfma_f32_16x16x32_bf16 v[20:23], v[186:189], v[220:223], v[20:23]
	v_mfma_f32_16x16x32_bf16 v[4:7], v[186:189], v[228:231], v[4:7]
	v_mfma_f32_16x16x32_bf16 v[4:7], v[190:193], v[232:235], v[4:7]
	v_mfma_f32_16x16x32_bf16 v[8:11], v[182:185], v[232:235], v[8:11]
	v_mfma_f32_16x16x32_bf16 v[8:11], v[178:181], v[228:231], v[8:11]
	s_setprio 0
	s_barrier
	s_add_i32 s33, s33, 2
	s_add_u32 s26, s26, 0x100
	s_addc_u32 s27, s27, 0
	s_add_u32 s22, s22, 0x100
	s_addc_u32 s29, s29, 0
	s_cmp_gt_u32 s33, 29

.LBB0_707:
	s_ashr_i32 s27, s26, 31
	s_lshl_b64 s[34:35], s[26:27], 20
	s_add_u32 s34, s59, s34
	s_addc_u32 s35, s60, s35
	s_and_b64 s[36:37], s[38:39], exec
	s_cselect_b32 s27, s35, s41
	s_cselect_b32 s51, s34, s40
	s_ashr_i32 s13, s12, 31
	s_lshl_b64 s[36:37], s[12:13], 20
	s_add_u32 s36, s1, s36
	s_addc_u32 s37, s7, s37
	s_and_b64 s[44:45], s[38:39], exec
	s_cselect_b32 s13, s37, s43
	s_cselect_b32 s52, s36, s42
	s_add_u32 s40, s40, 0x80080
	s_addc_u32 s41, s41, 0
	s_add_u32 s53, s42, 0x100
	s_addc_u32 s54, s43, 0
	s_mov_b32 s55, -2
	s_add_u32 s42, s40, 0xfff80080
	s_addc_u32 s43, s41, -1
	s_add_i32 s61, 0, 0x10000
	s_cmp_eq_u32 s55, 28
	s_cselect_b32 s45, s27, s43
	s_cselect_b32 s44, s51, s42
	v_add_u32_e32 v142, s61, v144
	s_cselect_b32 s43, s13, s54
	s_cselect_b32 s42, s52, s53
	s_add_i32 s65, 0, 0x14000
	ds_read_b128 v[148:151], v142
	ds_read_b128 v[152:155], v142 offset:1024
	ds_read_b128 v[156:159], v142 offset:2048
	ds_read_b128 v[160:163], v142 offset:3072
	v_add_u32_e32 v142, s65, v144
	ds_read_b128 v[164:167], v142
	ds_read_b128 v[178:181], v142 offset:1024
	ds_read_b128 v[182:185], v142 offset:2048
	ds_read_b128 v[186:189], v142 offset:3072
	v_lshl_add_u64 v[142:143], s[40:41], 0, v[138:139]
	s_add_i32 m0, s21, 0xc000
	ds_read_b128 v[190:193], v146
	ds_read_b128 v[194:197], v146 offset:1024
	ds_read_b128 v[208:211], v146 offset:2048
	ds_read_b128 v[212:215], v146 offset:3072
	ds_read_b128 v[216:219], v146 offset:4096
	ds_read_b128 v[220:223], v146 offset:5120
	ds_read_b128 v[224:227], v146 offset:6144
	ds_read_b128 v[228:231], v146 offset:7168
	global_load_lds_dwordx4 v[142:143], off
	v_lshl_add_u64 v[142:143], s[40:41], 0, v[140:141]
	s_add_i32 m0, s21, 0xe000
	s_nop 0
	global_load_lds_dwordx4 v[142:143], off
	s_waitcnt vmcnt(8)
	s_waitcnt lgkmcnt(0)
	s_barrier
	s_setprio 1
	s_waitcnt lgkmcnt(0)
	v_mfma_f32_16x16x32_bf16 v[128:131], v[148:151], v[190:193], 0
	v_mfma_f32_16x16x32_bf16 v[128:131], v[152:155], v[194:197], v[128:131]
	v_mfma_f32_16x16x32_bf16 v[124:127], v[160:163], v[194:197], 0
	v_mfma_f32_16x16x32_bf16 v[124:127], v[156:159], v[190:193], v[124:127]
	v_mfma_f32_16x16x32_bf16 v[112:115], v[156:159], v[208:211], 0
	v_mfma_f32_16x16x32_bf16 v[112:115], v[160:163], v[212:215], v[112:115]
	v_mfma_f32_16x16x32_bf16 v[120:123], v[152:155], v[212:215], 0
	v_mfma_f32_16x16x32_bf16 v[120:123], v[148:151], v[208:211], v[120:123]
	v_mfma_f32_16x16x32_bf16 v[104:107], v[148:151], v[216:219], 0
	v_mfma_f32_16x16x32_bf16 v[104:107], v[152:155], v[220:223], v[104:107]
	v_mfma_f32_16x16x32_bf16 v[96:99], v[160:163], v[220:223], 0
	v_mfma_f32_16x16x32_bf16 v[96:99], v[156:159], v[216:219], v[96:99]
	v_mfma_f32_16x16x32_bf16 v[80:83], v[156:159], v[224:227], 0
	v_mfma_f32_16x16x32_bf16 v[80:83], v[160:163], v[228:231], v[80:83]
	v_mfma_f32_16x16x32_bf16 v[88:91], v[152:155], v[228:231], 0
	v_mfma_f32_16x16x32_bf16 v[88:91], v[148:151], v[224:227], v[88:91]
	s_setprio 0
	s_setprio 1
	v_mfma_f32_16x16x32_bf16 v[116:119], v[164:167], v[190:193], 0
	v_mfma_f32_16x16x32_bf16 v[116:119], v[178:181], v[194:197], v[116:119]
	v_mfma_f32_16x16x32_bf16 v[108:111], v[186:189], v[194:197], 0
	v_mfma_f32_16x16x32_bf16 v[108:111], v[182:185], v[190:193], v[108:111]
	v_mfma_f32_16x16x32_bf16 v[92:95], v[182:185], v[208:211], 0
	v_mfma_f32_16x16x32_bf16 v[92:95], v[186:189], v[212:215], v[92:95]
	v_mfma_f32_16x16x32_bf16 v[100:103], v[178:181], v[212:215], 0
	v_mfma_f32_16x16x32_bf16 v[100:103], v[164:167], v[208:211], v[100:103]
	v_mfma_f32_16x16x32_bf16 v[84:87], v[164:167], v[216:219], 0
	v_mfma_f32_16x16x32_bf16 v[84:87], v[178:181], v[220:223], v[84:87]
	v_mfma_f32_16x16x32_bf16 v[76:79], v[186:189], v[220:223], 0
	v_mfma_f32_16x16x32_bf16 v[76:79], v[182:185], v[216:219], v[76:79]
	v_mfma_f32_16x16x32_bf16 v[68:71], v[182:185], v[224:227], 0
	v_mfma_f32_16x16x32_bf16 v[68:71], v[186:189], v[228:231], v[68:71]
	v_mfma_f32_16x16x32_bf16 v[72:75], v[178:181], v[228:231], 0
	v_mfma_f32_16x16x32_bf16 v[72:75], v[164:167], v[224:227], v[72:75]
	s_setprio 0
	s_barrier
	s_add_i32 s61, s61, s11
	v_lshl_add_u64 v[142:143], s[42:43], 0, v[2:3]
	s_mov_b32 m0, s61
	ds_read_b128 v[190:193], v146 offset:16384
	ds_read_b128 v[194:197], v146 offset:17408
	ds_read_b128 v[208:211], v146 offset:18432
	ds_read_b128 v[212:215], v146 offset:19456
	ds_read_b128 v[216:219], v146 offset:20480
	ds_read_b128 v[220:223], v146 offset:21504
	ds_read_b128 v[224:227], v146 offset:22528
	ds_read_b128 v[228:231], v146 offset:23552
	global_load_lds_dwordx4 v[142:143], off
	s_add_i32 m0, s61, 0x2000
	s_add_u32 s62, s42, 0x80000
	v_lshl_add_u64 v[168:169], s[42:43], 0, v[136:137]
	s_addc_u32 s63, s43, 0
	s_add_i32 s61, s65, s11
	global_load_lds_dwordx4 v[168:169], off
	v_lshl_add_u64 v[232:233], s[62:63], 0, v[2:3]
	s_mov_b32 m0, s61
	v_lshl_add_u64 v[234:235], s[44:45], 0, v[134:135]
	global_load_lds_dwordx4 v[232:233], off
	v_lshl_add_u64 v[232:233], s[62:63], 0, v[136:137]
	s_add_i32 m0, s61, 0x2000
	s_nop 0
	global_load_lds_dwordx4 v[232:233], off
	v_lshl_add_u64 v[232:233], s[44:45], 0, v[132:133]
	s_mov_b32 m0, s21
	s_nop 0
	global_load_lds_dwordx4 v[232:233], off
	s_mov_b32 m0, s22
	s_nop 0
	global_load_lds_dwordx4 v[234:235], off
	s_waitcnt vmcnt(8)
	s_waitcnt lgkmcnt(0)
	s_barrier
	s_setprio 1
	s_waitcnt lgkmcnt(0)
	v_mfma_f32_16x16x32_bf16 v[64:67], v[148:151], v[190:193], 0
	v_mfma_f32_16x16x32_bf16 v[64:67], v[152:155], v[194:197], v[64:67]
	v_mfma_f32_16x16x32_bf16 v[60:63], v[160:163], v[194:197], 0
	v_mfma_f32_16x16x32_bf16 v[60:63], v[156:159], v[190:193], v[60:63]
	v_mfma_f32_16x16x32_bf16 v[48:51], v[156:159], v[208:211], 0
	v_mfma_f32_16x16x32_bf16 v[48:51], v[160:163], v[212:215], v[48:51]
	v_mfma_f32_16x16x32_bf16 v[56:59], v[152:155], v[212:215], 0
	v_mfma_f32_16x16x32_bf16 v[56:59], v[148:151], v[208:211], v[56:59]
	v_mfma_f32_16x16x32_bf16 v[40:43], v[148:151], v[216:219], 0
	v_mfma_f32_16x16x32_bf16 v[40:43], v[152:155], v[220:223], v[40:43]
	v_mfma_f32_16x16x32_bf16 v[32:35], v[160:163], v[220:223], 0
	v_mfma_f32_16x16x32_bf16 v[32:35], v[156:159], v[216:219], v[32:35]
	v_mfma_f32_16x16x32_bf16 v[16:19], v[156:159], v[224:227], 0
	v_mfma_f32_16x16x32_bf16 v[16:19], v[160:163], v[228:231], v[16:19]
	v_mfma_f32_16x16x32_bf16 v[24:27], v[152:155], v[228:231], 0
	v_mfma_f32_16x16x32_bf16 v[24:27], v[148:151], v[224:227], v[24:27]
	s_setprio 0
	s_setprio 1
	v_mfma_f32_16x16x32_bf16 v[52:55], v[164:167], v[190:193], 0
	v_mfma_f32_16x16x32_bf16 v[52:55], v[178:181], v[194:197], v[52:55]
	v_mfma_f32_16x16x32_bf16 v[44:47], v[186:189], v[194:197], 0
	v_mfma_f32_16x16x32_bf16 v[44:47], v[182:185], v[190:193], v[44:47]
	v_mfma_f32_16x16x32_bf16 v[28:31], v[182:185], v[208:211], 0
	v_mfma_f32_16x16x32_bf16 v[28:31], v[186:189], v[212:215], v[28:31]
	v_mfma_f32_16x16x32_bf16 v[36:39], v[178:181], v[212:215], 0
	v_mfma_f32_16x16x32_bf16 v[36:39], v[164:167], v[208:211], v[36:39]
	v_mfma_f32_16x16x32_bf16 v[20:23], v[164:167], v[216:219], 0
	v_mfma_f32_16x16x32_bf16 v[20:23], v[178:181], v[220:223], v[20:23]
	v_mfma_f32_16x16x32_bf16 v[12:15], v[186:189], v[220:223], 0
	v_mfma_f32_16x16x32_bf16 v[12:15], v[182:185], v[216:219], v[12:15]
	v_mfma_f32_16x16x32_bf16 v[4:7], v[182:185], v[224:227], 0
	v_mfma_f32_16x16x32_bf16 v[4:7], v[186:189], v[228:231], v[4:7]
	v_mfma_f32_16x16x32_bf16 v[8:11], v[178:181], v[228:231], 0
	v_mfma_f32_16x16x32_bf16 v[8:11], v[164:167], v[224:227], v[8:11]
	s_setprio 0
	s_barrier
	s_add_i32 s61, 0, 0x18000
	v_add_u32_e32 v147, s61, v144
	s_add_i32 s62, 0, 0x1c000
	ds_read_b128 v[148:151], v147
	ds_read_b128 v[152:155], v147 offset:1024
	ds_read_b128 v[156:159], v147 offset:2048
	ds_read_b128 v[160:163], v147 offset:3072
	v_add_u32_e32 v147, s62, v144
	ds_read_b128 v[164:167], v147
	ds_read_b128 v[178:181], v147 offset:1024
	ds_read_b128 v[182:185], v147 offset:2048
	ds_read_b128 v[186:189], v147 offset:3072
	s_add_u32 s44, s44, 0x80000
	s_addc_u32 s45, s45, 0
	s_mov_b32 m0, s33
	v_lshl_add_u64 v[236:237], s[44:45], 0, v[132:133]
	ds_read_b128 v[190:193], v146 offset:32768
	ds_read_b128 v[194:197], v146 offset:33792
	ds_read_b128 v[208:211], v146 offset:34816
	ds_read_b128 v[212:215], v146 offset:35840
	ds_read_b128 v[216:219], v146 offset:36864
	ds_read_b128 v[220:223], v146 offset:37888
	ds_read_b128 v[224:227], v146 offset:38912
	ds_read_b128 v[228:231], v146 offset:39936
	global_load_lds_dwordx4 v[236:237], off
	v_lshl_add_u64 v[236:237], s[44:45], 0, v[134:135]
	s_mov_b32 m0, s46
	s_nop 0
	global_load_lds_dwordx4 v[236:237], off
	s_waitcnt vmcnt(8)
	s_waitcnt lgkmcnt(0)
	s_barrier
	s_setprio 1
	s_waitcnt lgkmcnt(0)
	v_mfma_f32_16x16x32_bf16 v[128:131], v[148:151], v[190:193], v[128:131]
	v_mfma_f32_16x16x32_bf16 v[128:131], v[152:155], v[194:197], v[128:131]
	v_mfma_f32_16x16x32_bf16 v[124:127], v[160:163], v[194:197], v[124:127]
	v_mfma_f32_16x16x32_bf16 v[124:127], v[156:159], v[190:193], v[124:127]
	v_mfma_f32_16x16x32_bf16 v[112:115], v[156:159], v[208:211], v[112:115]
	v_mfma_f32_16x16x32_bf16 v[112:115], v[160:163], v[212:215], v[112:115]
	v_mfma_f32_16x16x32_bf16 v[120:123], v[152:155], v[212:215], v[120:123]
	v_mfma_f32_16x16x32_bf16 v[120:123], v[148:151], v[208:211], v[120:123]
	v_mfma_f32_16x16x32_bf16 v[104:107], v[148:151], v[216:219], v[104:107]
	v_mfma_f32_16x16x32_bf16 v[104:107], v[152:155], v[220:223], v[104:107]
	v_mfma_f32_16x16x32_bf16 v[96:99], v[160:163], v[220:223], v[96:99]
	v_mfma_f32_16x16x32_bf16 v[96:99], v[156:159], v[216:219], v[96:99]
	v_mfma_f32_16x16x32_bf16 v[80:83], v[156:159], v[224:227], v[80:83]
	v_mfma_f32_16x16x32_bf16 v[80:83], v[160:163], v[228:231], v[80:83]
	v_mfma_f32_16x16x32_bf16 v[88:91], v[152:155], v[228:231], v[88:91]
	v_mfma_f32_16x16x32_bf16 v[88:91], v[148:151], v[224:227], v[88:91]
	s_setprio 0
	s_setprio 1
	v_mfma_f32_16x16x32_bf16 v[116:119], v[164:167], v[190:193], v[116:119]
	v_mfma_f32_16x16x32_bf16 v[116:119], v[178:181], v[194:197], v[116:119]
	v_mfma_f32_16x16x32_bf16 v[108:111], v[186:189], v[194:197], v[108:111]
	v_mfma_f32_16x16x32_bf16 v[108:111], v[182:185], v[190:193], v[108:111]
	v_mfma_f32_16x16x32_bf16 v[92:95], v[182:185], v[208:211], v[92:95]
	v_mfma_f32_16x16x32_bf16 v[92:95], v[186:189], v[212:215], v[92:95]
	v_mfma_f32_16x16x32_bf16 v[100:103], v[178:181], v[212:215], v[100:103]
	v_mfma_f32_16x16x32_bf16 v[100:103], v[164:167], v[208:211], v[100:103]
	v_mfma_f32_16x16x32_bf16 v[84:87], v[164:167], v[216:219], v[84:87]
	v_mfma_f32_16x16x32_bf16 v[84:87], v[178:181], v[220:223], v[84:87]
	v_mfma_f32_16x16x32_bf16 v[76:79], v[186:189], v[220:223], v[76:79]
	v_mfma_f32_16x16x32_bf16 v[76:79], v[182:185], v[216:219], v[76:79]
	v_mfma_f32_16x16x32_bf16 v[68:71], v[182:185], v[224:227], v[68:71]
	v_mfma_f32_16x16x32_bf16 v[68:71], v[186:189], v[228:231], v[68:71]
	v_mfma_f32_16x16x32_bf16 v[72:75], v[178:181], v[228:231], v[72:75]
	v_mfma_f32_16x16x32_bf16 v[72:75], v[164:167], v[224:227], v[72:75]
	s_setprio 0
	s_barrier
	s_add_i32 s44, s61, s11
	v_lshl_add_u64 v[142:143], v[142:143], 0, s[18:19]
	s_mov_b32 m0, s44
	ds_read_b128 v[190:193], v146 offset:49152
	ds_read_b128 v[194:197], v146 offset:50176
	ds_read_b128 v[208:211], v146 offset:51200
	ds_read_b128 v[212:215], v146 offset:52224
	ds_read_b128 v[216:219], v146 offset:53248
	ds_read_b128 v[220:223], v146 offset:54272
	ds_read_b128 v[224:227], v146 offset:55296
	ds_read_b128 v[228:231], v146 offset:56320
	global_load_lds_dwordx4 v[142:143], off
	s_add_i32 m0, s44, 0x2000
	s_add_u32 s42, s42, 0x80080
	v_lshl_add_u64 v[142:143], v[168:169], 0, s[18:19]
	s_addc_u32 s43, s43, 0
	s_add_i32 s44, s62, s11
	global_load_lds_dwordx4 v[142:143], off
	v_lshl_add_u64 v[142:143], s[42:43], 0, v[2:3]
	s_mov_b32 m0, s44
	s_nop 0
	global_load_lds_dwordx4 v[142:143], off
	v_lshl_add_u64 v[142:143], s[42:43], 0, v[136:137]
	s_add_i32 m0, s44, 0x2000
	s_nop 0
	global_load_lds_dwordx4 v[142:143], off
	v_lshl_add_u64 v[142:143], v[232:233], 0, s[18:19]
	s_mov_b32 m0, s47
	s_nop 0
	global_load_lds_dwordx4 v[142:143], off
	v_lshl_add_u64 v[142:143], v[234:235], 0, s[18:19]
	s_mov_b32 m0, s48
	s_nop 0
	global_load_lds_dwordx4 v[142:143], off
	s_waitcnt vmcnt(8)
	s_waitcnt lgkmcnt(0)
	s_barrier
	s_setprio 1
	s_waitcnt lgkmcnt(0)
	v_mfma_f32_16x16x32_bf16 v[64:67], v[148:151], v[190:193], v[64:67]
	v_mfma_f32_16x16x32_bf16 v[64:67], v[152:155], v[194:197], v[64:67]
	v_mfma_f32_16x16x32_bf16 v[60:63], v[160:163], v[194:197], v[60:63]
	v_mfma_f32_16x16x32_bf16 v[60:63], v[156:159], v[190:193], v[60:63]
	v_mfma_f32_16x16x32_bf16 v[48:51], v[156:159], v[208:211], v[48:51]
	v_mfma_f32_16x16x32_bf16 v[48:51], v[160:163], v[212:215], v[48:51]
	v_mfma_f32_16x16x32_bf16 v[56:59], v[152:155], v[212:215], v[56:59]
	v_mfma_f32_16x16x32_bf16 v[56:59], v[148:151], v[208:211], v[56:59]
	v_mfma_f32_16x16x32_bf16 v[40:43], v[148:151], v[216:219], v[40:43]
	v_mfma_f32_16x16x32_bf16 v[40:43], v[152:155], v[220:223], v[40:43]
	v_mfma_f32_16x16x32_bf16 v[32:35], v[160:163], v[220:223], v[32:35]
	v_mfma_f32_16x16x32_bf16 v[32:35], v[156:159], v[216:219], v[32:35]
	v_mfma_f32_16x16x32_bf16 v[16:19], v[156:159], v[224:227], v[16:19]
	v_mfma_f32_16x16x32_bf16 v[16:19], v[160:163], v[228:231], v[16:19]
	v_mfma_f32_16x16x32_bf16 v[24:27], v[152:155], v[228:231], v[24:27]
	v_mfma_f32_16x16x32_bf16 v[24:27], v[148:151], v[224:227], v[24:27]
	s_setprio 0
	s_setprio 1
	v_mfma_f32_16x16x32_bf16 v[52:55], v[164:167], v[190:193], v[52:55]
	v_mfma_f32_16x16x32_bf16 v[52:55], v[178:181], v[194:197], v[52:55]
	v_mfma_f32_16x16x32_bf16 v[44:47], v[186:189], v[194:197], v[44:47]
	v_mfma_f32_16x16x32_bf16 v[44:47], v[182:185], v[190:193], v[44:47]
	v_mfma_f32_16x16x32_bf16 v[28:31], v[182:185], v[208:211], v[28:31]
	v_mfma_f32_16x16x32_bf16 v[28:31], v[186:189], v[212:215], v[28:31]
	v_mfma_f32_16x16x32_bf16 v[36:39], v[178:181], v[212:215], v[36:39]
	v_mfma_f32_16x16x32_bf16 v[36:39], v[164:167], v[208:211], v[36:39]
	v_mfma_f32_16x16x32_bf16 v[20:23], v[164:167], v[216:219], v[20:23]
	v_mfma_f32_16x16x32_bf16 v[20:23], v[178:181], v[220:223], v[20:23]
	v_mfma_f32_16x16x32_bf16 v[12:15], v[186:189], v[220:223], v[12:15]
	v_mfma_f32_16x16x32_bf16 v[12:15], v[182:185], v[216:219], v[12:15]
	v_mfma_f32_16x16x32_bf16 v[4:7], v[182:185], v[224:227], v[4:7]
	v_mfma_f32_16x16x32_bf16 v[4:7], v[186:189], v[228:231], v[4:7]
	v_mfma_f32_16x16x32_bf16 v[8:11], v[178:181], v[228:231], v[8:11]
	v_mfma_f32_16x16x32_bf16 v[8:11], v[164:167], v[224:227], v[8:11]
	s_setprio 0
	s_barrier
	s_add_i32 s55, s55, 2
	s_add_u32 s40, s40, 0x100
	s_addc_u32 s41, s41, 0
	s_add_u32 s53, s53, 0x100
	s_addc_u32 s54, s54, 0
	s_cmp_gt_u32 s55, 29

.LBB0_721:
	s_add_i32 s67, s67, 1
	s_mov_b32 s69, s4
	s_mul_i32 s4, s67, s24
	s_add_i32 s4, s4, s23
	s_cmpk_lt_i32 s4, 0x100
	s_mov_b32 s68, s22
	s_cselect_b64 s[36:37], -1, 0
	s_bfe_u32 s22, s4, 0x30003
	s_ashr_i32 s4, s4, 6
	s_ashr_i32 s5, s4, 31
	s_mov_b64 s[40:41], s[8:9]
	s_lshl_b64 s[8:9], s[4:5], 20
	s_mov_b64 s[38:39], s[12:13]
	s_add_u32 s12, s10, s8
	s_addc_u32 s13, s11, s9
	s_and_b64 s[8:9], s[36:37], exec
	s_cselect_b32 s5, s13, s39
	s_cselect_b32 s70, s12, s38
	s_lshl_b32 s8, s22, 20
	s_add_u32 s8, s1, s8
	s_addc_u32 s9, s7, 0
	s_and_b64 s[42:43], s[36:37], exec
	s_cselect_b32 s71, s9, s41
	s_cselect_b32 s72, s8, s40
	s_mov_b64 s[42:43], -1
	s_mov_b64 s[44:45], 0
	s_mov_b32 s46, 0
	s_add_u32 s47, s38, s46
	s_addc_u32 s52, s39, 0
	s_add_u32 s50, s47, 0x100
	s_addc_u32 s51, s52, 0
	s_and_b64 s[48:49], s[44:45], exec
	s_cselect_b32 s49, s5, s51
	s_cselect_b32 s48, s70, s50
	s_add_u32 s46, s40, s46
	s_addc_u32 s50, s41, 0
	s_add_u32 s46, s46, 0x100
	s_addc_u32 s50, s50, 0
	s_add_i32 s83, 0, 0x10000
	s_and_b64 s[44:45], s[44:45], exec
	s_cselect_b32 s51, s71, s50
	s_cselect_b32 s50, s72, s46
	s_add_i32 s45, 0, 0x14000
	s_add_u32 s54, s47, 0x80080
	s_addc_u32 s55, s52, 0
	s_add_i32 s82, s83, s21
	s_add_i32 m0, s33, 0xc000
	s_add_i32 s85, s33, 0xe000
	s_add_i32 s77, s82, 0x2000
	v_add_u32_e32 v2, s83, v136
	s_add_u32 s52, s50, 0x80000
	ds_read_b128 v[140:143], v2
	ds_read_b128 v[144:147], v2 offset:1024
	ds_read_b128 v[148:151], v2 offset:2048
	ds_read_b128 v[152:155], v2 offset:3072
	v_add_u32_e32 v2, s45, v136
	s_addc_u32 s53, s51, 0
	s_add_i32 s81, s45, s21
	ds_read_b128 v[156:159], v2
	ds_read_b128 v[160:163], v2 offset:1024
	ds_read_b128 v[164:167], v2 offset:2048
	ds_read_b128 v[178:181], v2 offset:3072
	s_add_i32 s80, s81, 0x2000
	s_add_i32 s76, 0, 0x18000
	s_add_i32 s75, 0, 0x1c000
	s_add_u32 s46, s48, 0x80000
	s_addc_u32 s47, s49, 0
	s_add_i32 s74, s76, s21
	s_add_i32 s73, s74, 0x2000
	s_add_u32 s44, s50, 0x80080
	s_addc_u32 s45, s51, 0
	s_add_i32 s84, s75, s21
	s_add_i32 s83, s84, 0x2000
	v_lshl_add_u64 v[168:169], s[54:55], 0, v[134:135]
	ds_read_b128 v[182:185], v138
	ds_read_b128 v[186:189], v138 offset:1024
	ds_read_b128 v[190:193], v138 offset:2048
	ds_read_b128 v[194:197], v138 offset:3072
	ds_read_b128 v[208:211], v138 offset:4096
	ds_read_b128 v[212:215], v138 offset:5120
	ds_read_b128 v[216:219], v138 offset:6144
	ds_read_b128 v[220:223], v138 offset:7168
	global_load_lds_dwordx4 v[168:169], off
	v_lshl_add_u64 v[168:169], s[54:55], 0, v[132:133]
	s_mov_b32 m0, s85
	s_nop 0
	global_load_lds_dwordx4 v[168:169], off
	s_waitcnt vmcnt(8)
	s_waitcnt lgkmcnt(0)
	s_barrier
	s_setprio 1
	s_waitcnt lgkmcnt(0)
	v_mfma_f32_16x16x32_bf16 v[128:131], v[140:143], v[182:185], 0
	v_mfma_f32_16x16x32_bf16 v[128:131], v[144:147], v[186:189], v[128:131]
	v_mfma_f32_16x16x32_bf16 v[124:127], v[152:155], v[186:189], 0
	v_mfma_f32_16x16x32_bf16 v[124:127], v[148:151], v[182:185], v[124:127]
	v_mfma_f32_16x16x32_bf16 v[116:119], v[148:151], v[190:193], 0
	v_mfma_f32_16x16x32_bf16 v[116:119], v[152:155], v[194:197], v[116:119]
	v_mfma_f32_16x16x32_bf16 v[120:123], v[144:147], v[194:197], 0
	v_mfma_f32_16x16x32_bf16 v[120:123], v[140:143], v[190:193], v[120:123]
	v_mfma_f32_16x16x32_bf16 v[108:111], v[140:143], v[208:211], 0
	v_mfma_f32_16x16x32_bf16 v[108:111], v[144:147], v[212:215], v[108:111]
	v_mfma_f32_16x16x32_bf16 v[100:103], v[152:155], v[212:215], 0
	v_mfma_f32_16x16x32_bf16 v[100:103], v[148:151], v[208:211], v[100:103]
	v_mfma_f32_16x16x32_bf16 v[84:87], v[148:151], v[216:219], 0
	v_mfma_f32_16x16x32_bf16 v[84:87], v[152:155], v[220:223], v[84:87]
	v_mfma_f32_16x16x32_bf16 v[92:95], v[144:147], v[220:223], 0
	v_mfma_f32_16x16x32_bf16 v[92:95], v[140:143], v[216:219], v[92:95]
	s_setprio 0
	s_setprio 1
	v_mfma_f32_16x16x32_bf16 v[112:115], v[156:159], v[182:185], 0
	v_mfma_f32_16x16x32_bf16 v[112:115], v[160:163], v[186:189], v[112:115]
	v_mfma_f32_16x16x32_bf16 v[104:107], v[178:181], v[186:189], 0
	v_mfma_f32_16x16x32_bf16 v[104:107], v[164:167], v[182:185], v[104:107]
	v_mfma_f32_16x16x32_bf16 v[88:91], v[164:167], v[190:193], 0
	v_mfma_f32_16x16x32_bf16 v[88:91], v[178:181], v[194:197], v[88:91]
	v_mfma_f32_16x16x32_bf16 v[96:99], v[160:163], v[194:197], 0
	v_mfma_f32_16x16x32_bf16 v[96:99], v[156:159], v[190:193], v[96:99]
	v_mfma_f32_16x16x32_bf16 v[80:83], v[156:159], v[208:211], 0
	v_mfma_f32_16x16x32_bf16 v[80:83], v[160:163], v[212:215], v[80:83]
	v_mfma_f32_16x16x32_bf16 v[76:79], v[178:181], v[212:215], 0
	v_mfma_f32_16x16x32_bf16 v[76:79], v[164:167], v[208:211], v[76:79]
	v_mfma_f32_16x16x32_bf16 v[68:71], v[164:167], v[216:219], 0
	v_mfma_f32_16x16x32_bf16 v[68:71], v[178:181], v[220:223], v[68:71]
	v_mfma_f32_16x16x32_bf16 v[72:75], v[160:163], v[220:223], 0
	v_mfma_f32_16x16x32_bf16 v[72:75], v[156:159], v[216:219], v[72:75]
	s_setprio 0
	s_barrier
	s_mov_b32 m0, s82
	v_lshl_add_u64 v[168:169], s[50:51], 0, v[134:135]
	ds_read_b128 v[182:185], v138 offset:16384
	ds_read_b128 v[186:189], v138 offset:17408
	ds_read_b128 v[190:193], v138 offset:18432
	ds_read_b128 v[194:197], v138 offset:19456
	ds_read_b128 v[208:211], v138 offset:20480
	ds_read_b128 v[212:215], v138 offset:21504
	ds_read_b128 v[216:219], v138 offset:22528
	ds_read_b128 v[220:223], v138 offset:23552
	global_load_lds_dwordx4 v[168:169], off
	v_lshl_add_u64 v[224:225], s[50:51], 0, v[132:133]
	s_mov_b32 m0, s77
	v_lshl_add_u64 v[226:227], s[52:53], 0, v[134:135]
	global_load_lds_dwordx4 v[224:225], off
	s_mov_b32 m0, s81
	v_lshl_add_u64 v[228:229], s[48:49], 0, v[132:133]
	global_load_lds_dwordx4 v[226:227], off
	v_lshl_add_u64 v[226:227], s[52:53], 0, v[132:133]
	s_mov_b32 m0, s80
	s_nop 0
	global_load_lds_dwordx4 v[226:227], off
	v_lshl_add_u64 v[226:227], s[48:49], 0, v[134:135]
	s_mov_b32 m0, s33
	s_nop 0
	global_load_lds_dwordx4 v[226:227], off
	s_mov_b32 m0, s61
	s_nop 0
	global_load_lds_dwordx4 v[228:229], off
	s_waitcnt vmcnt(8)
	s_waitcnt lgkmcnt(0)
	s_barrier
	s_setprio 1
	s_waitcnt lgkmcnt(0)
	v_mfma_f32_16x16x32_bf16 v[64:67], v[140:143], v[182:185], 0
	v_mfma_f32_16x16x32_bf16 v[64:67], v[144:147], v[186:189], v[64:67]
	v_mfma_f32_16x16x32_bf16 v[60:63], v[152:155], v[186:189], 0
	v_mfma_f32_16x16x32_bf16 v[60:63], v[148:151], v[182:185], v[60:63]
	v_mfma_f32_16x16x32_bf16 v[52:55], v[148:151], v[190:193], 0
	v_mfma_f32_16x16x32_bf16 v[52:55], v[152:155], v[194:197], v[52:55]
	v_mfma_f32_16x16x32_bf16 v[56:59], v[144:147], v[194:197], 0
	v_mfma_f32_16x16x32_bf16 v[56:59], v[140:143], v[190:193], v[56:59]
	v_mfma_f32_16x16x32_bf16 v[40:43], v[140:143], v[208:211], 0
	v_mfma_f32_16x16x32_bf16 v[40:43], v[144:147], v[212:215], v[40:43]
	v_mfma_f32_16x16x32_bf16 v[36:39], v[152:155], v[212:215], 0
	v_mfma_f32_16x16x32_bf16 v[36:39], v[148:151], v[208:211], v[36:39]
	v_mfma_f32_16x16x32_bf16 v[20:23], v[148:151], v[216:219], 0
	v_mfma_f32_16x16x32_bf16 v[20:23], v[152:155], v[220:223], v[20:23]
	v_mfma_f32_16x16x32_bf16 v[24:27], v[144:147], v[220:223], 0
	v_mfma_f32_16x16x32_bf16 v[24:27], v[140:143], v[216:219], v[24:27]
	s_setprio 0
	s_setprio 1
	v_mfma_f32_16x16x32_bf16 v[48:51], v[156:159], v[182:185], 0
	v_mfma_f32_16x16x32_bf16 v[48:51], v[160:163], v[186:189], v[48:51]
	v_mfma_f32_16x16x32_bf16 v[44:47], v[178:181], v[186:189], 0
	v_mfma_f32_16x16x32_bf16 v[44:47], v[164:167], v[182:185], v[44:47]
	v_mfma_f32_16x16x32_bf16 v[28:31], v[164:167], v[190:193], 0
	v_mfma_f32_16x16x32_bf16 v[28:31], v[178:181], v[194:197], v[28:31]
	v_mfma_f32_16x16x32_bf16 v[32:35], v[160:163], v[194:197], 0
	v_mfma_f32_16x16x32_bf16 v[32:35], v[156:159], v[190:193], v[32:35]
	v_mfma_f32_16x16x32_bf16 v[16:19], v[156:159], v[208:211], 0
	v_mfma_f32_16x16x32_bf16 v[16:19], v[160:163], v[212:215], v[16:19]
	v_mfma_f32_16x16x32_bf16 v[12:15], v[178:181], v[212:215], 0
	v_mfma_f32_16x16x32_bf16 v[12:15], v[164:167], v[208:211], v[12:15]
	v_mfma_f32_16x16x32_bf16 v[4:7], v[164:167], v[216:219], 0
	v_mfma_f32_16x16x32_bf16 v[4:7], v[178:181], v[220:223], v[4:7]
	v_mfma_f32_16x16x32_bf16 v[8:11], v[160:163], v[220:223], 0
	v_mfma_f32_16x16x32_bf16 v[8:11], v[156:159], v[216:219], v[8:11]
	s_setprio 0
	s_barrier
	v_add_u32_e32 v2, s76, v136
	ds_read_b128 v[140:143], v2
	ds_read_b128 v[144:147], v2 offset:1024
	ds_read_b128 v[148:151], v2 offset:2048
	ds_read_b128 v[152:155], v2 offset:3072
	v_add_u32_e32 v2, s75, v136
	ds_read_b128 v[156:159], v2
	ds_read_b128 v[160:163], v2 offset:1024
	ds_read_b128 v[164:167], v2 offset:2048
	ds_read_b128 v[178:181], v2 offset:3072
	s_mov_b32 m0, s62
	v_lshl_add_u64 v[230:231], s[46:47], 0, v[134:135]
	ds_read_b128 v[182:185], v138 offset:32768
	ds_read_b128 v[186:189], v138 offset:33792
	ds_read_b128 v[190:193], v138 offset:34816
	ds_read_b128 v[194:197], v138 offset:35840
	ds_read_b128 v[208:211], v138 offset:36864
	ds_read_b128 v[212:215], v138 offset:37888
	ds_read_b128 v[216:219], v138 offset:38912
	ds_read_b128 v[220:223], v138 offset:39936
	global_load_lds_dwordx4 v[230:231], off
	v_lshl_add_u64 v[230:231], s[46:47], 0, v[132:133]
	s_mov_b32 m0, s63
	s_nop 0
	global_load_lds_dwordx4 v[230:231], off
	s_waitcnt vmcnt(8)
	s_waitcnt lgkmcnt(0)
	s_barrier
	s_setprio 1
	s_waitcnt lgkmcnt(0)
	v_mfma_f32_16x16x32_bf16 v[128:131], v[140:143], v[182:185], v[128:131]
	v_mfma_f32_16x16x32_bf16 v[128:131], v[144:147], v[186:189], v[128:131]
	v_mfma_f32_16x16x32_bf16 v[124:127], v[152:155], v[186:189], v[124:127]
	v_mfma_f32_16x16x32_bf16 v[124:127], v[148:151], v[182:185], v[124:127]
	v_mfma_f32_16x16x32_bf16 v[116:119], v[148:151], v[190:193], v[116:119]
	v_mfma_f32_16x16x32_bf16 v[116:119], v[152:155], v[194:197], v[116:119]
	v_mfma_f32_16x16x32_bf16 v[120:123], v[144:147], v[194:197], v[120:123]
	v_mfma_f32_16x16x32_bf16 v[120:123], v[140:143], v[190:193], v[120:123]
	v_mfma_f32_16x16x32_bf16 v[108:111], v[140:143], v[208:211], v[108:111]
	v_mfma_f32_16x16x32_bf16 v[108:111], v[144:147], v[212:215], v[108:111]
	v_mfma_f32_16x16x32_bf16 v[100:103], v[152:155], v[212:215], v[100:103]
	v_mfma_f32_16x16x32_bf16 v[100:103], v[148:151], v[208:211], v[100:103]
	v_mfma_f32_16x16x32_bf16 v[84:87], v[148:151], v[216:219], v[84:87]
	v_mfma_f32_16x16x32_bf16 v[84:87], v[152:155], v[220:223], v[84:87]
	v_mfma_f32_16x16x32_bf16 v[92:95], v[144:147], v[220:223], v[92:95]
	v_mfma_f32_16x16x32_bf16 v[92:95], v[140:143], v[216:219], v[92:95]
	s_setprio 0
	s_setprio 1
	v_mfma_f32_16x16x32_bf16 v[112:115], v[156:159], v[182:185], v[112:115]
	v_mfma_f32_16x16x32_bf16 v[112:115], v[160:163], v[186:189], v[112:115]
	v_mfma_f32_16x16x32_bf16 v[104:107], v[178:181], v[186:189], v[104:107]
	v_mfma_f32_16x16x32_bf16 v[104:107], v[164:167], v[182:185], v[104:107]
	v_mfma_f32_16x16x32_bf16 v[88:91], v[164:167], v[190:193], v[88:91]
	v_mfma_f32_16x16x32_bf16 v[88:91], v[178:181], v[194:197], v[88:91]
	v_mfma_f32_16x16x32_bf16 v[96:99], v[160:163], v[194:197], v[96:99]
	v_mfma_f32_16x16x32_bf16 v[96:99], v[156:159], v[190:193], v[96:99]
	v_mfma_f32_16x16x32_bf16 v[80:83], v[156:159], v[208:211], v[80:83]
	v_mfma_f32_16x16x32_bf16 v[80:83], v[160:163], v[212:215], v[80:83]
	v_mfma_f32_16x16x32_bf16 v[76:79], v[178:181], v[212:215], v[76:79]
	v_mfma_f32_16x16x32_bf16 v[76:79], v[164:167], v[208:211], v[76:79]
	v_mfma_f32_16x16x32_bf16 v[68:71], v[164:167], v[216:219], v[68:71]
	v_mfma_f32_16x16x32_bf16 v[68:71], v[178:181], v[220:223], v[68:71]
	v_mfma_f32_16x16x32_bf16 v[72:75], v[160:163], v[220:223], v[72:75]
	v_mfma_f32_16x16x32_bf16 v[72:75], v[156:159], v[216:219], v[72:75]
	s_setprio 0
	s_barrier
	s_mov_b32 m0, s74
	v_lshl_add_u64 v[168:169], v[168:169], 0, s[18:19]
	ds_read_b128 v[182:185], v138 offset:49152
	ds_read_b128 v[186:189], v138 offset:50176
	ds_read_b128 v[190:193], v138 offset:51200
	ds_read_b128 v[194:197], v138 offset:52224
	ds_read_b128 v[208:211], v138 offset:53248
	ds_read_b128 v[212:215], v138 offset:54272
	ds_read_b128 v[216:219], v138 offset:55296
	ds_read_b128 v[220:223], v138 offset:56320
	global_load_lds_dwordx4 v[168:169], off
	v_lshl_add_u64 v[168:169], v[224:225], 0, s[18:19]
	s_mov_b32 m0, s73
	s_nop 0
	global_load_lds_dwordx4 v[168:169], off
	v_lshl_add_u64 v[168:169], s[44:45], 0, v[134:135]
	s_mov_b32 m0, s84
	s_nop 0
	global_load_lds_dwordx4 v[168:169], off
	v_lshl_add_u64 v[168:169], s[44:45], 0, v[132:133]
	s_mov_b32 m0, s83
	s_nop 0
	global_load_lds_dwordx4 v[168:169], off
	v_lshl_add_u64 v[168:169], v[226:227], 0, s[18:19]
	s_mov_b32 m0, s65
	s_nop 0
	global_load_lds_dwordx4 v[168:169], off
	v_lshl_add_u64 v[168:169], v[228:229], 0, s[18:19]
	s_mov_b32 m0, s66
	s_nop 0
	global_load_lds_dwordx4 v[168:169], off
	s_waitcnt vmcnt(8)
	s_waitcnt lgkmcnt(0)
	s_barrier
	s_setprio 1
	s_waitcnt lgkmcnt(0)
	v_mfma_f32_16x16x32_bf16 v[64:67], v[140:143], v[182:185], v[64:67]
	v_mfma_f32_16x16x32_bf16 v[64:67], v[144:147], v[186:189], v[64:67]
	v_mfma_f32_16x16x32_bf16 v[60:63], v[152:155], v[186:189], v[60:63]
	v_mfma_f32_16x16x32_bf16 v[60:63], v[148:151], v[182:185], v[60:63]
	v_mfma_f32_16x16x32_bf16 v[52:55], v[148:151], v[190:193], v[52:55]
	v_mfma_f32_16x16x32_bf16 v[52:55], v[152:155], v[194:197], v[52:55]
	v_mfma_f32_16x16x32_bf16 v[56:59], v[144:147], v[194:197], v[56:59]
	v_mfma_f32_16x16x32_bf16 v[56:59], v[140:143], v[190:193], v[56:59]
	v_mfma_f32_16x16x32_bf16 v[40:43], v[140:143], v[208:211], v[40:43]
	v_mfma_f32_16x16x32_bf16 v[40:43], v[144:147], v[212:215], v[40:43]
	v_mfma_f32_16x16x32_bf16 v[36:39], v[152:155], v[212:215], v[36:39]
	v_mfma_f32_16x16x32_bf16 v[36:39], v[148:151], v[208:211], v[36:39]
	v_mfma_f32_16x16x32_bf16 v[20:23], v[148:151], v[216:219], v[20:23]
	v_mfma_f32_16x16x32_bf16 v[20:23], v[152:155], v[220:223], v[20:23]
	v_mfma_f32_16x16x32_bf16 v[24:27], v[144:147], v[220:223], v[24:27]
	v_mfma_f32_16x16x32_bf16 v[24:27], v[140:143], v[216:219], v[24:27]
	s_setprio 0
	s_setprio 1
	v_mfma_f32_16x16x32_bf16 v[48:51], v[156:159], v[182:185], v[48:51]
	v_mfma_f32_16x16x32_bf16 v[48:51], v[160:163], v[186:189], v[48:51]
	v_mfma_f32_16x16x32_bf16 v[44:47], v[178:181], v[186:189], v[44:47]
	v_mfma_f32_16x16x32_bf16 v[44:47], v[164:167], v[182:185], v[44:47]
	v_mfma_f32_16x16x32_bf16 v[28:31], v[164:167], v[190:193], v[28:31]
	v_mfma_f32_16x16x32_bf16 v[28:31], v[178:181], v[194:197], v[28:31]
	v_mfma_f32_16x16x32_bf16 v[32:35], v[160:163], v[194:197], v[32:35]
	v_mfma_f32_16x16x32_bf16 v[32:35], v[156:159], v[190:193], v[32:35]
	v_mfma_f32_16x16x32_bf16 v[16:19], v[156:159], v[208:211], v[16:19]
	v_mfma_f32_16x16x32_bf16 v[16:19], v[160:163], v[212:215], v[16:19]
	v_mfma_f32_16x16x32_bf16 v[12:15], v[178:181], v[212:215], v[12:15]
	v_mfma_f32_16x16x32_bf16 v[12:15], v[164:167], v[208:211], v[12:15]
	v_mfma_f32_16x16x32_bf16 v[4:7], v[164:167], v[216:219], v[4:7]
	v_mfma_f32_16x16x32_bf16 v[4:7], v[178:181], v[220:223], v[4:7]
	v_mfma_f32_16x16x32_bf16 v[8:11], v[160:163], v[220:223], v[8:11]
	v_mfma_f32_16x16x32_bf16 v[8:11], v[156:159], v[216:219], v[8:11]
	s_setprio 0
	s_barrier
	s_movk_i32 s46, 0x100
	s_andn2_b64 vcc, exec, s[42:43]
	s_mov_b64 s[44:45], -1
	s_mov_b64 s[42:43], 0

.LBB0_747:
	s_ashr_i32 s27, s26, 31
	s_lshl_b64 s[34:35], s[26:27], 21
	s_add_u32 s34, s59, s34
	s_addc_u32 s35, s60, s35
	s_and_b64 s[36:37], s[38:39], exec
	s_cselect_b32 s27, s35, s41
	s_cselect_b32 s51, s34, s40
	s_ashr_i32 s13, s12, 31
	s_lshl_b64 s[36:37], s[12:13], 21
	s_add_u32 s36, s1, s36
	s_addc_u32 s37, s7, s37
	s_and_b64 s[44:45], s[38:39], exec
	s_cselect_b32 s13, s37, s43
	s_cselect_b32 s52, s36, s42
	s_add_u32 s40, s40, 0x100080
	s_addc_u32 s41, s41, 0
	s_add_u32 s53, s42, 0x100
	s_addc_u32 s54, s43, 0
	s_mov_b32 s55, -2
	s_add_u32 s42, s40, 0xfff00080
	s_addc_u32 s43, s41, -1
	s_add_i32 s61, 0, 0x10000
	s_cmp_eq_u32 s55, 60
	s_cselect_b32 s45, s27, s43
	s_cselect_b32 s44, s51, s42
	v_add_u32_e32 v142, s61, v144
	s_cselect_b32 s43, s13, s54
	s_cselect_b32 s42, s52, s53
	s_add_i32 s65, 0, 0x14000
	ds_read_b128 v[148:151], v142
	ds_read_b128 v[152:155], v142 offset:1024
	ds_read_b128 v[156:159], v142 offset:2048
	ds_read_b128 v[160:163], v142 offset:3072
	v_add_u32_e32 v142, s65, v144
	ds_read_b128 v[164:167], v142
	ds_read_b128 v[178:181], v142 offset:1024
	ds_read_b128 v[182:185], v142 offset:2048
	ds_read_b128 v[186:189], v142 offset:3072
	v_lshl_add_u64 v[142:143], s[40:41], 0, v[138:139]
	s_add_i32 m0, s21, 0xc000
	ds_read_b128 v[190:193], v146
	ds_read_b128 v[194:197], v146 offset:1024
	ds_read_b128 v[208:211], v146 offset:2048
	ds_read_b128 v[212:215], v146 offset:3072
	ds_read_b128 v[216:219], v146 offset:4096
	ds_read_b128 v[220:223], v146 offset:5120
	ds_read_b128 v[224:227], v146 offset:6144
	ds_read_b128 v[228:231], v146 offset:7168
	global_load_lds_dwordx4 v[142:143], off
	v_lshl_add_u64 v[142:143], s[40:41], 0, v[140:141]
	s_add_i32 m0, s21, 0xe000
	s_nop 0
	global_load_lds_dwordx4 v[142:143], off
	s_waitcnt vmcnt(8)
	s_waitcnt lgkmcnt(0)
	s_barrier
	s_setprio 1
	s_waitcnt lgkmcnt(0)
	v_mfma_f32_16x16x32_bf16 v[128:131], v[148:151], v[190:193], 0
	v_mfma_f32_16x16x32_bf16 v[128:131], v[152:155], v[194:197], v[128:131]
	v_mfma_f32_16x16x32_bf16 v[124:127], v[160:163], v[194:197], 0
	v_mfma_f32_16x16x32_bf16 v[124:127], v[156:159], v[190:193], v[124:127]
	v_mfma_f32_16x16x32_bf16 v[112:115], v[156:159], v[208:211], 0
	v_mfma_f32_16x16x32_bf16 v[112:115], v[160:163], v[212:215], v[112:115]
	v_mfma_f32_16x16x32_bf16 v[120:123], v[152:155], v[212:215], 0
	v_mfma_f32_16x16x32_bf16 v[120:123], v[148:151], v[208:211], v[120:123]
	v_mfma_f32_16x16x32_bf16 v[104:107], v[148:151], v[216:219], 0
	v_mfma_f32_16x16x32_bf16 v[104:107], v[152:155], v[220:223], v[104:107]
	v_mfma_f32_16x16x32_bf16 v[96:99], v[160:163], v[220:223], 0
	v_mfma_f32_16x16x32_bf16 v[96:99], v[156:159], v[216:219], v[96:99]
	v_mfma_f32_16x16x32_bf16 v[80:83], v[156:159], v[224:227], 0
	v_mfma_f32_16x16x32_bf16 v[80:83], v[160:163], v[228:231], v[80:83]
	v_mfma_f32_16x16x32_bf16 v[88:91], v[152:155], v[228:231], 0
	v_mfma_f32_16x16x32_bf16 v[88:91], v[148:151], v[224:227], v[88:91]
	s_setprio 0
	s_setprio 1
	v_mfma_f32_16x16x32_bf16 v[116:119], v[164:167], v[190:193], 0
	v_mfma_f32_16x16x32_bf16 v[116:119], v[178:181], v[194:197], v[116:119]
	v_mfma_f32_16x16x32_bf16 v[108:111], v[186:189], v[194:197], 0
	v_mfma_f32_16x16x32_bf16 v[108:111], v[182:185], v[190:193], v[108:111]
	v_mfma_f32_16x16x32_bf16 v[92:95], v[182:185], v[208:211], 0
	v_mfma_f32_16x16x32_bf16 v[92:95], v[186:189], v[212:215], v[92:95]
	v_mfma_f32_16x16x32_bf16 v[100:103], v[178:181], v[212:215], 0
	v_mfma_f32_16x16x32_bf16 v[100:103], v[164:167], v[208:211], v[100:103]
	v_mfma_f32_16x16x32_bf16 v[84:87], v[164:167], v[216:219], 0
	v_mfma_f32_16x16x32_bf16 v[84:87], v[178:181], v[220:223], v[84:87]
	v_mfma_f32_16x16x32_bf16 v[76:79], v[186:189], v[220:223], 0
	v_mfma_f32_16x16x32_bf16 v[76:79], v[182:185], v[216:219], v[76:79]
	v_mfma_f32_16x16x32_bf16 v[68:71], v[182:185], v[224:227], 0
	v_mfma_f32_16x16x32_bf16 v[68:71], v[186:189], v[228:231], v[68:71]
	v_mfma_f32_16x16x32_bf16 v[72:75], v[178:181], v[228:231], 0
	v_mfma_f32_16x16x32_bf16 v[72:75], v[164:167], v[224:227], v[72:75]
	s_setprio 0
	s_barrier
	s_add_i32 s61, s61, s11
	v_lshl_add_u64 v[142:143], s[42:43], 0, v[2:3]
	s_mov_b32 m0, s61
	ds_read_b128 v[190:193], v146 offset:16384
	ds_read_b128 v[194:197], v146 offset:17408
	ds_read_b128 v[208:211], v146 offset:18432
	ds_read_b128 v[212:215], v146 offset:19456
	ds_read_b128 v[216:219], v146 offset:20480
	ds_read_b128 v[220:223], v146 offset:21504
	ds_read_b128 v[224:227], v146 offset:22528
	ds_read_b128 v[228:231], v146 offset:23552
	global_load_lds_dwordx4 v[142:143], off
	s_add_i32 m0, s61, 0x2000
	s_add_u32 s62, s42, 0x100000
	v_lshl_add_u64 v[168:169], s[42:43], 0, v[136:137]
	s_addc_u32 s63, s43, 0
	s_add_i32 s61, s65, s11
	global_load_lds_dwordx4 v[168:169], off
	v_lshl_add_u64 v[232:233], s[62:63], 0, v[2:3]
	s_mov_b32 m0, s61
	v_lshl_add_u64 v[234:235], s[44:45], 0, v[134:135]
	global_load_lds_dwordx4 v[232:233], off
	v_lshl_add_u64 v[232:233], s[62:63], 0, v[136:137]
	s_add_i32 m0, s61, 0x2000
	s_nop 0
	global_load_lds_dwordx4 v[232:233], off
	v_lshl_add_u64 v[232:233], s[44:45], 0, v[132:133]
	s_mov_b32 m0, s21
	s_nop 0
	global_load_lds_dwordx4 v[232:233], off
	s_mov_b32 m0, s22
	s_nop 0
	global_load_lds_dwordx4 v[234:235], off
	s_waitcnt vmcnt(8)
	s_waitcnt lgkmcnt(0)
	s_barrier
	s_setprio 1
	s_waitcnt lgkmcnt(0)
	v_mfma_f32_16x16x32_bf16 v[64:67], v[148:151], v[190:193], 0
	v_mfma_f32_16x16x32_bf16 v[64:67], v[152:155], v[194:197], v[64:67]
	v_mfma_f32_16x16x32_bf16 v[60:63], v[160:163], v[194:197], 0
	v_mfma_f32_16x16x32_bf16 v[60:63], v[156:159], v[190:193], v[60:63]
	v_mfma_f32_16x16x32_bf16 v[48:51], v[156:159], v[208:211], 0
	v_mfma_f32_16x16x32_bf16 v[48:51], v[160:163], v[212:215], v[48:51]
	v_mfma_f32_16x16x32_bf16 v[56:59], v[152:155], v[212:215], 0
	v_mfma_f32_16x16x32_bf16 v[56:59], v[148:151], v[208:211], v[56:59]
	v_mfma_f32_16x16x32_bf16 v[40:43], v[148:151], v[216:219], 0
	v_mfma_f32_16x16x32_bf16 v[40:43], v[152:155], v[220:223], v[40:43]
	v_mfma_f32_16x16x32_bf16 v[32:35], v[160:163], v[220:223], 0
	v_mfma_f32_16x16x32_bf16 v[32:35], v[156:159], v[216:219], v[32:35]
	v_mfma_f32_16x16x32_bf16 v[16:19], v[156:159], v[224:227], 0
	v_mfma_f32_16x16x32_bf16 v[16:19], v[160:163], v[228:231], v[16:19]
	v_mfma_f32_16x16x32_bf16 v[24:27], v[152:155], v[228:231], 0
	v_mfma_f32_16x16x32_bf16 v[24:27], v[148:151], v[224:227], v[24:27]
	s_setprio 0
	s_setprio 1
	v_mfma_f32_16x16x32_bf16 v[52:55], v[164:167], v[190:193], 0
	v_mfma_f32_16x16x32_bf16 v[52:55], v[178:181], v[194:197], v[52:55]
	v_mfma_f32_16x16x32_bf16 v[44:47], v[186:189], v[194:197], 0
	v_mfma_f32_16x16x32_bf16 v[44:47], v[182:185], v[190:193], v[44:47]
	v_mfma_f32_16x16x32_bf16 v[28:31], v[182:185], v[208:211], 0
	v_mfma_f32_16x16x32_bf16 v[28:31], v[186:189], v[212:215], v[28:31]
	v_mfma_f32_16x16x32_bf16 v[36:39], v[178:181], v[212:215], 0
	v_mfma_f32_16x16x32_bf16 v[36:39], v[164:167], v[208:211], v[36:39]
	v_mfma_f32_16x16x32_bf16 v[20:23], v[164:167], v[216:219], 0
	v_mfma_f32_16x16x32_bf16 v[20:23], v[178:181], v[220:223], v[20:23]
	v_mfma_f32_16x16x32_bf16 v[12:15], v[186:189], v[220:223], 0
	v_mfma_f32_16x16x32_bf16 v[12:15], v[182:185], v[216:219], v[12:15]
	v_mfma_f32_16x16x32_bf16 v[4:7], v[182:185], v[224:227], 0
	v_mfma_f32_16x16x32_bf16 v[4:7], v[186:189], v[228:231], v[4:7]
	v_mfma_f32_16x16x32_bf16 v[8:11], v[178:181], v[228:231], 0
	v_mfma_f32_16x16x32_bf16 v[8:11], v[164:167], v[224:227], v[8:11]
	s_setprio 0
	s_barrier
	s_add_i32 s61, 0, 0x18000
	v_add_u32_e32 v147, s61, v144
	s_add_i32 s62, 0, 0x1c000
	ds_read_b128 v[148:151], v147
	ds_read_b128 v[152:155], v147 offset:1024
	ds_read_b128 v[156:159], v147 offset:2048
	ds_read_b128 v[160:163], v147 offset:3072
	v_add_u32_e32 v147, s62, v144
	ds_read_b128 v[164:167], v147
	ds_read_b128 v[178:181], v147 offset:1024
	ds_read_b128 v[182:185], v147 offset:2048
	ds_read_b128 v[186:189], v147 offset:3072
	s_add_u32 s44, s44, 0x100000
	s_addc_u32 s45, s45, 0
	s_mov_b32 m0, s33
	v_lshl_add_u64 v[236:237], s[44:45], 0, v[132:133]
	ds_read_b128 v[190:193], v146 offset:32768
	ds_read_b128 v[194:197], v146 offset:33792
	ds_read_b128 v[208:211], v146 offset:34816
	ds_read_b128 v[212:215], v146 offset:35840
	ds_read_b128 v[216:219], v146 offset:36864
	ds_read_b128 v[220:223], v146 offset:37888
	ds_read_b128 v[224:227], v146 offset:38912
	ds_read_b128 v[228:231], v146 offset:39936
	global_load_lds_dwordx4 v[236:237], off
	v_lshl_add_u64 v[236:237], s[44:45], 0, v[134:135]
	s_mov_b32 m0, s46
	s_nop 0
	global_load_lds_dwordx4 v[236:237], off
	s_waitcnt vmcnt(8)
	s_waitcnt lgkmcnt(0)
	s_barrier
	s_setprio 1
	s_waitcnt lgkmcnt(0)
	v_mfma_f32_16x16x32_bf16 v[128:131], v[148:151], v[190:193], v[128:131]
	v_mfma_f32_16x16x32_bf16 v[128:131], v[152:155], v[194:197], v[128:131]
	v_mfma_f32_16x16x32_bf16 v[124:127], v[160:163], v[194:197], v[124:127]
	v_mfma_f32_16x16x32_bf16 v[124:127], v[156:159], v[190:193], v[124:127]
	v_mfma_f32_16x16x32_bf16 v[112:115], v[156:159], v[208:211], v[112:115]
	v_mfma_f32_16x16x32_bf16 v[112:115], v[160:163], v[212:215], v[112:115]
	v_mfma_f32_16x16x32_bf16 v[120:123], v[152:155], v[212:215], v[120:123]
	v_mfma_f32_16x16x32_bf16 v[120:123], v[148:151], v[208:211], v[120:123]
	v_mfma_f32_16x16x32_bf16 v[104:107], v[148:151], v[216:219], v[104:107]
	v_mfma_f32_16x16x32_bf16 v[104:107], v[152:155], v[220:223], v[104:107]
	v_mfma_f32_16x16x32_bf16 v[96:99], v[160:163], v[220:223], v[96:99]
	v_mfma_f32_16x16x32_bf16 v[96:99], v[156:159], v[216:219], v[96:99]
	v_mfma_f32_16x16x32_bf16 v[80:83], v[156:159], v[224:227], v[80:83]
	v_mfma_f32_16x16x32_bf16 v[80:83], v[160:163], v[228:231], v[80:83]
	v_mfma_f32_16x16x32_bf16 v[88:91], v[152:155], v[228:231], v[88:91]
	v_mfma_f32_16x16x32_bf16 v[88:91], v[148:151], v[224:227], v[88:91]
	s_setprio 0
	s_setprio 1
	v_mfma_f32_16x16x32_bf16 v[116:119], v[164:167], v[190:193], v[116:119]
	v_mfma_f32_16x16x32_bf16 v[116:119], v[178:181], v[194:197], v[116:119]
	v_mfma_f32_16x16x32_bf16 v[108:111], v[186:189], v[194:197], v[108:111]
	v_mfma_f32_16x16x32_bf16 v[108:111], v[182:185], v[190:193], v[108:111]
	v_mfma_f32_16x16x32_bf16 v[92:95], v[182:185], v[208:211], v[92:95]
	v_mfma_f32_16x16x32_bf16 v[92:95], v[186:189], v[212:215], v[92:95]
	v_mfma_f32_16x16x32_bf16 v[100:103], v[178:181], v[212:215], v[100:103]
	v_mfma_f32_16x16x32_bf16 v[100:103], v[164:167], v[208:211], v[100:103]
	v_mfma_f32_16x16x32_bf16 v[84:87], v[164:167], v[216:219], v[84:87]
	v_mfma_f32_16x16x32_bf16 v[84:87], v[178:181], v[220:223], v[84:87]
	v_mfma_f32_16x16x32_bf16 v[76:79], v[186:189], v[220:223], v[76:79]
	v_mfma_f32_16x16x32_bf16 v[76:79], v[182:185], v[216:219], v[76:79]
	v_mfma_f32_16x16x32_bf16 v[68:71], v[182:185], v[224:227], v[68:71]
	v_mfma_f32_16x16x32_bf16 v[68:71], v[186:189], v[228:231], v[68:71]
	v_mfma_f32_16x16x32_bf16 v[72:75], v[178:181], v[228:231], v[72:75]
	v_mfma_f32_16x16x32_bf16 v[72:75], v[164:167], v[224:227], v[72:75]
	s_setprio 0
	s_barrier
	s_add_i32 s44, s61, s11
	v_lshl_add_u64 v[142:143], v[142:143], 0, s[18:19]
	s_mov_b32 m0, s44
	ds_read_b128 v[190:193], v146 offset:49152
	ds_read_b128 v[194:197], v146 offset:50176
	ds_read_b128 v[208:211], v146 offset:51200
	ds_read_b128 v[212:215], v146 offset:52224
	ds_read_b128 v[216:219], v146 offset:53248
	ds_read_b128 v[220:223], v146 offset:54272
	ds_read_b128 v[224:227], v146 offset:55296
	ds_read_b128 v[228:231], v146 offset:56320
	global_load_lds_dwordx4 v[142:143], off
	s_add_i32 m0, s44, 0x2000
	s_add_u32 s42, s42, 0x100080
	v_lshl_add_u64 v[142:143], v[168:169], 0, s[18:19]
	s_addc_u32 s43, s43, 0
	s_add_i32 s44, s62, s11
	global_load_lds_dwordx4 v[142:143], off
	v_lshl_add_u64 v[142:143], s[42:43], 0, v[2:3]
	s_mov_b32 m0, s44
	s_nop 0
	global_load_lds_dwordx4 v[142:143], off
	v_lshl_add_u64 v[142:143], s[42:43], 0, v[136:137]
	s_add_i32 m0, s44, 0x2000
	s_nop 0
	global_load_lds_dwordx4 v[142:143], off
	v_lshl_add_u64 v[142:143], v[232:233], 0, s[18:19]
	s_mov_b32 m0, s47
	s_nop 0
	global_load_lds_dwordx4 v[142:143], off
	v_lshl_add_u64 v[142:143], v[234:235], 0, s[18:19]
	s_mov_b32 m0, s48
	s_nop 0
	global_load_lds_dwordx4 v[142:143], off
	s_waitcnt vmcnt(8)
	s_waitcnt lgkmcnt(0)
	s_barrier
	s_setprio 1
	s_waitcnt lgkmcnt(0)
	v_mfma_f32_16x16x32_bf16 v[64:67], v[148:151], v[190:193], v[64:67]
	v_mfma_f32_16x16x32_bf16 v[64:67], v[152:155], v[194:197], v[64:67]
	v_mfma_f32_16x16x32_bf16 v[60:63], v[160:163], v[194:197], v[60:63]
	v_mfma_f32_16x16x32_bf16 v[60:63], v[156:159], v[190:193], v[60:63]
	v_mfma_f32_16x16x32_bf16 v[48:51], v[156:159], v[208:211], v[48:51]
	v_mfma_f32_16x16x32_bf16 v[48:51], v[160:163], v[212:215], v[48:51]
	v_mfma_f32_16x16x32_bf16 v[56:59], v[152:155], v[212:215], v[56:59]
	v_mfma_f32_16x16x32_bf16 v[56:59], v[148:151], v[208:211], v[56:59]
	v_mfma_f32_16x16x32_bf16 v[40:43], v[148:151], v[216:219], v[40:43]
	v_mfma_f32_16x16x32_bf16 v[40:43], v[152:155], v[220:223], v[40:43]
	v_mfma_f32_16x16x32_bf16 v[32:35], v[160:163], v[220:223], v[32:35]
	v_mfma_f32_16x16x32_bf16 v[32:35], v[156:159], v[216:219], v[32:35]
	v_mfma_f32_16x16x32_bf16 v[16:19], v[156:159], v[224:227], v[16:19]
	v_mfma_f32_16x16x32_bf16 v[16:19], v[160:163], v[228:231], v[16:19]
	v_mfma_f32_16x16x32_bf16 v[24:27], v[152:155], v[228:231], v[24:27]
	v_mfma_f32_16x16x32_bf16 v[24:27], v[148:151], v[224:227], v[24:27]
	s_setprio 0
	s_setprio 1
	v_mfma_f32_16x16x32_bf16 v[52:55], v[164:167], v[190:193], v[52:55]
	v_mfma_f32_16x16x32_bf16 v[52:55], v[178:181], v[194:197], v[52:55]
	v_mfma_f32_16x16x32_bf16 v[44:47], v[186:189], v[194:197], v[44:47]
	v_mfma_f32_16x16x32_bf16 v[44:47], v[182:185], v[190:193], v[44:47]
	v_mfma_f32_16x16x32_bf16 v[28:31], v[182:185], v[208:211], v[28:31]
	v_mfma_f32_16x16x32_bf16 v[28:31], v[186:189], v[212:215], v[28:31]
	v_mfma_f32_16x16x32_bf16 v[36:39], v[178:181], v[212:215], v[36:39]
	v_mfma_f32_16x16x32_bf16 v[36:39], v[164:167], v[208:211], v[36:39]
	v_mfma_f32_16x16x32_bf16 v[20:23], v[164:167], v[216:219], v[20:23]
	v_mfma_f32_16x16x32_bf16 v[20:23], v[178:181], v[220:223], v[20:23]
	v_mfma_f32_16x16x32_bf16 v[12:15], v[186:189], v[220:223], v[12:15]
	v_mfma_f32_16x16x32_bf16 v[12:15], v[182:185], v[216:219], v[12:15]
	v_mfma_f32_16x16x32_bf16 v[4:7], v[182:185], v[224:227], v[4:7]
	v_mfma_f32_16x16x32_bf16 v[4:7], v[186:189], v[228:231], v[4:7]
	v_mfma_f32_16x16x32_bf16 v[8:11], v[178:181], v[228:231], v[8:11]
	v_mfma_f32_16x16x32_bf16 v[8:11], v[164:167], v[224:227], v[8:11]
	s_setprio 0
	s_barrier
	s_add_i32 s55, s55, 2
	s_add_u32 s40, s40, 0x100
	s_addc_u32 s41, s41, 0
	s_add_u32 s53, s53, 0x100
	s_addc_u32 s54, s54, 0
	s_cmp_gt_u32 s55, 61

.LBB0_761:
	s_add_i32 s46, s46, 1
	s_mov_b32 s48, s2
	s_mul_i32 s2, s46, s24
	s_add_i32 s2, s2, s23
	s_cmpk_lt_i32 s2, 0x100
	s_mov_b32 s47, s22
	s_cselect_b64 s[34:35], -1, 0
	s_bfe_u32 s22, s2, 0x30003
	s_ashr_i32 s2, s2, 6
	s_ashr_i32 s3, s2, 31
	s_mov_b64 s[38:39], s[4:5]
	s_lshl_b64 s[4:5], s[2:3], 21
	s_mov_b64 s[36:37], s[8:9]
	s_add_u32 s8, s10, s4
	s_addc_u32 s9, s11, s5
	s_and_b64 s[4:5], s[34:35], exec
	s_cselect_b32 s3, s9, s37
	s_cselect_b32 s49, s8, s36
	s_lshl_b32 s4, s22, 21
	s_add_u32 s4, s1, s4
	s_addc_u32 s5, s7, 0
	s_and_b64 s[40:41], s[34:35], exec
	s_cselect_b32 s50, s5, s39
	s_cselect_b32 s51, s4, s38
	s_add_u32 s36, s36, 0x100080
	s_addc_u32 s37, s37, 0
	s_add_u32 s52, s38, 0x100
	s_addc_u32 s53, s39, 0
	s_mov_b32 s54, -2
	s_add_u32 s38, s36, 0xfff00080
	s_addc_u32 s39, s37, -1
	s_add_i32 s55, 0, 0x10000
	s_cmp_eq_u32 s54, 4
	s_cselect_b32 s41, s3, s39
	s_cselect_b32 s40, s49, s38
	v_add_u32_e32 v2, s55, v140
	s_cselect_b32 s39, s50, s53
	s_cselect_b32 s38, s51, s52
	s_add_i32 s58, 0, 0x14000
	ds_read_b128 v[144:147], v2
	ds_read_b128 v[148:151], v2 offset:1024
	ds_read_b128 v[152:155], v2 offset:2048
	ds_read_b128 v[156:159], v2 offset:3072
	v_add_u32_e32 v2, s58, v140
	ds_read_b128 v[160:163], v2
	ds_read_b128 v[164:167], v2 offset:1024
	ds_read_b128 v[178:181], v2 offset:2048
	ds_read_b128 v[182:185], v2 offset:3072
	v_lshl_add_u64 v[168:169], s[36:37], 0, v[136:137]
	s_add_i32 m0, s33, 0xc000
	ds_read_b128 v[186:189], v142
	ds_read_b128 v[190:193], v142 offset:1024
	ds_read_b128 v[194:197], v142 offset:2048
	ds_read_b128 v[208:211], v142 offset:3072
	ds_read_b128 v[212:215], v142 offset:4096
	ds_read_b128 v[216:219], v142 offset:5120
	ds_read_b128 v[220:223], v142 offset:6144
	ds_read_b128 v[224:227], v142 offset:7168
	global_load_lds_dwordx4 v[168:169], off
	v_lshl_add_u64 v[168:169], s[36:37], 0, v[138:139]
	s_add_i32 m0, s33, 0xe000
	s_nop 0
	global_load_lds_dwordx4 v[168:169], off
	s_waitcnt vmcnt(8)
	s_waitcnt lgkmcnt(0)
	s_barrier
	s_setprio 1
	s_waitcnt lgkmcnt(0)
	v_mfma_f32_16x16x32_bf16 v[128:131], v[144:147], v[186:189], 0
	v_mfma_f32_16x16x32_bf16 v[128:131], v[148:151], v[190:193], v[128:131]
	v_mfma_f32_16x16x32_bf16 v[124:127], v[156:159], v[190:193], 0
	v_mfma_f32_16x16x32_bf16 v[124:127], v[152:155], v[186:189], v[124:127]
	v_mfma_f32_16x16x32_bf16 v[116:119], v[152:155], v[194:197], 0
	v_mfma_f32_16x16x32_bf16 v[116:119], v[156:159], v[208:211], v[116:119]
	v_mfma_f32_16x16x32_bf16 v[120:123], v[148:151], v[208:211], 0
	v_mfma_f32_16x16x32_bf16 v[120:123], v[144:147], v[194:197], v[120:123]
	v_mfma_f32_16x16x32_bf16 v[108:111], v[144:147], v[212:215], 0
	v_mfma_f32_16x16x32_bf16 v[108:111], v[148:151], v[216:219], v[108:111]
	v_mfma_f32_16x16x32_bf16 v[100:103], v[156:159], v[216:219], 0
	v_mfma_f32_16x16x32_bf16 v[100:103], v[152:155], v[212:215], v[100:103]
	v_mfma_f32_16x16x32_bf16 v[84:87], v[152:155], v[220:223], 0
	v_mfma_f32_16x16x32_bf16 v[84:87], v[156:159], v[224:227], v[84:87]
	v_mfma_f32_16x16x32_bf16 v[92:95], v[148:151], v[224:227], 0
	v_mfma_f32_16x16x32_bf16 v[92:95], v[144:147], v[220:223], v[92:95]
	s_setprio 0
	s_setprio 1
	v_mfma_f32_16x16x32_bf16 v[112:115], v[160:163], v[186:189], 0
	v_mfma_f32_16x16x32_bf16 v[112:115], v[164:167], v[190:193], v[112:115]
	v_mfma_f32_16x16x32_bf16 v[104:107], v[182:185], v[190:193], 0
	v_mfma_f32_16x16x32_bf16 v[104:107], v[178:181], v[186:189], v[104:107]
	v_mfma_f32_16x16x32_bf16 v[88:91], v[178:181], v[194:197], 0
	v_mfma_f32_16x16x32_bf16 v[88:91], v[182:185], v[208:211], v[88:91]
	v_mfma_f32_16x16x32_bf16 v[96:99], v[164:167], v[208:211], 0
	v_mfma_f32_16x16x32_bf16 v[96:99], v[160:163], v[194:197], v[96:99]
	v_mfma_f32_16x16x32_bf16 v[80:83], v[160:163], v[212:215], 0
	v_mfma_f32_16x16x32_bf16 v[80:83], v[164:167], v[216:219], v[80:83]
	v_mfma_f32_16x16x32_bf16 v[76:79], v[182:185], v[216:219], 0
	v_mfma_f32_16x16x32_bf16 v[76:79], v[178:181], v[212:215], v[76:79]
	v_mfma_f32_16x16x32_bf16 v[68:71], v[178:181], v[220:223], 0
	v_mfma_f32_16x16x32_bf16 v[68:71], v[182:185], v[224:227], v[68:71]
	v_mfma_f32_16x16x32_bf16 v[72:75], v[164:167], v[224:227], 0
	v_mfma_f32_16x16x32_bf16 v[72:75], v[160:163], v[220:223], v[72:75]
	s_setprio 0
	s_barrier
	s_add_i32 s55, s55, s21
	v_lshl_add_u64 v[168:169], s[38:39], 0, v[134:135]
	s_mov_b32 m0, s55
	ds_read_b128 v[186:189], v142 offset:16384
	ds_read_b128 v[190:193], v142 offset:17408
	ds_read_b128 v[194:197], v142 offset:18432
	ds_read_b128 v[208:211], v142 offset:19456
	ds_read_b128 v[212:215], v142 offset:20480
	ds_read_b128 v[216:219], v142 offset:21504
	ds_read_b128 v[220:223], v142 offset:22528
	ds_read_b128 v[224:227], v142 offset:23552
	global_load_lds_dwordx4 v[168:169], off
	s_add_i32 m0, s55, 0x2000
	s_add_u32 s56, s38, 0x100000
	v_lshl_add_u64 v[228:229], s[38:39], 0, v[132:133]
	s_addc_u32 s57, s39, 0
	s_add_i32 s55, s58, s21
	global_load_lds_dwordx4 v[228:229], off
	v_lshl_add_u64 v[230:231], s[56:57], 0, v[134:135]
	s_mov_b32 m0, s55
	v_lshl_add_u64 v[232:233], s[40:41], 0, v[132:133]
	global_load_lds_dwordx4 v[230:231], off
	v_lshl_add_u64 v[230:231], s[56:57], 0, v[132:133]
	s_add_i32 m0, s55, 0x2000
	s_nop 0
	global_load_lds_dwordx4 v[230:231], off
	v_lshl_add_u64 v[230:231], s[40:41], 0, v[134:135]
	s_mov_b32 m0, s33
	s_nop 0
	global_load_lds_dwordx4 v[230:231], off
	s_mov_b32 m0, s42
	s_nop 0
	global_load_lds_dwordx4 v[232:233], off
	s_waitcnt vmcnt(8)
	s_waitcnt lgkmcnt(0)
	s_barrier
	s_setprio 1
	s_waitcnt lgkmcnt(0)
	v_mfma_f32_16x16x32_bf16 v[64:67], v[144:147], v[186:189], 0
	v_mfma_f32_16x16x32_bf16 v[64:67], v[148:151], v[190:193], v[64:67]
	v_mfma_f32_16x16x32_bf16 v[60:63], v[156:159], v[190:193], 0
	v_mfma_f32_16x16x32_bf16 v[60:63], v[152:155], v[186:189], v[60:63]
	v_mfma_f32_16x16x32_bf16 v[52:55], v[152:155], v[194:197], 0
	v_mfma_f32_16x16x32_bf16 v[52:55], v[156:159], v[208:211], v[52:55]
	v_mfma_f32_16x16x32_bf16 v[56:59], v[148:151], v[208:211], 0
	v_mfma_f32_16x16x32_bf16 v[56:59], v[144:147], v[194:197], v[56:59]
	v_mfma_f32_16x16x32_bf16 v[40:43], v[144:147], v[212:215], 0
	v_mfma_f32_16x16x32_bf16 v[40:43], v[148:151], v[216:219], v[40:43]
	v_mfma_f32_16x16x32_bf16 v[36:39], v[156:159], v[216:219], 0
	v_mfma_f32_16x16x32_bf16 v[36:39], v[152:155], v[212:215], v[36:39]
	v_mfma_f32_16x16x32_bf16 v[20:23], v[152:155], v[220:223], 0
	v_mfma_f32_16x16x32_bf16 v[20:23], v[156:159], v[224:227], v[20:23]
	v_mfma_f32_16x16x32_bf16 v[24:27], v[148:151], v[224:227], 0
	v_mfma_f32_16x16x32_bf16 v[24:27], v[144:147], v[220:223], v[24:27]
	s_setprio 0
	s_setprio 1
	v_mfma_f32_16x16x32_bf16 v[48:51], v[160:163], v[186:189], 0
	v_mfma_f32_16x16x32_bf16 v[48:51], v[164:167], v[190:193], v[48:51]
	v_mfma_f32_16x16x32_bf16 v[44:47], v[182:185], v[190:193], 0
	v_mfma_f32_16x16x32_bf16 v[44:47], v[178:181], v[186:189], v[44:47]
	v_mfma_f32_16x16x32_bf16 v[28:31], v[178:181], v[194:197], 0
	v_mfma_f32_16x16x32_bf16 v[28:31], v[182:185], v[208:211], v[28:31]
	v_mfma_f32_16x16x32_bf16 v[32:35], v[164:167], v[208:211], 0
	v_mfma_f32_16x16x32_bf16 v[32:35], v[160:163], v[194:197], v[32:35]
	v_mfma_f32_16x16x32_bf16 v[16:19], v[160:163], v[212:215], 0
	v_mfma_f32_16x16x32_bf16 v[16:19], v[164:167], v[216:219], v[16:19]
	v_mfma_f32_16x16x32_bf16 v[12:15], v[182:185], v[216:219], 0
	v_mfma_f32_16x16x32_bf16 v[12:15], v[178:181], v[212:215], v[12:15]
	v_mfma_f32_16x16x32_bf16 v[4:7], v[178:181], v[220:223], 0
	v_mfma_f32_16x16x32_bf16 v[4:7], v[182:185], v[224:227], v[4:7]
	v_mfma_f32_16x16x32_bf16 v[8:11], v[164:167], v[224:227], 0
	v_mfma_f32_16x16x32_bf16 v[8:11], v[160:163], v[220:223], v[8:11]
	s_setprio 0
	s_barrier
	s_add_i32 s55, 0, 0x18000
	v_add_u32_e32 v2, s55, v140
	s_add_i32 s56, 0, 0x1c000
	ds_read_b128 v[144:147], v2
	ds_read_b128 v[148:151], v2 offset:1024
	ds_read_b128 v[152:155], v2 offset:2048
	ds_read_b128 v[156:159], v2 offset:3072
	v_add_u32_e32 v2, s56, v140
	ds_read_b128 v[160:163], v2
	ds_read_b128 v[164:167], v2 offset:1024
	ds_read_b128 v[178:181], v2 offset:2048
	ds_read_b128 v[182:185], v2 offset:3072
	s_add_u32 s40, s40, 0x100000
	s_addc_u32 s41, s41, 0
	s_mov_b32 m0, s43
	v_lshl_add_u64 v[234:235], s[40:41], 0, v[134:135]
	ds_read_b128 v[186:189], v142 offset:32768
	ds_read_b128 v[190:193], v142 offset:33792
	ds_read_b128 v[194:197], v142 offset:34816
	ds_read_b128 v[208:211], v142 offset:35840
	ds_read_b128 v[212:215], v142 offset:36864
	ds_read_b128 v[216:219], v142 offset:37888
	ds_read_b128 v[220:223], v142 offset:38912
	ds_read_b128 v[224:227], v142 offset:39936
	global_load_lds_dwordx4 v[234:235], off
	v_lshl_add_u64 v[234:235], s[40:41], 0, v[132:133]
	s_mov_b32 m0, s44
	s_nop 0
	global_load_lds_dwordx4 v[234:235], off
	s_waitcnt vmcnt(8)
	s_waitcnt lgkmcnt(0)
	s_barrier
	s_setprio 1
	s_waitcnt lgkmcnt(0)
	v_mfma_f32_16x16x32_bf16 v[128:131], v[144:147], v[186:189], v[128:131]
	v_mfma_f32_16x16x32_bf16 v[128:131], v[148:151], v[190:193], v[128:131]
	v_mfma_f32_16x16x32_bf16 v[124:127], v[156:159], v[190:193], v[124:127]
	v_mfma_f32_16x16x32_bf16 v[124:127], v[152:155], v[186:189], v[124:127]
	v_mfma_f32_16x16x32_bf16 v[116:119], v[152:155], v[194:197], v[116:119]
	v_mfma_f32_16x16x32_bf16 v[116:119], v[156:159], v[208:211], v[116:119]
	v_mfma_f32_16x16x32_bf16 v[120:123], v[148:151], v[208:211], v[120:123]
	v_mfma_f32_16x16x32_bf16 v[120:123], v[144:147], v[194:197], v[120:123]
	v_mfma_f32_16x16x32_bf16 v[108:111], v[144:147], v[212:215], v[108:111]
	v_mfma_f32_16x16x32_bf16 v[108:111], v[148:151], v[216:219], v[108:111]
	v_mfma_f32_16x16x32_bf16 v[100:103], v[156:159], v[216:219], v[100:103]
	v_mfma_f32_16x16x32_bf16 v[100:103], v[152:155], v[212:215], v[100:103]
	v_mfma_f32_16x16x32_bf16 v[84:87], v[152:155], v[220:223], v[84:87]
	v_mfma_f32_16x16x32_bf16 v[84:87], v[156:159], v[224:227], v[84:87]
	v_mfma_f32_16x16x32_bf16 v[92:95], v[148:151], v[224:227], v[92:95]
	v_mfma_f32_16x16x32_bf16 v[92:95], v[144:147], v[220:223], v[92:95]
	s_setprio 0
	s_setprio 1
	v_mfma_f32_16x16x32_bf16 v[112:115], v[160:163], v[186:189], v[112:115]
	v_mfma_f32_16x16x32_bf16 v[112:115], v[164:167], v[190:193], v[112:115]
	v_mfma_f32_16x16x32_bf16 v[104:107], v[182:185], v[190:193], v[104:107]
	v_mfma_f32_16x16x32_bf16 v[104:107], v[178:181], v[186:189], v[104:107]
	v_mfma_f32_16x16x32_bf16 v[88:91], v[178:181], v[194:197], v[88:91]
	v_mfma_f32_16x16x32_bf16 v[88:91], v[182:185], v[208:211], v[88:91]
	v_mfma_f32_16x16x32_bf16 v[96:99], v[164:167], v[208:211], v[96:99]
	v_mfma_f32_16x16x32_bf16 v[96:99], v[160:163], v[194:197], v[96:99]
	v_mfma_f32_16x16x32_bf16 v[80:83], v[160:163], v[212:215], v[80:83]
	v_mfma_f32_16x16x32_bf16 v[80:83], v[164:167], v[216:219], v[80:83]
	v_mfma_f32_16x16x32_bf16 v[76:79], v[182:185], v[216:219], v[76:79]
	v_mfma_f32_16x16x32_bf16 v[76:79], v[178:181], v[212:215], v[76:79]
	v_mfma_f32_16x16x32_bf16 v[68:71], v[178:181], v[220:223], v[68:71]
	v_mfma_f32_16x16x32_bf16 v[68:71], v[182:185], v[224:227], v[68:71]
	v_mfma_f32_16x16x32_bf16 v[72:75], v[164:167], v[224:227], v[72:75]
	v_mfma_f32_16x16x32_bf16 v[72:75], v[160:163], v[220:223], v[72:75]
	s_setprio 0
	s_barrier
	s_add_i32 s40, s55, s21
	v_lshl_add_u64 v[168:169], v[168:169], 0, s[18:19]
	s_mov_b32 m0, s40
	ds_read_b128 v[186:189], v142 offset:49152
	ds_read_b128 v[190:193], v142 offset:50176
	ds_read_b128 v[194:197], v142 offset:51200
	ds_read_b128 v[208:211], v142 offset:52224
	ds_read_b128 v[212:215], v142 offset:53248
	ds_read_b128 v[216:219], v142 offset:54272
	ds_read_b128 v[220:223], v142 offset:55296
	ds_read_b128 v[224:227], v142 offset:56320
	global_load_lds_dwordx4 v[168:169], off
	s_add_i32 m0, s40, 0x2000
	s_add_u32 s38, s38, 0x100080
	v_lshl_add_u64 v[168:169], v[228:229], 0, s[18:19]
	s_addc_u32 s39, s39, 0
	s_add_i32 s40, s56, s21
	global_load_lds_dwordx4 v[168:169], off
	v_lshl_add_u64 v[168:169], s[38:39], 0, v[134:135]
	s_mov_b32 m0, s40
	s_nop 0
	global_load_lds_dwordx4 v[168:169], off
	v_lshl_add_u64 v[168:169], s[38:39], 0, v[132:133]
	s_add_i32 m0, s40, 0x2000
	s_nop 0
	global_load_lds_dwordx4 v[168:169], off
	v_lshl_add_u64 v[168:169], v[230:231], 0, s[18:19]
	s_mov_b32 m0, s25
	s_nop 0
	global_load_lds_dwordx4 v[168:169], off
	v_lshl_add_u64 v[168:169], v[232:233], 0, s[18:19]
	s_mov_b32 m0, s45
	s_nop 0
	global_load_lds_dwordx4 v[168:169], off
	s_waitcnt vmcnt(8)
	s_waitcnt lgkmcnt(0)
	s_barrier
	s_setprio 1
	s_waitcnt lgkmcnt(0)
	v_mfma_f32_16x16x32_bf16 v[64:67], v[144:147], v[186:189], v[64:67]
	v_mfma_f32_16x16x32_bf16 v[64:67], v[148:151], v[190:193], v[64:67]
	v_mfma_f32_16x16x32_bf16 v[60:63], v[156:159], v[190:193], v[60:63]
	v_mfma_f32_16x16x32_bf16 v[60:63], v[152:155], v[186:189], v[60:63]
	v_mfma_f32_16x16x32_bf16 v[52:55], v[152:155], v[194:197], v[52:55]
	v_mfma_f32_16x16x32_bf16 v[52:55], v[156:159], v[208:211], v[52:55]
	v_mfma_f32_16x16x32_bf16 v[56:59], v[148:151], v[208:211], v[56:59]
	v_mfma_f32_16x16x32_bf16 v[56:59], v[144:147], v[194:197], v[56:59]
	v_mfma_f32_16x16x32_bf16 v[40:43], v[144:147], v[212:215], v[40:43]
	v_mfma_f32_16x16x32_bf16 v[40:43], v[148:151], v[216:219], v[40:43]
	v_mfma_f32_16x16x32_bf16 v[36:39], v[156:159], v[216:219], v[36:39]
	v_mfma_f32_16x16x32_bf16 v[36:39], v[152:155], v[212:215], v[36:39]
	v_mfma_f32_16x16x32_bf16 v[20:23], v[152:155], v[220:223], v[20:23]
	v_mfma_f32_16x16x32_bf16 v[20:23], v[156:159], v[224:227], v[20:23]
	v_mfma_f32_16x16x32_bf16 v[24:27], v[148:151], v[224:227], v[24:27]
	v_mfma_f32_16x16x32_bf16 v[24:27], v[144:147], v[220:223], v[24:27]
	s_setprio 0
	s_setprio 1
	v_mfma_f32_16x16x32_bf16 v[48:51], v[160:163], v[186:189], v[48:51]
	v_mfma_f32_16x16x32_bf16 v[48:51], v[164:167], v[190:193], v[48:51]
	v_mfma_f32_16x16x32_bf16 v[44:47], v[182:185], v[190:193], v[44:47]
	v_mfma_f32_16x16x32_bf16 v[44:47], v[178:181], v[186:189], v[44:47]
	v_mfma_f32_16x16x32_bf16 v[28:31], v[178:181], v[194:197], v[28:31]
	v_mfma_f32_16x16x32_bf16 v[28:31], v[182:185], v[208:211], v[28:31]
	v_mfma_f32_16x16x32_bf16 v[32:35], v[164:167], v[208:211], v[32:35]
	v_mfma_f32_16x16x32_bf16 v[32:35], v[160:163], v[194:197], v[32:35]
	v_mfma_f32_16x16x32_bf16 v[16:19], v[160:163], v[212:215], v[16:19]
	v_mfma_f32_16x16x32_bf16 v[16:19], v[164:167], v[216:219], v[16:19]
	v_mfma_f32_16x16x32_bf16 v[12:15], v[182:185], v[216:219], v[12:15]
	v_mfma_f32_16x16x32_bf16 v[12:15], v[178:181], v[212:215], v[12:15]
	v_mfma_f32_16x16x32_bf16 v[4:7], v[178:181], v[220:223], v[4:7]
	v_mfma_f32_16x16x32_bf16 v[4:7], v[182:185], v[224:227], v[4:7]
	v_mfma_f32_16x16x32_bf16 v[8:11], v[164:167], v[224:227], v[8:11]
	v_mfma_f32_16x16x32_bf16 v[8:11], v[160:163], v[220:223], v[8:11]
	s_setprio 0
	s_barrier
	s_add_i32 s54, s54, 2
	s_add_u32 s36, s36, 0x100
	s_addc_u32 s37, s37, 0
	s_add_u32 s52, s52, 0x100
	s_addc_u32 s53, s53, 0
	s_cmp_gt_u32 s54, 5

.LBB0_900:
	s_ashr_i32 s49, s48, 31
	s_lshl_b64 s[10:11], s[48:49], 20
	s_add_u32 s50, s34, s10
	s_addc_u32 s51, s35, s11
	s_and_b64 s[10:11], s[38:39], exec
	s_cselect_b32 s5, s51, s9
	s_cselect_b32 s7, s50, s8
	s_ashr_i32 s47, s46, 31
	s_lshl_b64 s[10:11], s[46:47], 20
	s_add_u32 s52, s37, s10
	s_addc_u32 s53, s54, s11
	s_and_b64 s[10:11], s[38:39], exec
	s_cselect_b32 s10, s53, s13
	s_cselect_b32 s11, s52, s12
	s_add_u32 s8, s8, 0x80080
	s_addc_u32 s9, s9, 0
	s_add_u32 s21, s12, 0x100
	s_addc_u32 s22, s13, 0
	s_mov_b32 s33, -2
	v_lshl_add_u32 v148, s4, 8, v150
	v_ashrrev_i32_e32 v149, 31, v148
	v_lshl_add_u64 v[144:145], v[148:149], 2, s[40:41]
	global_load_dword v244, v[144:145], off
	global_load_dword v245, v[144:145], off offset:64
	global_load_dword v246, v[144:145], off offset:128
	global_load_dword v247, v[144:145], off offset:192
	global_load_dword v248, v[144:145], off offset:512
	global_load_dword v249, v[144:145], off offset:576
	global_load_dword v250, v[144:145], off offset:640
	global_load_dword v251, v[144:145], off offset:704
	s_add_u32 s12, s8, 0xfff80080
	s_addc_u32 s13, s9, -1
	s_add_i32 s47, 0, 0x10000
	s_cmp_eq_u32 s33, 28
	s_cselect_b32 s27, s5, s13
	s_cselect_b32 s26, s7, s12
	s_cselect_b32 s13, s10, s22
	s_cselect_b32 s12, s11, s21
	s_add_i32 s49, 0, 0x14000
	v_add_u32_e32 v158, s47, v151
	v_add_u32_e32 v182, s49, v151
	ds_read_b128 v[142:145], v158
	ds_read_b128 v[146:149], v158 offset:1024
	ds_read_b128 v[154:157], v158 offset:2048
	ds_read_b128 v[158:161], v158 offset:3072
	ds_read_b128 v[162:165], v182
	ds_read_b128 v[166:169], v182 offset:1024
	ds_read_b128 v[178:181], v182 offset:2048
	ds_read_b128 v[182:185], v182 offset:3072
	v_lshl_add_u64 v[228:229], s[8:9], 0, v[138:139]
	s_add_i32 m0, s57, 0xc000
	ds_read_b128 v[186:189], v153
	ds_read_b128 v[190:193], v153 offset:1024
	ds_read_b128 v[194:197], v153 offset:2048
	ds_read_b128 v[208:211], v153 offset:3072
	ds_read_b128 v[212:215], v153 offset:4096
	ds_read_b128 v[216:219], v153 offset:5120
	ds_read_b128 v[220:223], v153 offset:6144
	ds_read_b128 v[224:227], v153 offset:7168
	global_load_lds_dwordx4 v[228:229], off
	v_lshl_add_u64 v[228:229], s[8:9], 0, v[140:141]
	s_add_i32 m0, s57, 0xe000
	s_nop 0
	global_load_lds_dwordx4 v[228:229], off
	s_waitcnt vmcnt(8)
	s_waitcnt lgkmcnt(0)
	s_barrier
	s_setprio 1
	s_waitcnt lgkmcnt(0)
	v_mfma_f32_16x16x32_bf16 v[128:131], v[142:145], v[186:189], 0
	v_mfma_f32_16x16x32_bf16 v[128:131], v[146:149], v[190:193], v[128:131]
	v_mfma_f32_16x16x32_bf16 v[124:127], v[158:161], v[190:193], 0
	v_mfma_f32_16x16x32_bf16 v[124:127], v[154:157], v[186:189], v[124:127]
	v_mfma_f32_16x16x32_bf16 v[108:111], v[154:157], v[194:197], 0
	v_mfma_f32_16x16x32_bf16 v[108:111], v[158:161], v[208:211], v[108:111]
	v_mfma_f32_16x16x32_bf16 v[112:115], v[146:149], v[208:211], 0
	v_mfma_f32_16x16x32_bf16 v[112:115], v[142:145], v[194:197], v[112:115]
	v_mfma_f32_16x16x32_bf16 v[96:99], v[142:145], v[212:215], 0
	v_mfma_f32_16x16x32_bf16 v[96:99], v[146:149], v[216:219], v[96:99]
	v_mfma_f32_16x16x32_bf16 v[92:95], v[158:161], v[216:219], 0
	v_mfma_f32_16x16x32_bf16 v[92:95], v[154:157], v[212:215], v[92:95]
	v_mfma_f32_16x16x32_bf16 v[76:79], v[154:157], v[220:223], 0
	v_mfma_f32_16x16x32_bf16 v[76:79], v[158:161], v[224:227], v[76:79]
	v_mfma_f32_16x16x32_bf16 v[80:83], v[146:149], v[224:227], 0
	v_mfma_f32_16x16x32_bf16 v[80:83], v[142:145], v[220:223], v[80:83]
	s_setprio 0
	s_setprio 1
	v_mfma_f32_16x16x32_bf16 v[120:123], v[162:165], v[186:189], 0
	v_mfma_f32_16x16x32_bf16 v[120:123], v[166:169], v[190:193], v[120:123]
	v_mfma_f32_16x16x32_bf16 v[116:119], v[182:185], v[190:193], 0
	v_mfma_f32_16x16x32_bf16 v[116:119], v[178:181], v[186:189], v[116:119]
	v_mfma_f32_16x16x32_bf16 v[100:103], v[178:181], v[194:197], 0
	v_mfma_f32_16x16x32_bf16 v[100:103], v[182:185], v[208:211], v[100:103]
	v_mfma_f32_16x16x32_bf16 v[104:107], v[166:169], v[208:211], 0
	v_mfma_f32_16x16x32_bf16 v[104:107], v[162:165], v[194:197], v[104:107]
	v_mfma_f32_16x16x32_bf16 v[88:91], v[162:165], v[212:215], 0
	v_mfma_f32_16x16x32_bf16 v[88:91], v[166:169], v[216:219], v[88:91]
	v_mfma_f32_16x16x32_bf16 v[84:87], v[182:185], v[216:219], 0
	v_mfma_f32_16x16x32_bf16 v[84:87], v[178:181], v[212:215], v[84:87]
	v_mfma_f32_16x16x32_bf16 v[68:71], v[178:181], v[220:223], 0
	v_mfma_f32_16x16x32_bf16 v[68:71], v[182:185], v[224:227], v[68:71]
	v_mfma_f32_16x16x32_bf16 v[72:75], v[166:169], v[224:227], 0
	v_mfma_f32_16x16x32_bf16 v[72:75], v[162:165], v[220:223], v[72:75]
	s_setprio 0
	s_barrier
	s_add_i32 s47, s47, s55
	v_lshl_add_u64 v[228:229], s[12:13], 0, v[2:3]
	s_mov_b32 m0, s47
	ds_read_b128 v[186:189], v153 offset:16384
	ds_read_b128 v[190:193], v153 offset:17408
	ds_read_b128 v[194:197], v153 offset:18432
	ds_read_b128 v[208:211], v153 offset:19456
	ds_read_b128 v[212:215], v153 offset:20480
	ds_read_b128 v[216:219], v153 offset:21504
	ds_read_b128 v[220:223], v153 offset:22528
	ds_read_b128 v[224:227], v153 offset:23552
	global_load_lds_dwordx4 v[228:229], off
	s_add_i32 m0, s47, 0x2000
	s_add_u32 s66, s12, 0x80000
	v_lshl_add_u64 v[230:231], s[12:13], 0, v[132:133]
	s_addc_u32 s67, s13, 0
	s_add_i32 s47, s49, s55
	global_load_lds_dwordx4 v[230:231], off
	v_lshl_add_u64 v[232:233], s[66:67], 0, v[2:3]
	s_mov_b32 m0, s47
	v_lshl_add_u64 v[234:235], s[26:27], 0, v[134:135]
	global_load_lds_dwordx4 v[232:233], off
	v_lshl_add_u64 v[232:233], s[66:67], 0, v[132:133]
	s_add_i32 m0, s47, 0x2000
	s_nop 0
	global_load_lds_dwordx4 v[232:233], off
	v_lshl_add_u64 v[232:233], s[26:27], 0, v[136:137]
	s_mov_b32 m0, s57
	s_nop 0
	global_load_lds_dwordx4 v[232:233], off
	s_mov_b32 m0, s58
	s_nop 0
	global_load_lds_dwordx4 v[234:235], off
	s_waitcnt vmcnt(8)
	s_waitcnt lgkmcnt(0)
	s_barrier
	s_setprio 1
	s_waitcnt lgkmcnt(0)
	v_mfma_f32_16x16x32_bf16 v[64:67], v[142:145], v[186:189], 0
	v_mfma_f32_16x16x32_bf16 v[64:67], v[146:149], v[190:193], v[64:67]
	v_mfma_f32_16x16x32_bf16 v[60:63], v[158:161], v[190:193], 0
	v_mfma_f32_16x16x32_bf16 v[60:63], v[154:157], v[186:189], v[60:63]
	v_mfma_f32_16x16x32_bf16 v[44:47], v[154:157], v[194:197], 0
	v_mfma_f32_16x16x32_bf16 v[44:47], v[158:161], v[208:211], v[44:47]
	v_mfma_f32_16x16x32_bf16 v[48:51], v[146:149], v[208:211], 0
	v_mfma_f32_16x16x32_bf16 v[48:51], v[142:145], v[194:197], v[48:51]
	v_mfma_f32_16x16x32_bf16 v[32:35], v[142:145], v[212:215], 0
	v_mfma_f32_16x16x32_bf16 v[32:35], v[146:149], v[216:219], v[32:35]
	v_mfma_f32_16x16x32_bf16 v[28:31], v[158:161], v[216:219], 0
	v_mfma_f32_16x16x32_bf16 v[28:31], v[154:157], v[212:215], v[28:31]
	v_mfma_f32_16x16x32_bf16 v[12:15], v[154:157], v[220:223], 0
	v_mfma_f32_16x16x32_bf16 v[12:15], v[158:161], v[224:227], v[12:15]
	v_mfma_f32_16x16x32_bf16 v[16:19], v[146:149], v[224:227], 0
	v_mfma_f32_16x16x32_bf16 v[16:19], v[142:145], v[220:223], v[16:19]
	s_setprio 0
	s_setprio 1
	v_mfma_f32_16x16x32_bf16 v[56:59], v[162:165], v[186:189], 0
	v_mfma_f32_16x16x32_bf16 v[56:59], v[166:169], v[190:193], v[56:59]
	v_mfma_f32_16x16x32_bf16 v[52:55], v[182:185], v[190:193], 0
	v_mfma_f32_16x16x32_bf16 v[52:55], v[178:181], v[186:189], v[52:55]
	v_mfma_f32_16x16x32_bf16 v[36:39], v[178:181], v[194:197], 0
	v_mfma_f32_16x16x32_bf16 v[36:39], v[182:185], v[208:211], v[36:39]
	v_mfma_f32_16x16x32_bf16 v[40:43], v[166:169], v[208:211], 0
	v_mfma_f32_16x16x32_bf16 v[40:43], v[162:165], v[194:197], v[40:43]
	v_mfma_f32_16x16x32_bf16 v[24:27], v[162:165], v[212:215], 0
	v_mfma_f32_16x16x32_bf16 v[24:27], v[166:169], v[216:219], v[24:27]
	v_mfma_f32_16x16x32_bf16 v[20:23], v[182:185], v[216:219], 0
	v_mfma_f32_16x16x32_bf16 v[20:23], v[178:181], v[212:215], v[20:23]
	v_mfma_f32_16x16x32_bf16 v[4:7], v[178:181], v[220:223], 0
	v_mfma_f32_16x16x32_bf16 v[4:7], v[182:185], v[224:227], v[4:7]
	v_mfma_f32_16x16x32_bf16 v[8:11], v[166:169], v[224:227], 0
	v_mfma_f32_16x16x32_bf16 v[8:11], v[162:165], v[220:223], v[8:11]
	s_setprio 0
	s_barrier
	s_add_i32 s47, 0, 0x18000
	s_add_i32 s49, 0, 0x1c000
	v_add_u32_e32 v158, s47, v151
	v_add_u32_e32 v182, s49, v151
	ds_read_b128 v[142:145], v158
	ds_read_b128 v[146:149], v158 offset:1024
	ds_read_b128 v[154:157], v158 offset:2048
	ds_read_b128 v[158:161], v158 offset:3072
	ds_read_b128 v[162:165], v182
	ds_read_b128 v[166:169], v182 offset:1024
	ds_read_b128 v[178:181], v182 offset:2048
	ds_read_b128 v[182:185], v182 offset:3072
	s_add_u32 s26, s26, 0x80000
	s_addc_u32 s27, s27, 0
	s_mov_b32 m0, s59
	v_lshl_add_u64 v[236:237], s[26:27], 0, v[136:137]
	ds_read_b128 v[186:189], v153 offset:32768
	ds_read_b128 v[190:193], v153 offset:33792
	ds_read_b128 v[194:197], v153 offset:34816
	ds_read_b128 v[208:211], v153 offset:35840
	ds_read_b128 v[212:215], v153 offset:36864
	ds_read_b128 v[216:219], v153 offset:37888
	ds_read_b128 v[220:223], v153 offset:38912
	ds_read_b128 v[224:227], v153 offset:39936
	global_load_lds_dwordx4 v[236:237], off
	v_lshl_add_u64 v[236:237], s[26:27], 0, v[134:135]
	s_mov_b32 m0, s60
	s_nop 0
	global_load_lds_dwordx4 v[236:237], off
	s_waitcnt vmcnt(8)
	s_waitcnt lgkmcnt(0)
	s_barrier
	s_setprio 1
	s_waitcnt lgkmcnt(0)
	v_mfma_f32_16x16x32_bf16 v[128:131], v[142:145], v[186:189], v[128:131]
	v_mfma_f32_16x16x32_bf16 v[128:131], v[146:149], v[190:193], v[128:131]
	v_mfma_f32_16x16x32_bf16 v[124:127], v[158:161], v[190:193], v[124:127]
	v_mfma_f32_16x16x32_bf16 v[124:127], v[154:157], v[186:189], v[124:127]
	v_mfma_f32_16x16x32_bf16 v[108:111], v[154:157], v[194:197], v[108:111]
	v_mfma_f32_16x16x32_bf16 v[108:111], v[158:161], v[208:211], v[108:111]
	v_mfma_f32_16x16x32_bf16 v[112:115], v[146:149], v[208:211], v[112:115]
	v_mfma_f32_16x16x32_bf16 v[112:115], v[142:145], v[194:197], v[112:115]
	v_mfma_f32_16x16x32_bf16 v[96:99], v[142:145], v[212:215], v[96:99]
	v_mfma_f32_16x16x32_bf16 v[96:99], v[146:149], v[216:219], v[96:99]
	v_mfma_f32_16x16x32_bf16 v[92:95], v[158:161], v[216:219], v[92:95]
	v_mfma_f32_16x16x32_bf16 v[92:95], v[154:157], v[212:215], v[92:95]
	v_mfma_f32_16x16x32_bf16 v[76:79], v[154:157], v[220:223], v[76:79]
	v_mfma_f32_16x16x32_bf16 v[76:79], v[158:161], v[224:227], v[76:79]
	v_mfma_f32_16x16x32_bf16 v[80:83], v[146:149], v[224:227], v[80:83]
	v_mfma_f32_16x16x32_bf16 v[80:83], v[142:145], v[220:223], v[80:83]
	s_setprio 0
	s_setprio 1
	v_mfma_f32_16x16x32_bf16 v[120:123], v[162:165], v[186:189], v[120:123]
	v_mfma_f32_16x16x32_bf16 v[120:123], v[166:169], v[190:193], v[120:123]
	v_mfma_f32_16x16x32_bf16 v[116:119], v[182:185], v[190:193], v[116:119]
	v_mfma_f32_16x16x32_bf16 v[116:119], v[178:181], v[186:189], v[116:119]
	v_mfma_f32_16x16x32_bf16 v[100:103], v[178:181], v[194:197], v[100:103]
	v_mfma_f32_16x16x32_bf16 v[100:103], v[182:185], v[208:211], v[100:103]
	v_mfma_f32_16x16x32_bf16 v[104:107], v[166:169], v[208:211], v[104:107]
	v_mfma_f32_16x16x32_bf16 v[104:107], v[162:165], v[194:197], v[104:107]
	v_mfma_f32_16x16x32_bf16 v[88:91], v[162:165], v[212:215], v[88:91]
	v_mfma_f32_16x16x32_bf16 v[88:91], v[166:169], v[216:219], v[88:91]
	v_mfma_f32_16x16x32_bf16 v[84:87], v[182:185], v[216:219], v[84:87]
	v_mfma_f32_16x16x32_bf16 v[84:87], v[178:181], v[212:215], v[84:87]
	v_mfma_f32_16x16x32_bf16 v[68:71], v[178:181], v[220:223], v[68:71]
	v_mfma_f32_16x16x32_bf16 v[68:71], v[182:185], v[224:227], v[68:71]
	v_mfma_f32_16x16x32_bf16 v[72:75], v[166:169], v[224:227], v[72:75]
	v_mfma_f32_16x16x32_bf16 v[72:75], v[162:165], v[220:223], v[72:75]
	s_setprio 0
	s_barrier
	s_add_i32 s26, s47, s55
	v_lshl_add_u64 v[228:229], v[228:229], 0, s[18:19]
	s_mov_b32 m0, s26
	ds_read_b128 v[186:189], v153 offset:49152
	ds_read_b128 v[190:193], v153 offset:50176
	ds_read_b128 v[194:197], v153 offset:51200
	ds_read_b128 v[208:211], v153 offset:52224
	ds_read_b128 v[212:215], v153 offset:53248
	ds_read_b128 v[216:219], v153 offset:54272
	ds_read_b128 v[220:223], v153 offset:55296
	ds_read_b128 v[224:227], v153 offset:56320
	global_load_lds_dwordx4 v[228:229], off
	s_add_i32 m0, s26, 0x2000
	s_add_u32 s12, s12, 0x80080
	v_lshl_add_u64 v[228:229], v[230:231], 0, s[18:19]
	s_addc_u32 s13, s13, 0
	s_add_i32 s26, s49, s55
	global_load_lds_dwordx4 v[228:229], off
	v_lshl_add_u64 v[228:229], s[12:13], 0, v[2:3]
	s_mov_b32 m0, s26
	s_nop 0
	global_load_lds_dwordx4 v[228:229], off
	v_lshl_add_u64 v[228:229], s[12:13], 0, v[132:133]
	s_add_i32 m0, s26, 0x2000
	s_nop 0
	global_load_lds_dwordx4 v[228:229], off
	v_lshl_add_u64 v[228:229], v[232:233], 0, s[18:19]
	s_mov_b32 m0, s14
	s_nop 0
	global_load_lds_dwordx4 v[228:229], off
	v_lshl_add_u64 v[228:229], v[234:235], 0, s[18:19]
	s_mov_b32 m0, s61
	s_nop 0
	global_load_lds_dwordx4 v[228:229], off
	s_waitcnt vmcnt(8)
	s_waitcnt lgkmcnt(0)
	s_barrier
	s_setprio 1
	s_waitcnt lgkmcnt(0)
	v_mfma_f32_16x16x32_bf16 v[64:67], v[142:145], v[186:189], v[64:67]
	v_mfma_f32_16x16x32_bf16 v[64:67], v[146:149], v[190:193], v[64:67]
	v_mfma_f32_16x16x32_bf16 v[60:63], v[158:161], v[190:193], v[60:63]
	v_mfma_f32_16x16x32_bf16 v[60:63], v[154:157], v[186:189], v[60:63]
	v_mfma_f32_16x16x32_bf16 v[44:47], v[154:157], v[194:197], v[44:47]
	v_mfma_f32_16x16x32_bf16 v[44:47], v[158:161], v[208:211], v[44:47]
	v_mfma_f32_16x16x32_bf16 v[48:51], v[146:149], v[208:211], v[48:51]
	v_mfma_f32_16x16x32_bf16 v[48:51], v[142:145], v[194:197], v[48:51]
	v_mfma_f32_16x16x32_bf16 v[32:35], v[142:145], v[212:215], v[32:35]
	v_mfma_f32_16x16x32_bf16 v[32:35], v[146:149], v[216:219], v[32:35]
	v_mfma_f32_16x16x32_bf16 v[28:31], v[158:161], v[216:219], v[28:31]
	v_mfma_f32_16x16x32_bf16 v[28:31], v[154:157], v[212:215], v[28:31]
	v_mfma_f32_16x16x32_bf16 v[12:15], v[154:157], v[220:223], v[12:15]
	v_mfma_f32_16x16x32_bf16 v[12:15], v[158:161], v[224:227], v[12:15]
	v_mfma_f32_16x16x32_bf16 v[16:19], v[146:149], v[224:227], v[16:19]
	v_mfma_f32_16x16x32_bf16 v[16:19], v[142:145], v[220:223], v[16:19]
	s_setprio 0
	s_setprio 1
	v_mfma_f32_16x16x32_bf16 v[56:59], v[162:165], v[186:189], v[56:59]
	v_mfma_f32_16x16x32_bf16 v[56:59], v[166:169], v[190:193], v[56:59]
	v_mfma_f32_16x16x32_bf16 v[52:55], v[182:185], v[190:193], v[52:55]
	v_mfma_f32_16x16x32_bf16 v[52:55], v[178:181], v[186:189], v[52:55]
	v_mfma_f32_16x16x32_bf16 v[36:39], v[178:181], v[194:197], v[36:39]
	v_mfma_f32_16x16x32_bf16 v[36:39], v[182:185], v[208:211], v[36:39]
	v_mfma_f32_16x16x32_bf16 v[40:43], v[166:169], v[208:211], v[40:43]
	v_mfma_f32_16x16x32_bf16 v[40:43], v[162:165], v[194:197], v[40:43]
	v_mfma_f32_16x16x32_bf16 v[24:27], v[162:165], v[212:215], v[24:27]
	v_mfma_f32_16x16x32_bf16 v[24:27], v[166:169], v[216:219], v[24:27]
	v_mfma_f32_16x16x32_bf16 v[20:23], v[182:185], v[216:219], v[20:23]
	v_mfma_f32_16x16x32_bf16 v[20:23], v[178:181], v[212:215], v[20:23]
	v_mfma_f32_16x16x32_bf16 v[4:7], v[178:181], v[220:223], v[4:7]
	v_mfma_f32_16x16x32_bf16 v[4:7], v[182:185], v[224:227], v[4:7]
	v_mfma_f32_16x16x32_bf16 v[8:11], v[166:169], v[224:227], v[8:11]
	v_mfma_f32_16x16x32_bf16 v[8:11], v[162:165], v[220:223], v[8:11]
	s_setprio 0
	s_barrier
	s_add_i32 s33, s33, 2
	s_add_u32 s8, s8, 0x100
	s_addc_u32 s9, s9, 0
	s_add_u32 s21, s21, 0x100
	s_addc_u32 s22, s22, 0
	s_cmp_gt_u32 s33, 29

.LBB0_1073:
	s_ashr_i32 s27, s26, 31
	s_lshl_b64 s[34:35], s[26:27], 22
	s_add_u32 s34, s22, s34
	s_addc_u32 s35, s25, s35
	s_and_b64 s[36:37], s[38:39], exec
	s_cselect_b32 s27, s35, s41
	s_cselect_b32 s54, s34, s40
	s_ashr_i32 s13, s12, 31
	s_lshl_b64 s[36:37], s[12:13], 22
	s_add_u32 s36, s10, s36
	s_addc_u32 s37, s11, s37
	s_and_b64 s[44:45], s[38:39], exec
	s_cselect_b32 s13, s37, s43
	s_cselect_b32 s55, s36, s42
	s_add_u32 s40, s40, 0x200080
	s_addc_u32 s41, s41, 0
	s_add_u32 s56, s42, 0x100
	s_addc_u32 s57, s43, 0
	s_mov_b32 s58, -2
	s_add_u32 s42, s40, 0xffe00080
	s_addc_u32 s43, s41, -1
	s_add_i32 s59, 0, 0x10000
	s_cmpk_eq_i32 s58, 0x7c
	s_cselect_b32 s45, s27, s43
	s_cselect_b32 s44, s54, s42
	v_add_u32_e32 v142, s59, v144
	s_cselect_b32 s43, s13, s57
	s_cselect_b32 s42, s55, s56
	s_add_i32 s62, 0, 0x14000
	ds_read_b128 v[148:151], v142
	ds_read_b128 v[152:155], v142 offset:1024
	ds_read_b128 v[156:159], v142 offset:2048
	ds_read_b128 v[160:163], v142 offset:3072
	v_add_u32_e32 v142, s62, v144
	ds_read_b128 v[164:167], v142
	ds_read_b128 v[178:181], v142 offset:1024
	ds_read_b128 v[182:185], v142 offset:2048
	ds_read_b128 v[186:189], v142 offset:3072
	v_lshl_add_u64 v[142:143], s[40:41], 0, v[138:139]
	s_add_i32 m0, s46, 0xc000
	ds_read_b128 v[190:193], v146
	ds_read_b128 v[194:197], v146 offset:1024
	ds_read_b128 v[208:211], v146 offset:2048
	ds_read_b128 v[212:215], v146 offset:3072
	ds_read_b128 v[216:219], v146 offset:4096
	ds_read_b128 v[220:223], v146 offset:5120
	ds_read_b128 v[224:227], v146 offset:6144
	ds_read_b128 v[228:231], v146 offset:7168
	global_load_lds_dwordx4 v[142:143], off
	v_lshl_add_u64 v[142:143], s[40:41], 0, v[140:141]
	s_add_i32 m0, s46, 0xe000
	s_nop 0
	global_load_lds_dwordx4 v[142:143], off
	s_waitcnt vmcnt(8)
	s_waitcnt lgkmcnt(0)
	s_barrier
	s_setprio 1
	s_waitcnt lgkmcnt(0)
	v_mfma_f32_16x16x32_bf16 v[128:131], v[148:151], v[190:193], 0
	v_mfma_f32_16x16x32_bf16 v[128:131], v[152:155], v[194:197], v[128:131]
	v_mfma_f32_16x16x32_bf16 v[124:127], v[160:163], v[194:197], 0
	v_mfma_f32_16x16x32_bf16 v[124:127], v[156:159], v[190:193], v[124:127]
	v_mfma_f32_16x16x32_bf16 v[112:115], v[156:159], v[208:211], 0
	v_mfma_f32_16x16x32_bf16 v[112:115], v[160:163], v[212:215], v[112:115]
	v_mfma_f32_16x16x32_bf16 v[120:123], v[152:155], v[212:215], 0
	v_mfma_f32_16x16x32_bf16 v[120:123], v[148:151], v[208:211], v[120:123]
	v_mfma_f32_16x16x32_bf16 v[104:107], v[148:151], v[216:219], 0
	v_mfma_f32_16x16x32_bf16 v[104:107], v[152:155], v[220:223], v[104:107]
	v_mfma_f32_16x16x32_bf16 v[96:99], v[160:163], v[220:223], 0
	v_mfma_f32_16x16x32_bf16 v[96:99], v[156:159], v[216:219], v[96:99]
	v_mfma_f32_16x16x32_bf16 v[80:83], v[156:159], v[224:227], 0
	v_mfma_f32_16x16x32_bf16 v[80:83], v[160:163], v[228:231], v[80:83]
	v_mfma_f32_16x16x32_bf16 v[88:91], v[152:155], v[228:231], 0
	v_mfma_f32_16x16x32_bf16 v[88:91], v[148:151], v[224:227], v[88:91]
	s_setprio 0
	s_setprio 1
	v_mfma_f32_16x16x32_bf16 v[116:119], v[164:167], v[190:193], 0
	v_mfma_f32_16x16x32_bf16 v[116:119], v[178:181], v[194:197], v[116:119]
	v_mfma_f32_16x16x32_bf16 v[108:111], v[186:189], v[194:197], 0
	v_mfma_f32_16x16x32_bf16 v[108:111], v[182:185], v[190:193], v[108:111]
	v_mfma_f32_16x16x32_bf16 v[92:95], v[182:185], v[208:211], 0
	v_mfma_f32_16x16x32_bf16 v[92:95], v[186:189], v[212:215], v[92:95]
	v_mfma_f32_16x16x32_bf16 v[100:103], v[178:181], v[212:215], 0
	v_mfma_f32_16x16x32_bf16 v[100:103], v[164:167], v[208:211], v[100:103]
	v_mfma_f32_16x16x32_bf16 v[84:87], v[164:167], v[216:219], 0
	v_mfma_f32_16x16x32_bf16 v[84:87], v[178:181], v[220:223], v[84:87]
	v_mfma_f32_16x16x32_bf16 v[76:79], v[186:189], v[220:223], 0
	v_mfma_f32_16x16x32_bf16 v[76:79], v[182:185], v[216:219], v[76:79]
	v_mfma_f32_16x16x32_bf16 v[68:71], v[182:185], v[224:227], 0
	v_mfma_f32_16x16x32_bf16 v[68:71], v[186:189], v[228:231], v[68:71]
	v_mfma_f32_16x16x32_bf16 v[72:75], v[178:181], v[228:231], 0
	v_mfma_f32_16x16x32_bf16 v[72:75], v[164:167], v[224:227], v[72:75]
	s_setprio 0
	s_barrier
	s_add_i32 s59, s59, s33
	v_lshl_add_u64 v[142:143], s[42:43], 0, v[2:3]
	s_mov_b32 m0, s59
	ds_read_b128 v[190:193], v146 offset:16384
	ds_read_b128 v[194:197], v146 offset:17408
	ds_read_b128 v[208:211], v146 offset:18432
	ds_read_b128 v[212:215], v146 offset:19456
	ds_read_b128 v[216:219], v146 offset:20480
	ds_read_b128 v[220:223], v146 offset:21504
	ds_read_b128 v[224:227], v146 offset:22528
	ds_read_b128 v[228:231], v146 offset:23552
	global_load_lds_dwordx4 v[142:143], off
	s_add_i32 m0, s59, 0x2000
	s_add_u32 s60, s42, 0x200000
	v_lshl_add_u64 v[168:169], s[42:43], 0, v[136:137]
	s_addc_u32 s61, s43, 0
	s_add_i32 s59, s62, s33
	global_load_lds_dwordx4 v[168:169], off
	v_lshl_add_u64 v[232:233], s[60:61], 0, v[2:3]
	s_mov_b32 m0, s59
	v_lshl_add_u64 v[234:235], s[44:45], 0, v[134:135]
	global_load_lds_dwordx4 v[232:233], off
	v_lshl_add_u64 v[232:233], s[60:61], 0, v[136:137]
	s_add_i32 m0, s59, 0x2000
	s_nop 0
	global_load_lds_dwordx4 v[232:233], off
	v_lshl_add_u64 v[232:233], s[44:45], 0, v[132:133]
	s_mov_b32 m0, s46
	s_nop 0
	global_load_lds_dwordx4 v[232:233], off
	s_mov_b32 m0, s47
	s_nop 0
	global_load_lds_dwordx4 v[234:235], off
	s_waitcnt vmcnt(8)
	s_waitcnt lgkmcnt(0)
	s_barrier
	s_setprio 1
	s_waitcnt lgkmcnt(0)
	v_mfma_f32_16x16x32_bf16 v[64:67], v[148:151], v[190:193], 0
	v_mfma_f32_16x16x32_bf16 v[64:67], v[152:155], v[194:197], v[64:67]
	v_mfma_f32_16x16x32_bf16 v[60:63], v[160:163], v[194:197], 0
	v_mfma_f32_16x16x32_bf16 v[60:63], v[156:159], v[190:193], v[60:63]
	v_mfma_f32_16x16x32_bf16 v[48:51], v[156:159], v[208:211], 0
	v_mfma_f32_16x16x32_bf16 v[48:51], v[160:163], v[212:215], v[48:51]
	v_mfma_f32_16x16x32_bf16 v[56:59], v[152:155], v[212:215], 0
	v_mfma_f32_16x16x32_bf16 v[56:59], v[148:151], v[208:211], v[56:59]
	v_mfma_f32_16x16x32_bf16 v[40:43], v[148:151], v[216:219], 0
	v_mfma_f32_16x16x32_bf16 v[40:43], v[152:155], v[220:223], v[40:43]
	v_mfma_f32_16x16x32_bf16 v[32:35], v[160:163], v[220:223], 0
	v_mfma_f32_16x16x32_bf16 v[32:35], v[156:159], v[216:219], v[32:35]
	v_mfma_f32_16x16x32_bf16 v[16:19], v[156:159], v[224:227], 0
	v_mfma_f32_16x16x32_bf16 v[16:19], v[160:163], v[228:231], v[16:19]
	v_mfma_f32_16x16x32_bf16 v[24:27], v[152:155], v[228:231], 0
	v_mfma_f32_16x16x32_bf16 v[24:27], v[148:151], v[224:227], v[24:27]
	s_setprio 0
	s_setprio 1
	v_mfma_f32_16x16x32_bf16 v[52:55], v[164:167], v[190:193], 0
	v_mfma_f32_16x16x32_bf16 v[52:55], v[178:181], v[194:197], v[52:55]
	v_mfma_f32_16x16x32_bf16 v[44:47], v[186:189], v[194:197], 0
	v_mfma_f32_16x16x32_bf16 v[44:47], v[182:185], v[190:193], v[44:47]
	v_mfma_f32_16x16x32_bf16 v[28:31], v[182:185], v[208:211], 0
	v_mfma_f32_16x16x32_bf16 v[28:31], v[186:189], v[212:215], v[28:31]
	v_mfma_f32_16x16x32_bf16 v[36:39], v[178:181], v[212:215], 0
	v_mfma_f32_16x16x32_bf16 v[36:39], v[164:167], v[208:211], v[36:39]
	v_mfma_f32_16x16x32_bf16 v[20:23], v[164:167], v[216:219], 0
	v_mfma_f32_16x16x32_bf16 v[20:23], v[178:181], v[220:223], v[20:23]
	v_mfma_f32_16x16x32_bf16 v[12:15], v[186:189], v[220:223], 0
	v_mfma_f32_16x16x32_bf16 v[12:15], v[182:185], v[216:219], v[12:15]
	v_mfma_f32_16x16x32_bf16 v[4:7], v[182:185], v[224:227], 0
	v_mfma_f32_16x16x32_bf16 v[4:7], v[186:189], v[228:231], v[4:7]
	v_mfma_f32_16x16x32_bf16 v[8:11], v[178:181], v[228:231], 0
	v_mfma_f32_16x16x32_bf16 v[8:11], v[164:167], v[224:227], v[8:11]
	s_setprio 0
	s_barrier
	s_add_i32 s59, 0, 0x18000
	v_add_u32_e32 v147, s59, v144
	s_add_i32 s60, 0, 0x1c000
	ds_read_b128 v[148:151], v147
	ds_read_b128 v[152:155], v147 offset:1024
	ds_read_b128 v[156:159], v147 offset:2048
	ds_read_b128 v[160:163], v147 offset:3072
	v_add_u32_e32 v147, s60, v144
	ds_read_b128 v[164:167], v147
	ds_read_b128 v[178:181], v147 offset:1024
	ds_read_b128 v[182:185], v147 offset:2048
	ds_read_b128 v[186:189], v147 offset:3072
	s_add_u32 s44, s44, 0x200000
	s_addc_u32 s45, s45, 0
	s_mov_b32 m0, s48
	v_lshl_add_u64 v[236:237], s[44:45], 0, v[132:133]
	ds_read_b128 v[190:193], v146 offset:32768
	ds_read_b128 v[194:197], v146 offset:33792
	ds_read_b128 v[208:211], v146 offset:34816
	ds_read_b128 v[212:215], v146 offset:35840
	ds_read_b128 v[216:219], v146 offset:36864
	ds_read_b128 v[220:223], v146 offset:37888
	ds_read_b128 v[224:227], v146 offset:38912
	ds_read_b128 v[228:231], v146 offset:39936
	global_load_lds_dwordx4 v[236:237], off
	v_lshl_add_u64 v[236:237], s[44:45], 0, v[134:135]
	s_mov_b32 m0, s49
	s_nop 0
	global_load_lds_dwordx4 v[236:237], off
	s_waitcnt vmcnt(8)
	s_waitcnt lgkmcnt(0)
	s_barrier
	s_setprio 1
	s_waitcnt lgkmcnt(0)
	v_mfma_f32_16x16x32_bf16 v[128:131], v[148:151], v[190:193], v[128:131]
	v_mfma_f32_16x16x32_bf16 v[128:131], v[152:155], v[194:197], v[128:131]
	v_mfma_f32_16x16x32_bf16 v[124:127], v[160:163], v[194:197], v[124:127]
	v_mfma_f32_16x16x32_bf16 v[124:127], v[156:159], v[190:193], v[124:127]
	v_mfma_f32_16x16x32_bf16 v[112:115], v[156:159], v[208:211], v[112:115]
	v_mfma_f32_16x16x32_bf16 v[112:115], v[160:163], v[212:215], v[112:115]
	v_mfma_f32_16x16x32_bf16 v[120:123], v[152:155], v[212:215], v[120:123]
	v_mfma_f32_16x16x32_bf16 v[120:123], v[148:151], v[208:211], v[120:123]
	v_mfma_f32_16x16x32_bf16 v[104:107], v[148:151], v[216:219], v[104:107]
	v_mfma_f32_16x16x32_bf16 v[104:107], v[152:155], v[220:223], v[104:107]
	v_mfma_f32_16x16x32_bf16 v[96:99], v[160:163], v[220:223], v[96:99]
	v_mfma_f32_16x16x32_bf16 v[96:99], v[156:159], v[216:219], v[96:99]
	v_mfma_f32_16x16x32_bf16 v[80:83], v[156:159], v[224:227], v[80:83]
	v_mfma_f32_16x16x32_bf16 v[80:83], v[160:163], v[228:231], v[80:83]
	v_mfma_f32_16x16x32_bf16 v[88:91], v[152:155], v[228:231], v[88:91]
	v_mfma_f32_16x16x32_bf16 v[88:91], v[148:151], v[224:227], v[88:91]
	s_setprio 0
	s_setprio 1
	v_mfma_f32_16x16x32_bf16 v[116:119], v[164:167], v[190:193], v[116:119]
	v_mfma_f32_16x16x32_bf16 v[116:119], v[178:181], v[194:197], v[116:119]
	v_mfma_f32_16x16x32_bf16 v[108:111], v[186:189], v[194:197], v[108:111]
	v_mfma_f32_16x16x32_bf16 v[108:111], v[182:185], v[190:193], v[108:111]
	v_mfma_f32_16x16x32_bf16 v[92:95], v[182:185], v[208:211], v[92:95]
	v_mfma_f32_16x16x32_bf16 v[92:95], v[186:189], v[212:215], v[92:95]
	v_mfma_f32_16x16x32_bf16 v[100:103], v[178:181], v[212:215], v[100:103]
	v_mfma_f32_16x16x32_bf16 v[100:103], v[164:167], v[208:211], v[100:103]
	v_mfma_f32_16x16x32_bf16 v[84:87], v[164:167], v[216:219], v[84:87]
	v_mfma_f32_16x16x32_bf16 v[84:87], v[178:181], v[220:223], v[84:87]
	v_mfma_f32_16x16x32_bf16 v[76:79], v[186:189], v[220:223], v[76:79]
	v_mfma_f32_16x16x32_bf16 v[76:79], v[182:185], v[216:219], v[76:79]
	v_mfma_f32_16x16x32_bf16 v[68:71], v[182:185], v[224:227], v[68:71]
	v_mfma_f32_16x16x32_bf16 v[68:71], v[186:189], v[228:231], v[68:71]
	v_mfma_f32_16x16x32_bf16 v[72:75], v[178:181], v[228:231], v[72:75]
	v_mfma_f32_16x16x32_bf16 v[72:75], v[164:167], v[224:227], v[72:75]
	s_setprio 0
	s_barrier
	s_add_i32 s44, s59, s33
	v_lshl_add_u64 v[142:143], v[142:143], 0, s[18:19]
	s_mov_b32 m0, s44
	ds_read_b128 v[190:193], v146 offset:49152
	ds_read_b128 v[194:197], v146 offset:50176
	ds_read_b128 v[208:211], v146 offset:51200
	ds_read_b128 v[212:215], v146 offset:52224
	ds_read_b128 v[216:219], v146 offset:53248
	ds_read_b128 v[220:223], v146 offset:54272
	ds_read_b128 v[224:227], v146 offset:55296
	ds_read_b128 v[228:231], v146 offset:56320
	global_load_lds_dwordx4 v[142:143], off
	s_add_i32 m0, s44, 0x2000
	s_add_u32 s42, s42, 0x200080
	v_lshl_add_u64 v[142:143], v[168:169], 0, s[18:19]
	s_addc_u32 s43, s43, 0
	s_add_i32 s44, s60, s33
	global_load_lds_dwordx4 v[142:143], off
	v_lshl_add_u64 v[142:143], s[42:43], 0, v[2:3]
	s_mov_b32 m0, s44
	s_nop 0
	global_load_lds_dwordx4 v[142:143], off
	v_lshl_add_u64 v[142:143], s[42:43], 0, v[136:137]
	s_add_i32 m0, s44, 0x2000
	s_nop 0
	global_load_lds_dwordx4 v[142:143], off
	v_lshl_add_u64 v[142:143], v[232:233], 0, s[18:19]
	s_mov_b32 m0, s50
	s_nop 0
	global_load_lds_dwordx4 v[142:143], off
	v_lshl_add_u64 v[142:143], v[234:235], 0, s[18:19]
	s_mov_b32 m0, s51
	s_nop 0
	global_load_lds_dwordx4 v[142:143], off
	s_waitcnt vmcnt(8)
	s_waitcnt lgkmcnt(0)
	s_barrier
	s_setprio 1
	s_waitcnt lgkmcnt(0)
	v_mfma_f32_16x16x32_bf16 v[64:67], v[148:151], v[190:193], v[64:67]
	v_mfma_f32_16x16x32_bf16 v[64:67], v[152:155], v[194:197], v[64:67]
	v_mfma_f32_16x16x32_bf16 v[60:63], v[160:163], v[194:197], v[60:63]
	v_mfma_f32_16x16x32_bf16 v[60:63], v[156:159], v[190:193], v[60:63]
	v_mfma_f32_16x16x32_bf16 v[48:51], v[156:159], v[208:211], v[48:51]
	v_mfma_f32_16x16x32_bf16 v[48:51], v[160:163], v[212:215], v[48:51]
	v_mfma_f32_16x16x32_bf16 v[56:59], v[152:155], v[212:215], v[56:59]
	v_mfma_f32_16x16x32_bf16 v[56:59], v[148:151], v[208:211], v[56:59]
	v_mfma_f32_16x16x32_bf16 v[40:43], v[148:151], v[216:219], v[40:43]
	v_mfma_f32_16x16x32_bf16 v[40:43], v[152:155], v[220:223], v[40:43]
	v_mfma_f32_16x16x32_bf16 v[32:35], v[160:163], v[220:223], v[32:35]
	v_mfma_f32_16x16x32_bf16 v[32:35], v[156:159], v[216:219], v[32:35]
	v_mfma_f32_16x16x32_bf16 v[16:19], v[156:159], v[224:227], v[16:19]
	v_mfma_f32_16x16x32_bf16 v[16:19], v[160:163], v[228:231], v[16:19]
	v_mfma_f32_16x16x32_bf16 v[24:27], v[152:155], v[228:231], v[24:27]
	v_mfma_f32_16x16x32_bf16 v[24:27], v[148:151], v[224:227], v[24:27]
	s_setprio 0
	s_setprio 1
	v_mfma_f32_16x16x32_bf16 v[52:55], v[164:167], v[190:193], v[52:55]
	v_mfma_f32_16x16x32_bf16 v[52:55], v[178:181], v[194:197], v[52:55]
	v_mfma_f32_16x16x32_bf16 v[44:47], v[186:189], v[194:197], v[44:47]
	v_mfma_f32_16x16x32_bf16 v[44:47], v[182:185], v[190:193], v[44:47]
	v_mfma_f32_16x16x32_bf16 v[28:31], v[182:185], v[208:211], v[28:31]
	v_mfma_f32_16x16x32_bf16 v[28:31], v[186:189], v[212:215], v[28:31]
	v_mfma_f32_16x16x32_bf16 v[36:39], v[178:181], v[212:215], v[36:39]
	v_mfma_f32_16x16x32_bf16 v[36:39], v[164:167], v[208:211], v[36:39]
	v_mfma_f32_16x16x32_bf16 v[20:23], v[164:167], v[216:219], v[20:23]
	v_mfma_f32_16x16x32_bf16 v[20:23], v[178:181], v[220:223], v[20:23]
	v_mfma_f32_16x16x32_bf16 v[12:15], v[186:189], v[220:223], v[12:15]
	v_mfma_f32_16x16x32_bf16 v[12:15], v[182:185], v[216:219], v[12:15]
	v_mfma_f32_16x16x32_bf16 v[4:7], v[182:185], v[224:227], v[4:7]
	v_mfma_f32_16x16x32_bf16 v[4:7], v[186:189], v[228:231], v[4:7]
	v_mfma_f32_16x16x32_bf16 v[8:11], v[178:181], v[228:231], v[8:11]
	v_mfma_f32_16x16x32_bf16 v[8:11], v[164:167], v[224:227], v[8:11]
	s_setprio 0
	s_barrier
	s_add_i32 s58, s58, 2
	s_add_u32 s40, s40, 0x100
	s_addc_u32 s41, s41, 0
	s_add_u32 s56, s56, 0x100
	s_addc_u32 s57, s57, 0
	s_cmpk_gt_u32 s58, 0x7d

.LBB0_1087:
	s_add_i32 s46, s46, 1
	s_mov_b32 s48, s2
	s_mul_i32 s2, s46, s24
	s_add_i32 s2, s2, s23
	s_cmpk_lt_i32 s2, 0x100
	s_mov_b32 s47, s33
	s_cselect_b64 s[34:35], -1, 0
	s_bfe_u32 s33, s2, 0x30003
	s_ashr_i32 s2, s2, 6
	s_ashr_i32 s3, s2, 31
	s_mov_b64 s[38:39], s[4:5]
	s_lshl_b64 s[4:5], s[2:3], 22
	s_mov_b64 s[36:37], s[8:9]
	s_add_u32 s8, s21, s4
	s_addc_u32 s9, s22, s5
	s_and_b64 s[4:5], s[34:35], exec
	s_cselect_b32 s3, s9, s37
	s_cselect_b32 s49, s8, s36
	s_lshl_b32 s4, s33, 22
	s_add_u32 s4, s10, s4
	s_addc_u32 s5, s11, 0
	s_and_b64 s[40:41], s[34:35], exec
	s_cselect_b32 s50, s5, s39
	s_cselect_b32 s51, s4, s38
	s_add_u32 s36, s36, 0x200080
	s_addc_u32 s37, s37, 0
	s_add_u32 s52, s38, 0x100
	s_addc_u32 s53, s39, 0
	s_mov_b32 s54, -2
	s_add_u32 s38, s36, 0xffe00080
	s_addc_u32 s39, s37, -1
	s_add_i32 s55, 0, 0x10000
	s_cmp_eq_u32 s54, 12
	s_cselect_b32 s41, s3, s39
	s_cselect_b32 s40, s49, s38
	v_add_u32_e32 v2, s55, v140
	s_cselect_b32 s39, s50, s53
	s_cselect_b32 s38, s51, s52
	s_add_i32 s58, 0, 0x14000
	ds_read_b128 v[144:147], v2
	ds_read_b128 v[148:151], v2 offset:1024
	ds_read_b128 v[152:155], v2 offset:2048
	ds_read_b128 v[156:159], v2 offset:3072
	v_add_u32_e32 v2, s58, v140
	ds_read_b128 v[160:163], v2
	ds_read_b128 v[164:167], v2 offset:1024
	ds_read_b128 v[178:181], v2 offset:2048
	ds_read_b128 v[182:185], v2 offset:3072
	v_lshl_add_u64 v[168:169], s[36:37], 0, v[136:137]
	s_add_i32 m0, s42, 0xc000
	ds_read_b128 v[186:189], v142
	ds_read_b128 v[190:193], v142 offset:1024
	ds_read_b128 v[194:197], v142 offset:2048
	ds_read_b128 v[208:211], v142 offset:3072
	ds_read_b128 v[212:215], v142 offset:4096
	ds_read_b128 v[216:219], v142 offset:5120
	ds_read_b128 v[220:223], v142 offset:6144
	ds_read_b128 v[224:227], v142 offset:7168
	global_load_lds_dwordx4 v[168:169], off
	v_lshl_add_u64 v[168:169], s[36:37], 0, v[138:139]
	s_add_i32 m0, s42, 0xe000
	s_nop 0
	global_load_lds_dwordx4 v[168:169], off
	s_waitcnt vmcnt(8)
	s_waitcnt lgkmcnt(0)
	s_barrier
	s_setprio 1
	s_waitcnt lgkmcnt(0)
	v_mfma_f32_16x16x32_bf16 v[128:131], v[144:147], v[186:189], 0
	v_mfma_f32_16x16x32_bf16 v[128:131], v[148:151], v[190:193], v[128:131]
	v_mfma_f32_16x16x32_bf16 v[124:127], v[156:159], v[190:193], 0
	v_mfma_f32_16x16x32_bf16 v[124:127], v[152:155], v[186:189], v[124:127]
	v_mfma_f32_16x16x32_bf16 v[116:119], v[152:155], v[194:197], 0
	v_mfma_f32_16x16x32_bf16 v[116:119], v[156:159], v[208:211], v[116:119]
	v_mfma_f32_16x16x32_bf16 v[120:123], v[148:151], v[208:211], 0
	v_mfma_f32_16x16x32_bf16 v[120:123], v[144:147], v[194:197], v[120:123]
	v_mfma_f32_16x16x32_bf16 v[108:111], v[144:147], v[212:215], 0
	v_mfma_f32_16x16x32_bf16 v[108:111], v[148:151], v[216:219], v[108:111]
	v_mfma_f32_16x16x32_bf16 v[100:103], v[156:159], v[216:219], 0
	v_mfma_f32_16x16x32_bf16 v[100:103], v[152:155], v[212:215], v[100:103]
	v_mfma_f32_16x16x32_bf16 v[84:87], v[152:155], v[220:223], 0
	v_mfma_f32_16x16x32_bf16 v[84:87], v[156:159], v[224:227], v[84:87]
	v_mfma_f32_16x16x32_bf16 v[92:95], v[148:151], v[224:227], 0
	v_mfma_f32_16x16x32_bf16 v[92:95], v[144:147], v[220:223], v[92:95]
	s_setprio 0
	s_setprio 1
	v_mfma_f32_16x16x32_bf16 v[112:115], v[160:163], v[186:189], 0
	v_mfma_f32_16x16x32_bf16 v[112:115], v[164:167], v[190:193], v[112:115]
	v_mfma_f32_16x16x32_bf16 v[104:107], v[182:185], v[190:193], 0
	v_mfma_f32_16x16x32_bf16 v[104:107], v[178:181], v[186:189], v[104:107]
	v_mfma_f32_16x16x32_bf16 v[88:91], v[178:181], v[194:197], 0
	v_mfma_f32_16x16x32_bf16 v[88:91], v[182:185], v[208:211], v[88:91]
	v_mfma_f32_16x16x32_bf16 v[96:99], v[164:167], v[208:211], 0
	v_mfma_f32_16x16x32_bf16 v[96:99], v[160:163], v[194:197], v[96:99]
	v_mfma_f32_16x16x32_bf16 v[80:83], v[160:163], v[212:215], 0
	v_mfma_f32_16x16x32_bf16 v[80:83], v[164:167], v[216:219], v[80:83]
	v_mfma_f32_16x16x32_bf16 v[76:79], v[182:185], v[216:219], 0
	v_mfma_f32_16x16x32_bf16 v[76:79], v[178:181], v[212:215], v[76:79]
	v_mfma_f32_16x16x32_bf16 v[68:71], v[178:181], v[220:223], 0
	v_mfma_f32_16x16x32_bf16 v[68:71], v[182:185], v[224:227], v[68:71]
	v_mfma_f32_16x16x32_bf16 v[72:75], v[164:167], v[224:227], 0
	v_mfma_f32_16x16x32_bf16 v[72:75], v[160:163], v[220:223], v[72:75]
	s_setprio 0
	s_barrier
	s_add_i32 s55, s55, s25
	v_lshl_add_u64 v[168:169], s[38:39], 0, v[134:135]
	s_mov_b32 m0, s55
	ds_read_b128 v[186:189], v142 offset:16384
	ds_read_b128 v[190:193], v142 offset:17408
	ds_read_b128 v[194:197], v142 offset:18432
	ds_read_b128 v[208:211], v142 offset:19456
	ds_read_b128 v[212:215], v142 offset:20480
	ds_read_b128 v[216:219], v142 offset:21504
	ds_read_b128 v[220:223], v142 offset:22528
	ds_read_b128 v[224:227], v142 offset:23552
	global_load_lds_dwordx4 v[168:169], off
	s_add_i32 m0, s55, 0x2000
	s_add_u32 s56, s38, 0x200000
	v_lshl_add_u64 v[228:229], s[38:39], 0, v[132:133]
	s_addc_u32 s57, s39, 0
	s_add_i32 s55, s58, s25
	global_load_lds_dwordx4 v[228:229], off
	v_lshl_add_u64 v[230:231], s[56:57], 0, v[134:135]
	s_mov_b32 m0, s55
	v_lshl_add_u64 v[232:233], s[40:41], 0, v[132:133]
	global_load_lds_dwordx4 v[230:231], off
	v_lshl_add_u64 v[230:231], s[56:57], 0, v[132:133]
	s_add_i32 m0, s55, 0x2000
	s_nop 0
	global_load_lds_dwordx4 v[230:231], off
	v_lshl_add_u64 v[230:231], s[40:41], 0, v[134:135]
	s_mov_b32 m0, s42
	s_nop 0
	global_load_lds_dwordx4 v[230:231], off
	s_mov_b32 m0, s43
	s_nop 0
	global_load_lds_dwordx4 v[232:233], off
	s_waitcnt vmcnt(8)
	s_waitcnt lgkmcnt(0)
	s_barrier
	s_setprio 1
	s_waitcnt lgkmcnt(0)
	v_mfma_f32_16x16x32_bf16 v[64:67], v[144:147], v[186:189], 0
	v_mfma_f32_16x16x32_bf16 v[64:67], v[148:151], v[190:193], v[64:67]
	v_mfma_f32_16x16x32_bf16 v[60:63], v[156:159], v[190:193], 0
	v_mfma_f32_16x16x32_bf16 v[60:63], v[152:155], v[186:189], v[60:63]
	v_mfma_f32_16x16x32_bf16 v[52:55], v[152:155], v[194:197], 0
	v_mfma_f32_16x16x32_bf16 v[52:55], v[156:159], v[208:211], v[52:55]
	v_mfma_f32_16x16x32_bf16 v[56:59], v[148:151], v[208:211], 0
	v_mfma_f32_16x16x32_bf16 v[56:59], v[144:147], v[194:197], v[56:59]
	v_mfma_f32_16x16x32_bf16 v[40:43], v[144:147], v[212:215], 0
	v_mfma_f32_16x16x32_bf16 v[40:43], v[148:151], v[216:219], v[40:43]
	v_mfma_f32_16x16x32_bf16 v[36:39], v[156:159], v[216:219], 0
	v_mfma_f32_16x16x32_bf16 v[36:39], v[152:155], v[212:215], v[36:39]
	v_mfma_f32_16x16x32_bf16 v[20:23], v[152:155], v[220:223], 0
	v_mfma_f32_16x16x32_bf16 v[20:23], v[156:159], v[224:227], v[20:23]
	v_mfma_f32_16x16x32_bf16 v[24:27], v[148:151], v[224:227], 0
	v_mfma_f32_16x16x32_bf16 v[24:27], v[144:147], v[220:223], v[24:27]
	s_setprio 0
	s_setprio 1
	v_mfma_f32_16x16x32_bf16 v[48:51], v[160:163], v[186:189], 0
	v_mfma_f32_16x16x32_bf16 v[48:51], v[164:167], v[190:193], v[48:51]
	v_mfma_f32_16x16x32_bf16 v[44:47], v[182:185], v[190:193], 0
	v_mfma_f32_16x16x32_bf16 v[44:47], v[178:181], v[186:189], v[44:47]
	v_mfma_f32_16x16x32_bf16 v[28:31], v[178:181], v[194:197], 0
	v_mfma_f32_16x16x32_bf16 v[28:31], v[182:185], v[208:211], v[28:31]
	v_mfma_f32_16x16x32_bf16 v[32:35], v[164:167], v[208:211], 0
	v_mfma_f32_16x16x32_bf16 v[32:35], v[160:163], v[194:197], v[32:35]
	v_mfma_f32_16x16x32_bf16 v[16:19], v[160:163], v[212:215], 0
	v_mfma_f32_16x16x32_bf16 v[16:19], v[164:167], v[216:219], v[16:19]
	v_mfma_f32_16x16x32_bf16 v[12:15], v[182:185], v[216:219], 0
	v_mfma_f32_16x16x32_bf16 v[12:15], v[178:181], v[212:215], v[12:15]
	v_mfma_f32_16x16x32_bf16 v[4:7], v[178:181], v[220:223], 0
	v_mfma_f32_16x16x32_bf16 v[4:7], v[182:185], v[224:227], v[4:7]
	v_mfma_f32_16x16x32_bf16 v[8:11], v[164:167], v[224:227], 0
	v_mfma_f32_16x16x32_bf16 v[8:11], v[160:163], v[220:223], v[8:11]
	s_setprio 0
	s_barrier
	s_add_i32 s55, 0, 0x18000
	v_add_u32_e32 v2, s55, v140
	s_add_i32 s56, 0, 0x1c000
	ds_read_b128 v[144:147], v2
	ds_read_b128 v[148:151], v2 offset:1024
	ds_read_b128 v[152:155], v2 offset:2048
	ds_read_b128 v[156:159], v2 offset:3072
	v_add_u32_e32 v2, s56, v140
	ds_read_b128 v[160:163], v2
	ds_read_b128 v[164:167], v2 offset:1024
	ds_read_b128 v[178:181], v2 offset:2048
	ds_read_b128 v[182:185], v2 offset:3072
	s_add_u32 s40, s40, 0x200000
	s_addc_u32 s41, s41, 0
	s_mov_b32 m0, s44
	v_lshl_add_u64 v[234:235], s[40:41], 0, v[134:135]
	ds_read_b128 v[186:189], v142 offset:32768
	ds_read_b128 v[190:193], v142 offset:33792
	ds_read_b128 v[194:197], v142 offset:34816
	ds_read_b128 v[208:211], v142 offset:35840
	ds_read_b128 v[212:215], v142 offset:36864
	ds_read_b128 v[216:219], v142 offset:37888
	ds_read_b128 v[220:223], v142 offset:38912
	ds_read_b128 v[224:227], v142 offset:39936
	global_load_lds_dwordx4 v[234:235], off
	v_lshl_add_u64 v[234:235], s[40:41], 0, v[132:133]
	s_mov_b32 m0, s45
	s_nop 0
	global_load_lds_dwordx4 v[234:235], off
	s_waitcnt vmcnt(8)
	s_waitcnt lgkmcnt(0)
	s_barrier
	s_setprio 1
	s_waitcnt lgkmcnt(0)
	v_mfma_f32_16x16x32_bf16 v[128:131], v[144:147], v[186:189], v[128:131]
	v_mfma_f32_16x16x32_bf16 v[128:131], v[148:151], v[190:193], v[128:131]
	v_mfma_f32_16x16x32_bf16 v[124:127], v[156:159], v[190:193], v[124:127]
	v_mfma_f32_16x16x32_bf16 v[124:127], v[152:155], v[186:189], v[124:127]
	v_mfma_f32_16x16x32_bf16 v[116:119], v[152:155], v[194:197], v[116:119]
	v_mfma_f32_16x16x32_bf16 v[116:119], v[156:159], v[208:211], v[116:119]
	v_mfma_f32_16x16x32_bf16 v[120:123], v[148:151], v[208:211], v[120:123]
	v_mfma_f32_16x16x32_bf16 v[120:123], v[144:147], v[194:197], v[120:123]
	v_mfma_f32_16x16x32_bf16 v[108:111], v[144:147], v[212:215], v[108:111]
	v_mfma_f32_16x16x32_bf16 v[108:111], v[148:151], v[216:219], v[108:111]
	v_mfma_f32_16x16x32_bf16 v[100:103], v[156:159], v[216:219], v[100:103]
	v_mfma_f32_16x16x32_bf16 v[100:103], v[152:155], v[212:215], v[100:103]
	v_mfma_f32_16x16x32_bf16 v[84:87], v[152:155], v[220:223], v[84:87]
	v_mfma_f32_16x16x32_bf16 v[84:87], v[156:159], v[224:227], v[84:87]
	v_mfma_f32_16x16x32_bf16 v[92:95], v[148:151], v[224:227], v[92:95]
	v_mfma_f32_16x16x32_bf16 v[92:95], v[144:147], v[220:223], v[92:95]
	s_setprio 0
	s_setprio 1
	v_mfma_f32_16x16x32_bf16 v[112:115], v[160:163], v[186:189], v[112:115]
	v_mfma_f32_16x16x32_bf16 v[112:115], v[164:167], v[190:193], v[112:115]
	v_mfma_f32_16x16x32_bf16 v[104:107], v[182:185], v[190:193], v[104:107]
	v_mfma_f32_16x16x32_bf16 v[104:107], v[178:181], v[186:189], v[104:107]
	v_mfma_f32_16x16x32_bf16 v[88:91], v[178:181], v[194:197], v[88:91]
	v_mfma_f32_16x16x32_bf16 v[88:91], v[182:185], v[208:211], v[88:91]
	v_mfma_f32_16x16x32_bf16 v[96:99], v[164:167], v[208:211], v[96:99]
	v_mfma_f32_16x16x32_bf16 v[96:99], v[160:163], v[194:197], v[96:99]
	v_mfma_f32_16x16x32_bf16 v[80:83], v[160:163], v[212:215], v[80:83]
	v_mfma_f32_16x16x32_bf16 v[80:83], v[164:167], v[216:219], v[80:83]
	v_mfma_f32_16x16x32_bf16 v[76:79], v[182:185], v[216:219], v[76:79]
	v_mfma_f32_16x16x32_bf16 v[76:79], v[178:181], v[212:215], v[76:79]
	v_mfma_f32_16x16x32_bf16 v[68:71], v[178:181], v[220:223], v[68:71]
	v_mfma_f32_16x16x32_bf16 v[68:71], v[182:185], v[224:227], v[68:71]
	v_mfma_f32_16x16x32_bf16 v[72:75], v[164:167], v[224:227], v[72:75]
	v_mfma_f32_16x16x32_bf16 v[72:75], v[160:163], v[220:223], v[72:75]
	s_setprio 0
	s_barrier
	s_add_i32 s40, s55, s25
	v_lshl_add_u64 v[168:169], v[168:169], 0, s[18:19]
	s_mov_b32 m0, s40
	ds_read_b128 v[186:189], v142 offset:49152
	ds_read_b128 v[190:193], v142 offset:50176
	ds_read_b128 v[194:197], v142 offset:51200
	ds_read_b128 v[208:211], v142 offset:52224
	ds_read_b128 v[212:215], v142 offset:53248
	ds_read_b128 v[216:219], v142 offset:54272
	ds_read_b128 v[220:223], v142 offset:55296
	ds_read_b128 v[224:227], v142 offset:56320
	global_load_lds_dwordx4 v[168:169], off
	s_add_i32 m0, s40, 0x2000
	s_add_u32 s38, s38, 0x200080
	v_lshl_add_u64 v[168:169], v[228:229], 0, s[18:19]
	s_addc_u32 s39, s39, 0
	s_add_i32 s40, s56, s25
	global_load_lds_dwordx4 v[168:169], off
	v_lshl_add_u64 v[168:169], s[38:39], 0, v[134:135]
	s_mov_b32 m0, s40
	s_nop 0
	global_load_lds_dwordx4 v[168:169], off
	v_lshl_add_u64 v[168:169], s[38:39], 0, v[132:133]
	s_add_i32 m0, s40, 0x2000
	s_nop 0
	global_load_lds_dwordx4 v[168:169], off
	v_lshl_add_u64 v[168:169], v[230:231], 0, s[18:19]
	s_mov_b32 m0, s1
	s_nop 0
	global_load_lds_dwordx4 v[168:169], off
	v_lshl_add_u64 v[168:169], v[232:233], 0, s[18:19]
	s_mov_b32 m0, s7
	s_nop 0
	global_load_lds_dwordx4 v[168:169], off
	s_waitcnt vmcnt(8)
	s_waitcnt lgkmcnt(0)
	s_barrier
	s_setprio 1
	s_waitcnt lgkmcnt(0)
	v_mfma_f32_16x16x32_bf16 v[64:67], v[144:147], v[186:189], v[64:67]
	v_mfma_f32_16x16x32_bf16 v[64:67], v[148:151], v[190:193], v[64:67]
	v_mfma_f32_16x16x32_bf16 v[60:63], v[156:159], v[190:193], v[60:63]
	v_mfma_f32_16x16x32_bf16 v[60:63], v[152:155], v[186:189], v[60:63]
	v_mfma_f32_16x16x32_bf16 v[52:55], v[152:155], v[194:197], v[52:55]
	v_mfma_f32_16x16x32_bf16 v[52:55], v[156:159], v[208:211], v[52:55]
	v_mfma_f32_16x16x32_bf16 v[56:59], v[148:151], v[208:211], v[56:59]
	v_mfma_f32_16x16x32_bf16 v[56:59], v[144:147], v[194:197], v[56:59]
	v_mfma_f32_16x16x32_bf16 v[40:43], v[144:147], v[212:215], v[40:43]
	v_mfma_f32_16x16x32_bf16 v[40:43], v[148:151], v[216:219], v[40:43]
	v_mfma_f32_16x16x32_bf16 v[36:39], v[156:159], v[216:219], v[36:39]
	v_mfma_f32_16x16x32_bf16 v[36:39], v[152:155], v[212:215], v[36:39]
	v_mfma_f32_16x16x32_bf16 v[20:23], v[152:155], v[220:223], v[20:23]
	v_mfma_f32_16x16x32_bf16 v[20:23], v[156:159], v[224:227], v[20:23]
	v_mfma_f32_16x16x32_bf16 v[24:27], v[148:151], v[224:227], v[24:27]
	v_mfma_f32_16x16x32_bf16 v[24:27], v[144:147], v[220:223], v[24:27]
	s_setprio 0
	s_setprio 1
	v_mfma_f32_16x16x32_bf16 v[48:51], v[160:163], v[186:189], v[48:51]
	v_mfma_f32_16x16x32_bf16 v[48:51], v[164:167], v[190:193], v[48:51]
	v_mfma_f32_16x16x32_bf16 v[44:47], v[182:185], v[190:193], v[44:47]
	v_mfma_f32_16x16x32_bf16 v[44:47], v[178:181], v[186:189], v[44:47]
	v_mfma_f32_16x16x32_bf16 v[28:31], v[178:181], v[194:197], v[28:31]
	v_mfma_f32_16x16x32_bf16 v[28:31], v[182:185], v[208:211], v[28:31]
	v_mfma_f32_16x16x32_bf16 v[32:35], v[164:167], v[208:211], v[32:35]
	v_mfma_f32_16x16x32_bf16 v[32:35], v[160:163], v[194:197], v[32:35]
	v_mfma_f32_16x16x32_bf16 v[16:19], v[160:163], v[212:215], v[16:19]
	v_mfma_f32_16x16x32_bf16 v[16:19], v[164:167], v[216:219], v[16:19]
	v_mfma_f32_16x16x32_bf16 v[12:15], v[182:185], v[216:219], v[12:15]
	v_mfma_f32_16x16x32_bf16 v[12:15], v[178:181], v[212:215], v[12:15]
	v_mfma_f32_16x16x32_bf16 v[4:7], v[178:181], v[220:223], v[4:7]
	v_mfma_f32_16x16x32_bf16 v[4:7], v[182:185], v[224:227], v[4:7]
	v_mfma_f32_16x16x32_bf16 v[8:11], v[164:167], v[224:227], v[8:11]
	v_mfma_f32_16x16x32_bf16 v[8:11], v[160:163], v[220:223], v[8:11]
	s_setprio 0
	s_barrier
	s_add_i32 s54, s54, 2
	s_add_u32 s36, s36, 0x100
	s_addc_u32 s37, s37, 0
	s_add_u32 s52, s52, 0x100
	s_addc_u32 s53, s53, 0
	s_cmp_gt_u32 s54, 13

.LBB0_1183:
	s_ashr_i32 s59, s58, 31
	s_lshl_b64 s[10:11], s[58:59], 20
	s_add_u32 s60, s34, s10
	s_addc_u32 s61, s35, s11
	s_and_b64 s[10:11], s[40:41], exec
	s_cselect_b32 s1, s61, s5
	s_cselect_b32 s3, s60, s4
	s_ashr_i32 s57, s56, 31
	s_lshl_b64 s[10:11], s[56:57], 20
	s_add_u32 s62, s36, s10
	s_addc_u32 s63, s37, s11
	s_and_b64 s[10:11], s[40:41], exec
	s_cselect_b32 s7, s63, s9
	s_cselect_b32 s10, s62, s8
	s_add_u32 s4, s4, 0x80080
	s_addc_u32 s5, s5, 0
	s_add_u32 s11, s8, 0x100
	s_addc_u32 s21, s9, 0
	s_mov_b32 s22, -2
	v_lshl_add_u32 v148, s2, 8, v161
	v_ashrrev_i32_e32 v149, 31, v148
	v_lshl_add_u64 v[152:153], v[148:149], 2, s[50:51]
	global_load_dword v246, v[152:153], off
	global_load_dword v247, v[152:153], off offset:64
	global_load_dword v248, v[152:153], off offset:128
	global_load_dword v249, v[152:153], off offset:192
	global_load_dword v250, v[152:153], off offset:512
	global_load_dword v251, v[152:153], off offset:576
	global_load_dword v254, v[152:153], off offset:640
	global_load_dword v255, v[152:153], off offset:704
	s_add_u32 s8, s4, 0xfff80080
	s_addc_u32 s9, s5, -1
	s_add_i32 s26, 0, 0x10000
	s_cmp_eq_u32 s22, 28
	s_cselect_b32 s13, s1, s9
	s_cselect_b32 s12, s3, s8
	v_add_u32_e32 v1, s26, v162
	s_cselect_b32 s9, s7, s21
	s_cselect_b32 s8, s10, s11
	s_add_i32 s33, 0, 0x14000
	ds_read_b128 v[148:151], v1
	ds_read_b128 v[152:155], v1 offset:1024
	ds_read_b128 v[156:159], v1 offset:2048
	ds_read_b128 v[166:169], v1 offset:3072
	v_add_u32_e32 v1, s33, v162
	ds_read_b128 v[178:181], v1
	ds_read_b128 v[182:185], v1 offset:1024
	ds_read_b128 v[186:189], v1 offset:2048
	ds_read_b128 v[190:193], v1 offset:3072
	v_lshl_add_u64 v[236:237], s[4:5], 0, v[144:145]
	s_add_i32 m0, s47, 0xc000
	ds_read_b128 v[194:197], v165
	ds_read_b128 v[208:211], v165 offset:1024
	ds_read_b128 v[212:215], v165 offset:2048
	ds_read_b128 v[216:219], v165 offset:3072
	ds_read_b128 v[220:223], v165 offset:4096
	ds_read_b128 v[224:227], v165 offset:5120
	ds_read_b128 v[228:231], v165 offset:6144
	ds_read_b128 v[232:235], v165 offset:7168
	global_load_lds_dwordx4 v[236:237], off
	v_lshl_add_u64 v[236:237], s[4:5], 0, v[146:147]
	s_add_i32 m0, s47, 0xe000
	s_nop 0
	global_load_lds_dwordx4 v[236:237], off
	s_waitcnt vmcnt(8)
	s_waitcnt lgkmcnt(0)
	s_barrier
	s_setprio 1
	s_waitcnt lgkmcnt(0)
	v_mfma_f32_16x16x32_bf16 v[128:131], v[148:151], v[194:197], 0
	v_mfma_f32_16x16x32_bf16 v[128:131], v[152:155], v[208:211], v[128:131]
	v_mfma_f32_16x16x32_bf16 v[124:127], v[166:169], v[208:211], 0
	v_mfma_f32_16x16x32_bf16 v[124:127], v[156:159], v[194:197], v[124:127]
	v_mfma_f32_16x16x32_bf16 v[108:111], v[156:159], v[212:215], 0
	v_mfma_f32_16x16x32_bf16 v[108:111], v[166:169], v[216:219], v[108:111]
	v_mfma_f32_16x16x32_bf16 v[112:115], v[152:155], v[216:219], 0
	v_mfma_f32_16x16x32_bf16 v[112:115], v[148:151], v[212:215], v[112:115]
	v_mfma_f32_16x16x32_bf16 v[96:99], v[148:151], v[220:223], 0
	v_mfma_f32_16x16x32_bf16 v[96:99], v[152:155], v[224:227], v[96:99]
	v_mfma_f32_16x16x32_bf16 v[92:95], v[166:169], v[224:227], 0
	v_mfma_f32_16x16x32_bf16 v[92:95], v[156:159], v[220:223], v[92:95]
	v_mfma_f32_16x16x32_bf16 v[76:79], v[156:159], v[228:231], 0
	v_mfma_f32_16x16x32_bf16 v[76:79], v[166:169], v[232:235], v[76:79]
	v_mfma_f32_16x16x32_bf16 v[80:83], v[152:155], v[232:235], 0
	v_mfma_f32_16x16x32_bf16 v[80:83], v[148:151], v[228:231], v[80:83]
	s_setprio 0
	s_setprio 1
	v_mfma_f32_16x16x32_bf16 v[120:123], v[178:181], v[194:197], 0
	v_mfma_f32_16x16x32_bf16 v[120:123], v[182:185], v[208:211], v[120:123]
	v_mfma_f32_16x16x32_bf16 v[116:119], v[190:193], v[208:211], 0
	v_mfma_f32_16x16x32_bf16 v[116:119], v[186:189], v[194:197], v[116:119]
	v_mfma_f32_16x16x32_bf16 v[100:103], v[186:189], v[212:215], 0
	v_mfma_f32_16x16x32_bf16 v[100:103], v[190:193], v[216:219], v[100:103]
	v_mfma_f32_16x16x32_bf16 v[104:107], v[182:185], v[216:219], 0
	v_mfma_f32_16x16x32_bf16 v[104:107], v[178:181], v[212:215], v[104:107]
	v_mfma_f32_16x16x32_bf16 v[88:91], v[178:181], v[220:223], 0
	v_mfma_f32_16x16x32_bf16 v[88:91], v[182:185], v[224:227], v[88:91]
	v_mfma_f32_16x16x32_bf16 v[84:87], v[190:193], v[224:227], 0
	v_mfma_f32_16x16x32_bf16 v[84:87], v[186:189], v[220:223], v[84:87]
	v_mfma_f32_16x16x32_bf16 v[68:71], v[186:189], v[228:231], 0
	v_mfma_f32_16x16x32_bf16 v[68:71], v[190:193], v[232:235], v[68:71]
	v_mfma_f32_16x16x32_bf16 v[72:75], v[182:185], v[232:235], 0
	v_mfma_f32_16x16x32_bf16 v[72:75], v[178:181], v[228:231], v[72:75]
	s_setprio 0
	s_barrier
	s_add_i32 s26, s26, s65
	v_lshl_add_u64 v[236:237], s[8:9], 0, v[134:135]
	s_mov_b32 m0, s26
	ds_read_b128 v[194:197], v165 offset:16384
	ds_read_b128 v[208:211], v165 offset:17408
	ds_read_b128 v[212:215], v165 offset:18432
	ds_read_b128 v[216:219], v165 offset:19456
	ds_read_b128 v[220:223], v165 offset:20480
	ds_read_b128 v[224:227], v165 offset:21504
	ds_read_b128 v[228:231], v165 offset:22528
	ds_read_b128 v[232:235], v165 offset:23552
	global_load_lds_dwordx4 v[236:237], off
	s_add_i32 m0, s26, 0x2000
	s_add_u32 s26, s8, 0x80000
	v_lshl_add_u64 v[238:239], s[8:9], 0, v[138:139]
	s_addc_u32 s27, s9, 0
	s_add_i32 s33, s33, s65
	global_load_lds_dwordx4 v[238:239], off
	v_lshl_add_u64 v[240:241], s[26:27], 0, v[134:135]
	s_mov_b32 m0, s33
	v_lshl_add_u64 v[242:243], s[12:13], 0, v[136:137]
	global_load_lds_dwordx4 v[240:241], off
	v_lshl_add_u64 v[240:241], s[26:27], 0, v[138:139]
	s_add_i32 m0, s33, 0x2000
	s_nop 0
	global_load_lds_dwordx4 v[240:241], off
	v_lshl_add_u64 v[240:241], s[12:13], 0, v[132:133]
	s_mov_b32 m0, s47
	s_nop 0
	global_load_lds_dwordx4 v[240:241], off
	s_mov_b32 m0, s66
	s_nop 0
	global_load_lds_dwordx4 v[242:243], off
	s_waitcnt vmcnt(8)
	s_waitcnt lgkmcnt(0)
	s_barrier
	s_setprio 1
	s_waitcnt lgkmcnt(0)
	v_mfma_f32_16x16x32_bf16 v[64:67], v[148:151], v[194:197], 0
	v_mfma_f32_16x16x32_bf16 v[64:67], v[152:155], v[208:211], v[64:67]
	v_mfma_f32_16x16x32_bf16 v[60:63], v[166:169], v[208:211], 0
	v_mfma_f32_16x16x32_bf16 v[60:63], v[156:159], v[194:197], v[60:63]
	v_mfma_f32_16x16x32_bf16 v[44:47], v[156:159], v[212:215], 0
	v_mfma_f32_16x16x32_bf16 v[44:47], v[166:169], v[216:219], v[44:47]
	v_mfma_f32_16x16x32_bf16 v[48:51], v[152:155], v[216:219], 0
	v_mfma_f32_16x16x32_bf16 v[48:51], v[148:151], v[212:215], v[48:51]
	v_mfma_f32_16x16x32_bf16 v[32:35], v[148:151], v[220:223], 0
	v_mfma_f32_16x16x32_bf16 v[32:35], v[152:155], v[224:227], v[32:35]
	v_mfma_f32_16x16x32_bf16 v[28:31], v[166:169], v[224:227], 0
	v_mfma_f32_16x16x32_bf16 v[28:31], v[156:159], v[220:223], v[28:31]
	v_mfma_f32_16x16x32_bf16 v[12:15], v[156:159], v[228:231], 0
	v_mfma_f32_16x16x32_bf16 v[12:15], v[166:169], v[232:235], v[12:15]
	v_mfma_f32_16x16x32_bf16 v[16:19], v[152:155], v[232:235], 0
	v_mfma_f32_16x16x32_bf16 v[16:19], v[148:151], v[228:231], v[16:19]
	s_setprio 0
	s_setprio 1
	v_mfma_f32_16x16x32_bf16 v[56:59], v[178:181], v[194:197], 0
	v_mfma_f32_16x16x32_bf16 v[56:59], v[182:185], v[208:211], v[56:59]
	v_mfma_f32_16x16x32_bf16 v[52:55], v[190:193], v[208:211], 0
	v_mfma_f32_16x16x32_bf16 v[52:55], v[186:189], v[194:197], v[52:55]
	v_mfma_f32_16x16x32_bf16 v[36:39], v[186:189], v[212:215], 0
	v_mfma_f32_16x16x32_bf16 v[36:39], v[190:193], v[216:219], v[36:39]
	v_mfma_f32_16x16x32_bf16 v[40:43], v[182:185], v[216:219], 0
	v_mfma_f32_16x16x32_bf16 v[40:43], v[178:181], v[212:215], v[40:43]
	v_mfma_f32_16x16x32_bf16 v[24:27], v[178:181], v[220:223], 0
	v_mfma_f32_16x16x32_bf16 v[24:27], v[182:185], v[224:227], v[24:27]
	v_mfma_f32_16x16x32_bf16 v[20:23], v[190:193], v[224:227], 0
	v_mfma_f32_16x16x32_bf16 v[20:23], v[186:189], v[220:223], v[20:23]
	v_mfma_f32_16x16x32_bf16 v[4:7], v[186:189], v[228:231], 0
	v_mfma_f32_16x16x32_bf16 v[4:7], v[190:193], v[232:235], v[4:7]
	v_mfma_f32_16x16x32_bf16 v[8:11], v[182:185], v[232:235], 0
	v_mfma_f32_16x16x32_bf16 v[8:11], v[178:181], v[228:231], v[8:11]
	s_setprio 0
	s_barrier
	s_add_i32 s26, 0, 0x18000
	v_add_u32_e32 v1, s26, v162
	s_add_i32 s27, 0, 0x1c000
	ds_read_b128 v[148:151], v1
	ds_read_b128 v[152:155], v1 offset:1024
	ds_read_b128 v[156:159], v1 offset:2048
	ds_read_b128 v[166:169], v1 offset:3072
	v_add_u32_e32 v1, s27, v162
	ds_read_b128 v[178:181], v1
	ds_read_b128 v[182:185], v1 offset:1024
	ds_read_b128 v[186:189], v1 offset:2048
	ds_read_b128 v[190:193], v1 offset:3072
	s_add_u32 s12, s12, 0x80000
	s_addc_u32 s13, s13, 0
	s_mov_b32 m0, s67
	v_lshl_add_u64 v[244:245], s[12:13], 0, v[132:133]
	ds_read_b128 v[194:197], v165 offset:32768
	ds_read_b128 v[208:211], v165 offset:33792
	ds_read_b128 v[212:215], v165 offset:34816
	ds_read_b128 v[216:219], v165 offset:35840
	ds_read_b128 v[220:223], v165 offset:36864
	ds_read_b128 v[224:227], v165 offset:37888
	ds_read_b128 v[228:231], v165 offset:38912
	ds_read_b128 v[232:235], v165 offset:39936
	global_load_lds_dwordx4 v[244:245], off
	v_lshl_add_u64 v[244:245], s[12:13], 0, v[136:137]
	s_mov_b32 m0, s68
	s_nop 0
	global_load_lds_dwordx4 v[244:245], off
	s_waitcnt vmcnt(8)
	s_waitcnt lgkmcnt(0)
	s_barrier
	s_setprio 1
	s_waitcnt lgkmcnt(0)
	v_mfma_f32_16x16x32_bf16 v[128:131], v[148:151], v[194:197], v[128:131]
	v_mfma_f32_16x16x32_bf16 v[128:131], v[152:155], v[208:211], v[128:131]
	v_mfma_f32_16x16x32_bf16 v[124:127], v[166:169], v[208:211], v[124:127]
	v_mfma_f32_16x16x32_bf16 v[124:127], v[156:159], v[194:197], v[124:127]
	v_mfma_f32_16x16x32_bf16 v[108:111], v[156:159], v[212:215], v[108:111]
	v_mfma_f32_16x16x32_bf16 v[108:111], v[166:169], v[216:219], v[108:111]
	v_mfma_f32_16x16x32_bf16 v[112:115], v[152:155], v[216:219], v[112:115]
	v_mfma_f32_16x16x32_bf16 v[112:115], v[148:151], v[212:215], v[112:115]
	v_mfma_f32_16x16x32_bf16 v[96:99], v[148:151], v[220:223], v[96:99]
	v_mfma_f32_16x16x32_bf16 v[96:99], v[152:155], v[224:227], v[96:99]
	v_mfma_f32_16x16x32_bf16 v[92:95], v[166:169], v[224:227], v[92:95]
	v_mfma_f32_16x16x32_bf16 v[92:95], v[156:159], v[220:223], v[92:95]
	v_mfma_f32_16x16x32_bf16 v[76:79], v[156:159], v[228:231], v[76:79]
	v_mfma_f32_16x16x32_bf16 v[76:79], v[166:169], v[232:235], v[76:79]
	v_mfma_f32_16x16x32_bf16 v[80:83], v[152:155], v[232:235], v[80:83]
	v_mfma_f32_16x16x32_bf16 v[80:83], v[148:151], v[228:231], v[80:83]
	s_setprio 0
	s_setprio 1
	v_mfma_f32_16x16x32_bf16 v[120:123], v[178:181], v[194:197], v[120:123]
	v_mfma_f32_16x16x32_bf16 v[120:123], v[182:185], v[208:211], v[120:123]
	v_mfma_f32_16x16x32_bf16 v[116:119], v[190:193], v[208:211], v[116:119]
	v_mfma_f32_16x16x32_bf16 v[116:119], v[186:189], v[194:197], v[116:119]
	v_mfma_f32_16x16x32_bf16 v[100:103], v[186:189], v[212:215], v[100:103]
	v_mfma_f32_16x16x32_bf16 v[100:103], v[190:193], v[216:219], v[100:103]
	v_mfma_f32_16x16x32_bf16 v[104:107], v[182:185], v[216:219], v[104:107]
	v_mfma_f32_16x16x32_bf16 v[104:107], v[178:181], v[212:215], v[104:107]
	v_mfma_f32_16x16x32_bf16 v[88:91], v[178:181], v[220:223], v[88:91]
	v_mfma_f32_16x16x32_bf16 v[88:91], v[182:185], v[224:227], v[88:91]
	v_mfma_f32_16x16x32_bf16 v[84:87], v[190:193], v[224:227], v[84:87]
	v_mfma_f32_16x16x32_bf16 v[84:87], v[186:189], v[220:223], v[84:87]
	v_mfma_f32_16x16x32_bf16 v[68:71], v[186:189], v[228:231], v[68:71]
	v_mfma_f32_16x16x32_bf16 v[68:71], v[190:193], v[232:235], v[68:71]
	v_mfma_f32_16x16x32_bf16 v[72:75], v[182:185], v[232:235], v[72:75]
	v_mfma_f32_16x16x32_bf16 v[72:75], v[178:181], v[228:231], v[72:75]
	s_setprio 0
	s_barrier
	s_add_i32 s12, s26, s65
	v_lshl_add_u64 v[236:237], v[236:237], 0, s[18:19]
	s_mov_b32 m0, s12
	ds_read_b128 v[194:197], v165 offset:49152
	ds_read_b128 v[208:211], v165 offset:50176
	ds_read_b128 v[212:215], v165 offset:51200
	ds_read_b128 v[216:219], v165 offset:52224
	ds_read_b128 v[220:223], v165 offset:53248
	ds_read_b128 v[224:227], v165 offset:54272
	ds_read_b128 v[228:231], v165 offset:55296
	ds_read_b128 v[232:235], v165 offset:56320
	global_load_lds_dwordx4 v[236:237], off
	s_add_i32 m0, s12, 0x2000
	s_add_u32 s8, s8, 0x80080
	v_lshl_add_u64 v[236:237], v[238:239], 0, s[18:19]
	s_addc_u32 s9, s9, 0
	s_add_i32 s12, s27, s65
	global_load_lds_dwordx4 v[236:237], off
	v_lshl_add_u64 v[236:237], s[8:9], 0, v[134:135]
	s_mov_b32 m0, s12
	s_nop 0
	global_load_lds_dwordx4 v[236:237], off
	v_lshl_add_u64 v[236:237], s[8:9], 0, v[138:139]
	s_add_i32 m0, s12, 0x2000
	s_nop 0
	global_load_lds_dwordx4 v[236:237], off
	v_lshl_add_u64 v[236:237], v[240:241], 0, s[18:19]
	s_mov_b32 m0, s82
	s_nop 0
	global_load_lds_dwordx4 v[236:237], off
	v_lshl_add_u64 v[236:237], v[242:243], 0, s[18:19]
	s_mov_b32 m0, s83
	s_nop 0
	global_load_lds_dwordx4 v[236:237], off
	s_waitcnt vmcnt(8)
	s_waitcnt lgkmcnt(0)
	s_barrier
	s_setprio 1
	s_waitcnt lgkmcnt(0)
	v_mfma_f32_16x16x32_bf16 v[64:67], v[148:151], v[194:197], v[64:67]
	v_mfma_f32_16x16x32_bf16 v[64:67], v[152:155], v[208:211], v[64:67]
	v_mfma_f32_16x16x32_bf16 v[60:63], v[166:169], v[208:211], v[60:63]
	v_mfma_f32_16x16x32_bf16 v[60:63], v[156:159], v[194:197], v[60:63]
	v_mfma_f32_16x16x32_bf16 v[44:47], v[156:159], v[212:215], v[44:47]
	v_mfma_f32_16x16x32_bf16 v[44:47], v[166:169], v[216:219], v[44:47]
	v_mfma_f32_16x16x32_bf16 v[48:51], v[152:155], v[216:219], v[48:51]
	v_mfma_f32_16x16x32_bf16 v[48:51], v[148:151], v[212:215], v[48:51]
	v_mfma_f32_16x16x32_bf16 v[32:35], v[148:151], v[220:223], v[32:35]
	v_mfma_f32_16x16x32_bf16 v[32:35], v[152:155], v[224:227], v[32:35]
	v_mfma_f32_16x16x32_bf16 v[28:31], v[166:169], v[224:227], v[28:31]
	v_mfma_f32_16x16x32_bf16 v[28:31], v[156:159], v[220:223], v[28:31]
	v_mfma_f32_16x16x32_bf16 v[12:15], v[156:159], v[228:231], v[12:15]
	v_mfma_f32_16x16x32_bf16 v[12:15], v[166:169], v[232:235], v[12:15]
	v_mfma_f32_16x16x32_bf16 v[16:19], v[152:155], v[232:235], v[16:19]
	v_mfma_f32_16x16x32_bf16 v[16:19], v[148:151], v[228:231], v[16:19]
	s_setprio 0
	s_setprio 1
	v_mfma_f32_16x16x32_bf16 v[56:59], v[178:181], v[194:197], v[56:59]
	v_mfma_f32_16x16x32_bf16 v[56:59], v[182:185], v[208:211], v[56:59]
	v_mfma_f32_16x16x32_bf16 v[52:55], v[190:193], v[208:211], v[52:55]
	v_mfma_f32_16x16x32_bf16 v[52:55], v[186:189], v[194:197], v[52:55]
	v_mfma_f32_16x16x32_bf16 v[36:39], v[186:189], v[212:215], v[36:39]
	v_mfma_f32_16x16x32_bf16 v[36:39], v[190:193], v[216:219], v[36:39]
	v_mfma_f32_16x16x32_bf16 v[40:43], v[182:185], v[216:219], v[40:43]
	v_mfma_f32_16x16x32_bf16 v[40:43], v[178:181], v[212:215], v[40:43]
	v_mfma_f32_16x16x32_bf16 v[24:27], v[178:181], v[220:223], v[24:27]
	v_mfma_f32_16x16x32_bf16 v[24:27], v[182:185], v[224:227], v[24:27]
	v_mfma_f32_16x16x32_bf16 v[20:23], v[190:193], v[224:227], v[20:23]
	v_mfma_f32_16x16x32_bf16 v[20:23], v[186:189], v[220:223], v[20:23]
	v_mfma_f32_16x16x32_bf16 v[4:7], v[186:189], v[228:231], v[4:7]
	v_mfma_f32_16x16x32_bf16 v[4:7], v[190:193], v[232:235], v[4:7]
	v_mfma_f32_16x16x32_bf16 v[8:11], v[182:185], v[232:235], v[8:11]
	v_mfma_f32_16x16x32_bf16 v[8:11], v[178:181], v[228:231], v[8:11]
	s_setprio 0
	s_barrier
	s_add_i32 s22, s22, 2
	s_add_u32 s4, s4, 0x100
	s_addc_u32 s5, s5, 0
	s_add_u32 s11, s11, 0x100
	s_addc_u32 s21, s21, 0
	s_cmp_gt_u32 s22, 29
